# v_ntwin plus sc1 (write-through) on the in-proj epilogue bf16 output stores, to shrink the L2 write-back at the following grid barrier
# speedup vs baseline: 1.0174x; 1.0174x over previous
; __device__ __forceinline__ float fast_exp(float x) { return __builtin_amdgcn_exp2f(x * LOG2E); }
;     __device__ __forceinline__ void operator()(const f32x4 (&acc)[2][2][4][2], const pg8::Unit& u, int wr, int wc, int fr, int fq) const {
;         asm volatile("" : "+v"(fr), "+v"(fq));
;         const int pn = u.pn, pm = u.pm;
;         const bool sample = pm >= (MP / 256);
;         TileT tt; tt.init(stg, wr * 4 + wc, fr, fq);
;         float rs8[2][4];
; #pragma unroll
;         for (int ai = 0; ai < 2; ++ai)
; #pragma unroll
;             for (int m = 0; m < 4; ++m) rs8[ai][m] = rstd[256 * pm + 128 * ai + 64 * wr + 16 * m + fr];
;         if (pn < 4) {
;     ...
;             f32x4 bg[2][2];
; #pragma unroll
;             for (int bj = 0; bj < 2; ++bj)
; #pragma unroll
;                 for (int n = 0; n < 2; ++n) bg[bj][n] = *(const f32x4*)(bgate + 64 * wc + 32 * bj + 8 * fq + 4 * n);
; #pragma unroll
;             for (int ai = 0; ai < 2; ++ai)
; #pragma unroll
;                 for (int m = 0; m < 4; ++m) {
;                     const int rowa = 256 * pm + 128 * ai + 64 * wr + 16 * m + tt.rr;
;                     const float rs = rs8[ai][m];
;                     v4u pk[2];
; #pragma unroll
;                     for (int bj = 0; bj < 2; ++bj) {
;                         f32x4 r2[2];
; #pragma unroll
;                         for (int n = 0; n < 2; ++n) {
;                             const f32x4 z = acc[ai][bj][m][n] * rs + bg[bj][n];
; #pragma unroll
;                             for (int j = 0; j < 4; ++j) { const float az = fabsf(z[j]); r2[n][j] = (fminf(z[j], 0.f) - __logf(1.0f + fast_exp(-az))) * (1.0f / 16.0f); }
.LBB0_414:
	v_mov_b32_e32 v158, v216
	v_mov_b32_e32 v146, v1
	s_lshl_b32 s9, s8, 8
	v_add_u32_e32 v159, s66, v146
	v_add_u32_e32 v130, s9, v159
	v_ashrrev_i32_e32 v131, 31, v130
	v_lshl_add_u64 v[132:133], v[130:131], 2, s[16:17]
	v_add_u32_e32 v134, 16, v130
	v_add_u32_e32 v136, 32, v130
	v_add_u32_e32 v138, 48, v130
	v_add_u32_e32 v140, 0x80, v130
	v_add_u32_e32 v142, 0x90, v130
	v_add_u32_e32 v144, 0xa0, v130
	v_add_u32_e32 v130, 0xb0, v130
	v_ashrrev_i32_e32 v135, 31, v134
	v_ashrrev_i32_e32 v137, 31, v136
	v_ashrrev_i32_e32 v139, 31, v138
	v_ashrrev_i32_e32 v141, 31, v140
	v_ashrrev_i32_e32 v143, 31, v142
	v_ashrrev_i32_e32 v145, 31, v144
	v_ashrrev_i32_e32 v131, 31, v130
	v_lshl_add_u64 v[134:135], v[134:135], 2, s[16:17]
	v_lshl_add_u64 v[136:137], v[136:137], 2, s[16:17]
	v_lshl_add_u64 v[138:139], v[138:139], 2, s[16:17]
	v_lshl_add_u64 v[140:141], v[140:141], 2, s[16:17]
	v_lshl_add_u64 v[142:143], v[142:143], 2, s[16:17]
	v_lshl_add_u64 v[144:145], v[144:145], 2, s[16:17]
	v_lshl_add_u64 v[130:131], v[130:131], 2, s[16:17]
	global_load_dword v162, v[132:133], off
	global_load_dword v210, v[134:135], off
	global_load_dword v208, v[136:137], off
	global_load_dword v206, v[138:139], off
	global_load_dword v204, v[140:141], off
	global_load_dword v202, v[142:143], off
	global_load_dword v198, v[144:145], off
	global_load_dword v196, v[130:131], off
	v_lshlrev_b32_e32 v200, 4, v158
	v_add_u32_e32 v130, v200, v146
	v_and_b32_e32 v213, 7, v146
	v_add_u32_e32 v132, 4, v158
	v_lshlrev_b32_e32 v133, 1, v158
	v_ashrrev_i32_e32 v227, 3, v130
	v_lshlrev_b32_e32 v130, 7, v146
	v_bitop3_b32 v131, v146, v158, 7 bitop3:0x6c
	v_bitop3_b32 v132, v132, v146, 7 bitop3:0x78
	v_bitop3_b32 v134, v133, v146, 7 bitop3:0x78
	v_bitop3_b32 v133, v133, v213, 1 bitop3:0x36
	v_lshl_add_u32 v225, v133, 4, v130
	v_bitop3_b32 v133, v227, v146, 7 bitop3:0x78
	s_cmpk_gt_i32 s8, 0xff
	v_lshl_add_u32 v229, v131, 4, v130
	v_lshl_add_u32 v228, v132, 4, v130
	v_lshl_add_u32 v226, v134, 4, v130
	v_lshlrev_b32_e32 v130, 7, v227
	s_cselect_b64 s[4:5], -1, 0
	v_lshl_add_u32 v230, v133, 4, v130
	s_cmp_gt_i32 s42, 3
	s_mov_b64 s[6:7], -1
	s_cbranch_scc0 .LBB0_475
	s_cmp_gt_u32 s42, 5
	s_cbranch_scc0 .LBB0_457
	s_cmp_gt_u32 s42, 7
	s_cbranch_scc0 .LBB0_454
	s_add_i32 s0, s9, s66
	v_add_u32_e32 v150, s0, v227
	s_cmp_gt_u32 s42, 13
	v_ashrrev_i32_e32 v151, 31, v150
	s_cbranch_scc0 .LBB0_419
	v_lshlrev_b32_e32 v130, 3, v158
	v_ashrrev_i32_e32 v131, 31, v130
	v_lshl_add_u64 v[130:131], v[130:131], 2, v[186:187]
	flat_load_dwordx4 v[142:145], v[130:131]
	flat_load_dwordx4 v[138:141], v[130:131] offset:16
	flat_load_dwordx4 v[134:137], v[130:131] offset:128
	s_nop 0
	flat_load_dwordx4 v[130:133], v[130:131] offset:144
	v_lshlrev_b32_e32 v184, 4, v213
	s_waitcnt vmcnt(0) lgkmcnt(0)
	v_fma_f32 v147, v126, v162, v142
	v_min_f32_e32 v146, 0, v147
	v_mul_f32_e64 v147, |v147|, s88
	v_exp_f32_e32 v147, v147
	v_fma_f32 v149, v127, v162, v143
	v_fma_f32 v153, v129, v162, v145
	v_fma_f32 v155, v123, v162, v139
	v_add_f32_e32 v147, 1.0, v147
	v_cmp_gt_f32_e32 vcc, s89, v147
	v_fma_f32 v157, v125, v162, v141
	v_fma_f32 v161, v115, v162, v131
	v_cndmask_b32_e64 v148, 0, 32, vcc
	v_ldexp_f32 v147, v147, v148
	v_log_f32_e32 v147, v147
	v_fma_f32 v167, v101, v210, v133
	v_mul_f32_e32 v148, 0x3f317217, v147
	v_fma_f32 v148, v147, s90, -v148
	v_fmac_f32_e32 v148, 0x3377d1cf, v147
	v_fmac_f32_e32 v148, 0x3f317217, v147
	v_cmp_lt_f32_e64 s[6:7], |v147|, s91
	s_nop 1
	v_cndmask_b32_e64 v147, v147, v148, s[6:7]
	v_cndmask_b32_e32 v148, 0, v222, vcc
	v_sub_f32_e32 v148, v147, v148
	v_min_f32_e32 v147, 0, v149
	v_mul_f32_e64 v149, |v149|, s88
	v_exp_f32_e32 v149, v149
	s_nop 0
	v_add_f32_e32 v149, 1.0, v149
	v_cmp_gt_f32_e32 vcc, s89, v149
	s_nop 1
	v_cndmask_b32_e64 v152, 0, 32, vcc
	v_ldexp_f32 v149, v149, v152
	v_log_f32_e32 v149, v149
	s_nop 0
	v_mul_f32_e32 v152, 0x3f317217, v149
	v_fma_f32 v152, v149, s90, -v152
	v_fmac_f32_e32 v152, 0x3377d1cf, v149
	v_fmac_f32_e32 v152, 0x3f317217, v149
	v_cmp_lt_f32_e64 s[6:7], |v149|, s91
	s_nop 1
	v_cndmask_b32_e64 v149, v149, v152, s[6:7]
	v_cndmask_b32_e32 v152, 0, v222, vcc
	v_sub_f32_e32 v149, v149, v152
	v_pk_add_f32 v[146:147], v[146:147], v[148:149] neg_lo:[0,1] neg_hi:[0,1]
	v_fma_f32 v149, v128, v162, v144
	v_min_f32_e32 v148, 0, v149
	v_mul_f32_e64 v149, |v149|, s88
	v_exp_f32_e32 v149, v149
	v_pk_mul_f32 v[146:147], v[146:147], s[28:29] op_sel_hi:[1,0]
	v_add_f32_e32 v149, 1.0, v149
	v_cmp_gt_f32_e32 vcc, s89, v149
	v_cvt_pk_bf16_f32 v146, v146, v147
	s_nop 0
	v_cndmask_b32_e64 v152, 0, 32, vcc
	v_ldexp_f32 v149, v149, v152
	v_log_f32_e32 v149, v149
	s_nop 0
	v_mul_f32_e32 v152, 0x3f317217, v149
	v_fma_f32 v152, v149, s90, -v152
	v_fmac_f32_e32 v152, 0x3377d1cf, v149
	v_fmac_f32_e32 v152, 0x3f317217, v149
	v_cmp_lt_f32_e64 s[6:7], |v149|, s91
	s_nop 1
	v_cndmask_b32_e64 v149, v149, v152, s[6:7]
	v_cndmask_b32_e32 v152, 0, v222, vcc
	v_sub_f32_e32 v152, v149, v152
	v_min_f32_e32 v149, 0, v153
	v_mul_f32_e64 v153, |v153|, s88
	v_exp_f32_e32 v153, v153
	s_nop 0
	v_add_f32_e32 v153, 1.0, v153
	v_cmp_gt_f32_e32 vcc, s89, v153
	s_nop 1
	v_cndmask_b32_e64 v154, 0, 32, vcc
	v_ldexp_f32 v153, v153, v154
	v_log_f32_e32 v153, v153
	s_nop 0
	v_mul_f32_e32 v154, 0x3f317217, v153
	v_fma_f32 v154, v153, s90, -v154
	v_fmac_f32_e32 v154, 0x3377d1cf, v153
	v_fmac_f32_e32 v154, 0x3f317217, v153
	v_cmp_lt_f32_e64 s[6:7], |v153|, s91
	s_nop 1
	v_cndmask_b32_e64 v153, v153, v154, s[6:7]
	v_cndmask_b32_e32 v154, 0, v222, vcc
	v_sub_f32_e32 v153, v153, v154
	v_pk_add_f32 v[148:149], v[148:149], v[152:153] neg_lo:[0,1] neg_hi:[0,1]
	v_fma_f32 v153, v122, v162, v138
; __device__ __forceinline__ v4u pack8(const f32x4 a, const f32x4 b) { v4u w; w.x = pk2(a[0], a[1]); w.y = pk2(a[2], a[3]); w.z = pk2(b[0], b[1]); w.w = pk2(b[2], b[3]); return w; }
; __device__ __forceinline__ float fast_exp(float x) { return __builtin_amdgcn_exp2f(x * LOG2E); }
;     __device__ __forceinline__ void operator()(const f32x4 (&acc)[2][2][4][2], const pg8::Unit& u, int wr, int wc, int fr, int fq) const {
;     ...
; #pragma unroll
;             for (int ai = 0; ai < 2; ++ai)
; #pragma unroll
;                 for (int m = 0; m < 4; ++m) {
;                     const int rowa = 256 * pm + 128 * ai + 64 * wr + 16 * m + tt.rr;
;                     const float rs = rs8[ai][m];
;                     v4u pk[2];
; #pragma unroll
;                     for (int bj = 0; bj < 2; ++bj) {
;                         f32x4 r2[2];
; #pragma unroll
;                         for (int n = 0; n < 2; ++n) {
;                             const f32x4 z = acc[ai][bj][m][n] * rs + bg[bj][n];
; #pragma unroll
;                             for (int j = 0; j < 4; ++j) { const float az = fabsf(z[j]); r2[n][j] = (fminf(z[j], 0.f) - __logf(1.0f + fast_exp(-az))) * (1.0f / 16.0f); }
;                         }
;                         pk[bj] = pack8(r2[0], r2[1]);
;                     }
;                     v4u a, b; tt.bf(pk[0], pk[1], a, b);
;                     bf16* d = (bf16*)(ws + WS_LOGA) + (size_t)rowa * 256 + 64 * wc + 8 * tt.p; *(v4u*)d = a; *(v4u*)(d + 8 * 256) = b;
	v_min_f32_e32 v152, 0, v153
	v_mul_f32_e64 v153, |v153|, s88
	v_exp_f32_e32 v153, v153
	v_pk_mul_f32 v[148:149], v[148:149], s[28:29] op_sel_hi:[1,0]
	v_add_f32_e32 v153, 1.0, v153
	v_cmp_gt_f32_e32 vcc, s89, v153
	v_cvt_pk_bf16_f32 v147, v148, v149
	s_nop 0
	v_cndmask_b32_e64 v154, 0, 32, vcc
	v_ldexp_f32 v153, v153, v154
	v_log_f32_e32 v153, v153
	s_nop 0
	v_mul_f32_e32 v154, 0x3f317217, v153
	v_fma_f32 v154, v153, s90, -v154
	v_fmac_f32_e32 v154, 0x3377d1cf, v153
	v_fmac_f32_e32 v154, 0x3f317217, v153
	v_cmp_lt_f32_e64 s[6:7], |v153|, s91
	s_nop 1
	v_cndmask_b32_e64 v153, v153, v154, s[6:7]
	v_cndmask_b32_e32 v154, 0, v222, vcc
	v_sub_f32_e32 v154, v153, v154
	v_min_f32_e32 v153, 0, v155
	v_mul_f32_e64 v155, |v155|, s88
	v_exp_f32_e32 v155, v155
	s_nop 0
	v_add_f32_e32 v155, 1.0, v155
	v_cmp_gt_f32_e32 vcc, s89, v155
	s_nop 1
	v_cndmask_b32_e64 v156, 0, 32, vcc
	v_ldexp_f32 v155, v155, v156
	v_log_f32_e32 v155, v155
	s_nop 0
	v_mul_f32_e32 v156, 0x3f317217, v155
	v_fma_f32 v156, v155, s90, -v156
	v_fmac_f32_e32 v156, 0x3377d1cf, v155
	v_fmac_f32_e32 v156, 0x3f317217, v155
	v_cmp_lt_f32_e64 s[6:7], |v155|, s91
	s_nop 1
	v_cndmask_b32_e64 v155, v155, v156, s[6:7]
	v_cndmask_b32_e32 v156, 0, v222, vcc
	v_sub_f32_e32 v155, v155, v156
	v_pk_add_f32 v[152:153], v[152:153], v[154:155] neg_lo:[0,1] neg_hi:[0,1]
	v_fma_f32 v155, v124, v162, v140
	v_min_f32_e32 v154, 0, v155
	v_mul_f32_e64 v155, |v155|, s88
	v_exp_f32_e32 v155, v155
	v_pk_mul_f32 v[152:153], v[152:153], s[28:29] op_sel_hi:[1,0]
	v_add_f32_e32 v155, 1.0, v155
	v_cmp_gt_f32_e32 vcc, s89, v155
	v_cvt_pk_bf16_f32 v148, v152, v153
	v_fma_f32 v153, v118, v162, v134
	v_cndmask_b32_e64 v156, 0, 32, vcc
	v_ldexp_f32 v155, v155, v156
	v_log_f32_e32 v155, v155
	v_min_f32_e32 v152, 0, v153
	v_mul_f32_e64 v153, |v153|, s88
	v_exp_f32_e32 v153, v153
	v_mul_f32_e32 v156, 0x3f317217, v155
	v_fma_f32 v156, v155, s90, -v156
	v_fmac_f32_e32 v156, 0x3377d1cf, v155
	v_fmac_f32_e32 v156, 0x3f317217, v155
	v_cmp_lt_f32_e64 s[6:7], |v155|, s91
	v_add_f32_e32 v153, 1.0, v153
	s_nop 0
	v_cndmask_b32_e64 v155, v155, v156, s[6:7]
	v_cndmask_b32_e32 v156, 0, v222, vcc
	v_sub_f32_e32 v156, v155, v156
	v_min_f32_e32 v155, 0, v157
	v_mul_f32_e64 v157, |v157|, s88
	v_exp_f32_e32 v157, v157
	s_nop 0
	v_add_f32_e32 v157, 1.0, v157
	v_cmp_gt_f32_e32 vcc, s89, v157
	s_nop 1
	v_cndmask_b32_e64 v160, 0, 32, vcc
	v_ldexp_f32 v157, v157, v160
	v_log_f32_e32 v157, v157
	s_nop 0
	v_mul_f32_e32 v160, 0x3f317217, v157
	v_fma_f32 v160, v157, s90, -v160
	v_fmac_f32_e32 v160, 0x3377d1cf, v157
	v_fmac_f32_e32 v160, 0x3f317217, v157
	v_cmp_lt_f32_e64 s[6:7], |v157|, s91
	s_nop 1
	v_cndmask_b32_e64 v157, v157, v160, s[6:7]
	v_cndmask_b32_e32 v160, 0, v222, vcc
	v_sub_f32_e32 v157, v157, v160
	v_pk_add_f32 v[154:155], v[154:155], v[156:157] neg_lo:[0,1] neg_hi:[0,1]
	v_cmp_gt_f32_e32 vcc, s89, v153
	v_pk_mul_f32 v[154:155], v[154:155], s[28:29] op_sel_hi:[1,0]
	v_fma_f32 v157, v121, v162, v137
	v_cvt_pk_bf16_f32 v149, v154, v155
	v_cndmask_b32_e64 v154, 0, 32, vcc
	v_ldexp_f32 v153, v153, v154
	v_log_f32_e32 v153, v153
	v_fma_f32 v155, v119, v162, v135
	v_mul_f32_e32 v154, 0x3f317217, v153
	v_fma_f32 v154, v153, s90, -v154
	v_fmac_f32_e32 v154, 0x3377d1cf, v153
	v_fmac_f32_e32 v154, 0x3f317217, v153
	v_cmp_lt_f32_e64 s[6:7], |v153|, s91
	s_nop 1
	v_cndmask_b32_e64 v153, v153, v154, s[6:7]
	v_cndmask_b32_e32 v154, 0, v222, vcc
	v_sub_f32_e32 v154, v153, v154
	v_min_f32_e32 v153, 0, v155
	v_mul_f32_e64 v155, |v155|, s88
	v_exp_f32_e32 v155, v155
	s_nop 0
	v_add_f32_e32 v155, 1.0, v155
	v_cmp_gt_f32_e32 vcc, s89, v155
	s_nop 1
	v_cndmask_b32_e64 v156, 0, 32, vcc
	v_ldexp_f32 v155, v155, v156
	v_log_f32_e32 v155, v155
	s_nop 0
	v_mul_f32_e32 v156, 0x3f317217, v155
	v_fma_f32 v156, v155, s90, -v156
	v_fmac_f32_e32 v156, 0x3377d1cf, v155
	v_fmac_f32_e32 v156, 0x3f317217, v155
	v_cmp_lt_f32_e64 s[6:7], |v155|, s91
	s_nop 1
	v_cndmask_b32_e64 v155, v155, v156, s[6:7]
	v_cndmask_b32_e32 v156, 0, v222, vcc
	v_sub_f32_e32 v155, v155, v156
	v_pk_add_f32 v[152:153], v[152:153], v[154:155] neg_lo:[0,1] neg_hi:[0,1]
	v_fma_f32 v155, v120, v162, v136
	v_min_f32_e32 v154, 0, v155
	v_mul_f32_e64 v155, |v155|, s88
	v_exp_f32_e32 v155, v155
	v_pk_mul_f32 v[152:153], v[152:153], s[28:29] op_sel_hi:[1,0]
	v_add_f32_e32 v155, 1.0, v155
	v_cmp_gt_f32_e32 vcc, s89, v155
	v_cvt_pk_bf16_f32 v152, v152, v153
	s_nop 0
	v_cndmask_b32_e64 v156, 0, 32, vcc
	v_ldexp_f32 v155, v155, v156
	v_log_f32_e32 v155, v155
	s_nop 0
	v_mul_f32_e32 v156, 0x3f317217, v155
	v_fma_f32 v156, v155, s90, -v156
	v_fmac_f32_e32 v156, 0x3377d1cf, v155
	v_fmac_f32_e32 v156, 0x3f317217, v155
	v_cmp_lt_f32_e64 s[6:7], |v155|, s91
	s_nop 1
	v_cndmask_b32_e64 v155, v155, v156, s[6:7]
	v_cndmask_b32_e32 v156, 0, v222, vcc
	v_sub_f32_e32 v156, v155, v156
	v_min_f32_e32 v155, 0, v157
	v_mul_f32_e64 v157, |v157|, s88
	v_exp_f32_e32 v157, v157
	s_nop 0
	v_add_f32_e32 v157, 1.0, v157
	v_cmp_gt_f32_e32 vcc, s89, v157
	s_nop 1
	v_cndmask_b32_e64 v160, 0, 32, vcc
	v_ldexp_f32 v157, v157, v160
	v_log_f32_e32 v157, v157
	s_nop 0
	v_mul_f32_e32 v160, 0x3f317217, v157
	v_fma_f32 v160, v157, s90, -v160
	v_fmac_f32_e32 v160, 0x3377d1cf, v157
	v_fmac_f32_e32 v160, 0x3f317217, v157
	v_cmp_lt_f32_e64 s[6:7], |v157|, s91
	s_nop 1
	v_cndmask_b32_e64 v157, v157, v160, s[6:7]
	v_cndmask_b32_e32 v160, 0, v222, vcc
	v_sub_f32_e32 v157, v157, v160
	v_pk_add_f32 v[154:155], v[154:155], v[156:157] neg_lo:[0,1] neg_hi:[0,1]
	v_fma_f32 v157, v114, v162, v130
	v_min_f32_e32 v156, 0, v157
	v_mul_f32_e64 v157, |v157|, s88
	v_exp_f32_e32 v157, v157
	v_pk_mul_f32 v[154:155], v[154:155], s[28:29] op_sel_hi:[1,0]
; __device__ __forceinline__ v4u pack8(const f32x4 a, const f32x4 b) { v4u w; w.x = pk2(a[0], a[1]); w.y = pk2(a[2], a[3]); w.z = pk2(b[0], b[1]); w.w = pk2(b[2], b[3]); return w; }
; __device__ __forceinline__ float fast_exp(float x) { return __builtin_amdgcn_exp2f(x * LOG2E); }
;     __device__ __forceinline__ void operator()(const f32x4 (&acc)[2][2][4][2], const pg8::Unit& u, int wr, int wc, int fr, int fq) const {
;     ...
;             for (int ai = 0; ai < 2; ++ai)
; #pragma unroll
;                 for (int m = 0; m < 4; ++m) {
;                     const int rowa = 256 * pm + 128 * ai + 64 * wr + 16 * m + tt.rr;
;                     const float rs = rs8[ai][m];
;                     v4u pk[2];
; #pragma unroll
;                     for (int bj = 0; bj < 2; ++bj) {
;                         f32x4 r2[2];
; #pragma unroll
;                         for (int n = 0; n < 2; ++n) {
;                             const f32x4 z = acc[ai][bj][m][n] * rs + bg[bj][n];
; #pragma unroll
;                             for (int j = 0; j < 4; ++j) { const float az = fabsf(z[j]); r2[n][j] = (fminf(z[j], 0.f) - __logf(1.0f + fast_exp(-az))) * (1.0f / 16.0f); }
;                         }
;                         pk[bj] = pack8(r2[0], r2[1]);
;                     }
;                     v4u a, b; tt.bf(pk[0], pk[1], a, b);
;                     bf16* d = (bf16*)(ws + WS_LOGA) + (size_t)rowa * 256 + 64 * wc + 8 * tt.p; *(v4u*)d = a; *(v4u*)(d + 8 * 256) = b;
	v_add_f32_e32 v157, 1.0, v157
	v_cmp_gt_f32_e32 vcc, s89, v157
	v_cvt_pk_bf16_f32 v153, v154, v155
	s_nop 0
	v_cndmask_b32_e64 v160, 0, 32, vcc
	v_ldexp_f32 v157, v157, v160
	v_log_f32_e32 v157, v157
	s_nop 0
	v_mul_f32_e32 v160, 0x3f317217, v157
	v_fma_f32 v160, v157, s90, -v160
	v_fmac_f32_e32 v160, 0x3377d1cf, v157
	v_fmac_f32_e32 v160, 0x3f317217, v157
	v_cmp_lt_f32_e64 s[6:7], |v157|, s91
	s_nop 1
	v_cndmask_b32_e64 v157, v157, v160, s[6:7]
	v_cndmask_b32_e32 v160, 0, v222, vcc
	v_sub_f32_e32 v160, v157, v160
	v_min_f32_e32 v157, 0, v161
	v_mul_f32_e64 v161, |v161|, s88
	v_exp_f32_e32 v161, v161
	s_nop 0
	v_add_f32_e32 v161, 1.0, v161
	v_cmp_gt_f32_e32 vcc, s89, v161
	s_nop 1
	v_cndmask_b32_e64 v163, 0, 32, vcc
	v_ldexp_f32 v161, v161, v163
	v_log_f32_e32 v161, v161
	s_nop 0
	v_mul_f32_e32 v163, 0x3f317217, v161
	v_fma_f32 v163, v161, s90, -v163
	v_fmac_f32_e32 v163, 0x3377d1cf, v161
	v_fmac_f32_e32 v163, 0x3f317217, v161
	v_cmp_lt_f32_e64 s[6:7], |v161|, s91
	s_nop 1
	v_cndmask_b32_e64 v161, v161, v163, s[6:7]
	v_cndmask_b32_e32 v163, 0, v222, vcc
	v_sub_f32_e32 v161, v161, v163
	v_pk_add_f32 v[156:157], v[156:157], v[160:161] neg_lo:[0,1] neg_hi:[0,1]
	v_fma_f32 v161, v116, v162, v132
	v_min_f32_e32 v160, 0, v161
	v_mul_f32_e64 v161, |v161|, s88
	v_exp_f32_e32 v161, v161
	v_pk_mul_f32 v[156:157], v[156:157], s[28:29] op_sel_hi:[1,0]
	v_add_f32_e32 v161, 1.0, v161
	v_cmp_gt_f32_e32 vcc, s89, v161
	v_cvt_pk_bf16_f32 v154, v156, v157
	v_lshlrev_b64 v[156:157], 9, v[150:151]
	v_cndmask_b32_e64 v163, 0, 32, vcc
	v_ldexp_f32 v161, v161, v163
	v_log_f32_e32 v161, v161
	v_lshl_add_u64 v[156:157], s[24:25], 0, v[156:157]
	v_lshl_add_u64 v[156:157], v[156:157], 0, v[184:185]
	v_mul_f32_e32 v163, 0x3f317217, v161
	v_fma_f32 v163, v161, s90, -v163
	v_fmac_f32_e32 v163, 0x3377d1cf, v161
	v_fmac_f32_e32 v163, 0x3f317217, v161
	v_cmp_lt_f32_e64 s[6:7], |v161|, s91
	s_nop 1
	v_cndmask_b32_e64 v161, v161, v163, s[6:7]
	v_cndmask_b32_e32 v163, 0, v222, vcc
	v_sub_f32_e32 v164, v161, v163
	v_fma_f32 v163, v117, v162, v133
	v_min_f32_e32 v161, 0, v163
	v_mul_f32_e64 v163, |v163|, s88
	v_exp_f32_e32 v163, v163
	s_nop 0
	v_add_f32_e32 v163, 1.0, v163
	v_cmp_gt_f32_e32 vcc, s89, v163
	s_nop 1
	v_cndmask_b32_e64 v165, 0, 32, vcc
	v_ldexp_f32 v163, v163, v165
	v_log_f32_e32 v163, v163
	s_nop 0
	v_mul_f32_e32 v165, 0x3f317217, v163
	v_fma_f32 v165, v163, s90, -v165
	v_fmac_f32_e32 v165, 0x3377d1cf, v163
	v_fmac_f32_e32 v165, 0x3f317217, v163
	v_cmp_lt_f32_e64 s[6:7], |v163|, s91
	s_nop 1
	v_cndmask_b32_e64 v163, v163, v165, s[6:7]
	v_cndmask_b32_e32 v165, 0, v222, vcc
	v_sub_f32_e32 v165, v163, v165
	v_pk_add_f32 v[160:161], v[160:161], v[164:165] neg_lo:[0,1] neg_hi:[0,1]
	v_add_u32_e32 v163, s77, v230
	v_pk_mul_f32 v[160:161], v[160:161], s[28:29] op_sel_hi:[1,0]
	v_fma_f32 v165, v99, v210, v131
	v_cvt_pk_bf16_f32 v155, v160, v161
	v_add_u32_e32 v160, s77, v229
	v_add_u32_e32 v161, s77, v228
	ds_write_b128 v160, v[146:149]
	ds_write_b128 v161, v[152:155]
	ds_read_b128 v[146:149], v163
	ds_read_b128 v[152:155], v163 offset:1024
	s_waitcnt lgkmcnt(1)
	global_store_dwordx4 v[156:157], v[146:149], off sc1
	s_nop 1
	v_add_co_u32_e32 v146, vcc, s92, v156
	v_fma_f32 v149, v111, v210, v143
	s_nop 0
	v_addc_co_u32_e32 v147, vcc, 0, v157, vcc
	s_waitcnt lgkmcnt(0)
	global_store_dwordx4 v[146:147], v[152:155], off sc1
	v_fma_f32 v147, v110, v210, v142
	v_min_f32_e32 v146, 0, v147
	v_mul_f32_e64 v147, |v147|, s88
	v_exp_f32_e32 v147, v147
	v_fma_f32 v153, v113, v210, v145
	v_fma_f32 v155, v107, v210, v139
	v_fma_f32 v157, v109, v210, v141
	v_add_f32_e32 v147, 1.0, v147
	v_cmp_gt_f32_e32 vcc, s89, v147
	s_nop 1
	v_cndmask_b32_e64 v148, 0, 32, vcc
	v_ldexp_f32 v147, v147, v148
	v_log_f32_e32 v147, v147
	s_nop 0
	v_mul_f32_e32 v148, 0x3f317217, v147
	v_fma_f32 v148, v147, s90, -v148
	v_fmac_f32_e32 v148, 0x3377d1cf, v147
	v_fmac_f32_e32 v148, 0x3f317217, v147
	v_cmp_lt_f32_e64 s[6:7], |v147|, s91
	s_nop 1
	v_cndmask_b32_e64 v147, v147, v148, s[6:7]
	v_cndmask_b32_e32 v148, 0, v222, vcc
	v_sub_f32_e32 v148, v147, v148
	v_min_f32_e32 v147, 0, v149
	v_mul_f32_e64 v149, |v149|, s88
	v_exp_f32_e32 v149, v149
	s_nop 0
	v_add_f32_e32 v149, 1.0, v149
	v_cmp_gt_f32_e32 vcc, s89, v149
	s_nop 1
	v_cndmask_b32_e64 v152, 0, 32, vcc
	v_ldexp_f32 v149, v149, v152
	v_log_f32_e32 v149, v149
	s_nop 0
	v_mul_f32_e32 v152, 0x3f317217, v149
	v_fma_f32 v152, v149, s90, -v152
	v_fmac_f32_e32 v152, 0x3377d1cf, v149
	v_fmac_f32_e32 v152, 0x3f317217, v149
	v_cmp_lt_f32_e64 s[6:7], |v149|, s91
	s_nop 1
	v_cndmask_b32_e64 v149, v149, v152, s[6:7]
	v_cndmask_b32_e32 v152, 0, v222, vcc
	v_sub_f32_e32 v149, v149, v152
	v_pk_add_f32 v[146:147], v[146:147], v[148:149] neg_lo:[0,1] neg_hi:[0,1]
	v_fma_f32 v149, v112, v210, v144
	v_min_f32_e32 v148, 0, v149
	v_mul_f32_e64 v149, |v149|, s88
	v_exp_f32_e32 v149, v149
	v_pk_mul_f32 v[146:147], v[146:147], s[28:29] op_sel_hi:[1,0]
	v_add_f32_e32 v149, 1.0, v149
	v_cmp_gt_f32_e32 vcc, s89, v149
	v_cvt_pk_bf16_f32 v146, v146, v147
	s_nop 0
	v_cndmask_b32_e64 v152, 0, 32, vcc
	v_ldexp_f32 v149, v149, v152
	v_log_f32_e32 v149, v149
	s_nop 0
	v_mul_f32_e32 v152, 0x3f317217, v149
	v_fma_f32 v152, v149, s90, -v152
	v_fmac_f32_e32 v152, 0x3377d1cf, v149
	v_fmac_f32_e32 v152, 0x3f317217, v149
	v_cmp_lt_f32_e64 s[6:7], |v149|, s91
	s_nop 1
	v_cndmask_b32_e64 v149, v149, v152, s[6:7]
	v_cndmask_b32_e32 v152, 0, v222, vcc
	v_sub_f32_e32 v152, v149, v152
	v_min_f32_e32 v149, 0, v153
	v_mul_f32_e64 v153, |v153|, s88
	v_exp_f32_e32 v153, v153
	s_nop 0
	v_add_f32_e32 v153, 1.0, v153
	v_cmp_gt_f32_e32 vcc, s89, v153
	s_nop 1
	v_cndmask_b32_e64 v154, 0, 32, vcc
; __device__ __forceinline__ v4u pack8(const f32x4 a, const f32x4 b) { v4u w; w.x = pk2(a[0], a[1]); w.y = pk2(a[2], a[3]); w.z = pk2(b[0], b[1]); w.w = pk2(b[2], b[3]); return w; }
; __device__ __forceinline__ float fast_exp(float x) { return __builtin_amdgcn_exp2f(x * LOG2E); }
;     __device__ __forceinline__ void operator()(const f32x4 (&acc)[2][2][4][2], const pg8::Unit& u, int wr, int wc, int fr, int fq) const {
;     ...
;             for (int ai = 0; ai < 2; ++ai)
; #pragma unroll
;                 for (int m = 0; m < 4; ++m) {
;                     const int rowa = 256 * pm + 128 * ai + 64 * wr + 16 * m + tt.rr;
;                     const float rs = rs8[ai][m];
;                     v4u pk[2];
; #pragma unroll
;                     for (int bj = 0; bj < 2; ++bj) {
;                         f32x4 r2[2];
; #pragma unroll
;                         for (int n = 0; n < 2; ++n) {
;                             const f32x4 z = acc[ai][bj][m][n] * rs + bg[bj][n];
; #pragma unroll
;                             for (int j = 0; j < 4; ++j) { const float az = fabsf(z[j]); r2[n][j] = (fminf(z[j], 0.f) - __logf(1.0f + fast_exp(-az))) * (1.0f / 16.0f); }
;                         }
;                         pk[bj] = pack8(r2[0], r2[1]);
;                     }
;                     v4u a, b; tt.bf(pk[0], pk[1], a, b);
;                     bf16* d = (bf16*)(ws + WS_LOGA) + (size_t)rowa * 256 + 64 * wc + 8 * tt.p; *(v4u*)d = a; *(v4u*)(d + 8 * 256) = b;
	v_ldexp_f32 v153, v153, v154
	v_log_f32_e32 v153, v153
	s_nop 0
	v_mul_f32_e32 v154, 0x3f317217, v153
	v_fma_f32 v154, v153, s90, -v154
	v_fmac_f32_e32 v154, 0x3377d1cf, v153
	v_fmac_f32_e32 v154, 0x3f317217, v153
	v_cmp_lt_f32_e64 s[6:7], |v153|, s91
	s_nop 1
	v_cndmask_b32_e64 v153, v153, v154, s[6:7]
	v_cndmask_b32_e32 v154, 0, v222, vcc
	v_sub_f32_e32 v153, v153, v154
	v_pk_add_f32 v[148:149], v[148:149], v[152:153] neg_lo:[0,1] neg_hi:[0,1]
	v_fma_f32 v153, v106, v210, v138
	v_min_f32_e32 v152, 0, v153
	v_mul_f32_e64 v153, |v153|, s88
	v_exp_f32_e32 v153, v153
	v_pk_mul_f32 v[148:149], v[148:149], s[28:29] op_sel_hi:[1,0]
	v_add_f32_e32 v153, 1.0, v153
	v_cmp_gt_f32_e32 vcc, s89, v153
	v_cvt_pk_bf16_f32 v147, v148, v149
	s_nop 0
	v_cndmask_b32_e64 v154, 0, 32, vcc
	v_ldexp_f32 v153, v153, v154
	v_log_f32_e32 v153, v153
	s_nop 0
	v_mul_f32_e32 v154, 0x3f317217, v153
	v_fma_f32 v154, v153, s90, -v154
	v_fmac_f32_e32 v154, 0x3377d1cf, v153
	v_fmac_f32_e32 v154, 0x3f317217, v153
	v_cmp_lt_f32_e64 s[6:7], |v153|, s91
	s_nop 1
	v_cndmask_b32_e64 v153, v153, v154, s[6:7]
	v_cndmask_b32_e32 v154, 0, v222, vcc
	v_sub_f32_e32 v154, v153, v154
	v_min_f32_e32 v153, 0, v155
	v_mul_f32_e64 v155, |v155|, s88
	v_exp_f32_e32 v155, v155
	s_nop 0
	v_add_f32_e32 v155, 1.0, v155
	v_cmp_gt_f32_e32 vcc, s89, v155
	s_nop 1
	v_cndmask_b32_e64 v156, 0, 32, vcc
	v_ldexp_f32 v155, v155, v156
	v_log_f32_e32 v155, v155
	s_nop 0
	v_mul_f32_e32 v156, 0x3f317217, v155
	v_fma_f32 v156, v155, s90, -v156
	v_fmac_f32_e32 v156, 0x3377d1cf, v155
	v_fmac_f32_e32 v156, 0x3f317217, v155
	v_cmp_lt_f32_e64 s[6:7], |v155|, s91
	s_nop 1
	v_cndmask_b32_e64 v155, v155, v156, s[6:7]
	v_cndmask_b32_e32 v156, 0, v222, vcc
	v_sub_f32_e32 v155, v155, v156
	v_pk_add_f32 v[152:153], v[152:153], v[154:155] neg_lo:[0,1] neg_hi:[0,1]
	v_fma_f32 v155, v108, v210, v140
	v_min_f32_e32 v154, 0, v155
	v_mul_f32_e64 v155, |v155|, s88
	v_exp_f32_e32 v155, v155
	v_pk_mul_f32 v[152:153], v[152:153], s[28:29] op_sel_hi:[1,0]
	v_add_f32_e32 v155, 1.0, v155
	v_cmp_gt_f32_e32 vcc, s89, v155
	v_cvt_pk_bf16_f32 v148, v152, v153
	v_fma_f32 v153, v102, v210, v134
	v_cndmask_b32_e64 v156, 0, 32, vcc
	v_ldexp_f32 v155, v155, v156
	v_log_f32_e32 v155, v155
	v_min_f32_e32 v152, 0, v153
	v_mul_f32_e64 v153, |v153|, s88
	v_exp_f32_e32 v153, v153
	v_mul_f32_e32 v156, 0x3f317217, v155
	v_fma_f32 v156, v155, s90, -v156
	v_fmac_f32_e32 v156, 0x3377d1cf, v155
	v_fmac_f32_e32 v156, 0x3f317217, v155
	v_cmp_lt_f32_e64 s[6:7], |v155|, s91
	v_add_f32_e32 v153, 1.0, v153
	s_nop 0
	v_cndmask_b32_e64 v155, v155, v156, s[6:7]
	v_cndmask_b32_e32 v156, 0, v222, vcc
	v_sub_f32_e32 v156, v155, v156
	v_min_f32_e32 v155, 0, v157
	v_mul_f32_e64 v157, |v157|, s88
	v_exp_f32_e32 v157, v157
	s_nop 0
	v_add_f32_e32 v157, 1.0, v157
	v_cmp_gt_f32_e32 vcc, s89, v157
	s_nop 1
	v_cndmask_b32_e64 v164, 0, 32, vcc
	v_ldexp_f32 v157, v157, v164
	v_log_f32_e32 v157, v157
	s_nop 0
	v_mul_f32_e32 v164, 0x3f317217, v157
	v_fma_f32 v164, v157, s90, -v164
	v_fmac_f32_e32 v164, 0x3377d1cf, v157
	v_fmac_f32_e32 v164, 0x3f317217, v157
	v_cmp_lt_f32_e64 s[6:7], |v157|, s91
	s_nop 1
	v_cndmask_b32_e64 v157, v157, v164, s[6:7]
	v_cndmask_b32_e32 v164, 0, v222, vcc
	v_sub_f32_e32 v157, v157, v164
	v_pk_add_f32 v[154:155], v[154:155], v[156:157] neg_lo:[0,1] neg_hi:[0,1]
	v_cmp_gt_f32_e32 vcc, s89, v153
	v_pk_mul_f32 v[154:155], v[154:155], s[28:29] op_sel_hi:[1,0]
	v_fma_f32 v157, v105, v210, v137
	v_cvt_pk_bf16_f32 v149, v154, v155
	v_cndmask_b32_e64 v154, 0, 32, vcc
	v_ldexp_f32 v153, v153, v154
	v_log_f32_e32 v153, v153
	v_fma_f32 v155, v103, v210, v135
	v_mul_f32_e32 v154, 0x3f317217, v153
	v_fma_f32 v154, v153, s90, -v154
	v_fmac_f32_e32 v154, 0x3377d1cf, v153
	v_fmac_f32_e32 v154, 0x3f317217, v153
	v_cmp_lt_f32_e64 s[6:7], |v153|, s91
	s_nop 1
	v_cndmask_b32_e64 v153, v153, v154, s[6:7]
	v_cndmask_b32_e32 v154, 0, v222, vcc
	v_sub_f32_e32 v154, v153, v154
	v_min_f32_e32 v153, 0, v155
	v_mul_f32_e64 v155, |v155|, s88
	v_exp_f32_e32 v155, v155
	s_nop 0
	v_add_f32_e32 v155, 1.0, v155
	v_cmp_gt_f32_e32 vcc, s89, v155
	s_nop 1
	v_cndmask_b32_e64 v156, 0, 32, vcc
	v_ldexp_f32 v155, v155, v156
	v_log_f32_e32 v155, v155
	s_nop 0
	v_mul_f32_e32 v156, 0x3f317217, v155
	v_fma_f32 v156, v155, s90, -v156
	v_fmac_f32_e32 v156, 0x3377d1cf, v155
	v_fmac_f32_e32 v156, 0x3f317217, v155
	v_cmp_lt_f32_e64 s[6:7], |v155|, s91
	s_nop 1
	v_cndmask_b32_e64 v155, v155, v156, s[6:7]
	v_cndmask_b32_e32 v156, 0, v222, vcc
	v_sub_f32_e32 v155, v155, v156
	v_pk_add_f32 v[152:153], v[152:153], v[154:155] neg_lo:[0,1] neg_hi:[0,1]
	v_fma_f32 v155, v104, v210, v136
	v_min_f32_e32 v154, 0, v155
	v_mul_f32_e64 v155, |v155|, s88
	v_exp_f32_e32 v155, v155
	v_pk_mul_f32 v[152:153], v[152:153], s[28:29] op_sel_hi:[1,0]
	v_add_f32_e32 v155, 1.0, v155
	v_cmp_gt_f32_e32 vcc, s89, v155
	v_cvt_pk_bf16_f32 v152, v152, v153
	s_nop 0
	v_cndmask_b32_e64 v156, 0, 32, vcc
	v_ldexp_f32 v155, v155, v156
	v_log_f32_e32 v155, v155
	s_nop 0
	v_mul_f32_e32 v156, 0x3f317217, v155
	v_fma_f32 v156, v155, s90, -v156
	v_fmac_f32_e32 v156, 0x3377d1cf, v155
	v_fmac_f32_e32 v156, 0x3f317217, v155
	v_cmp_lt_f32_e64 s[6:7], |v155|, s91
	s_nop 1
	v_cndmask_b32_e64 v155, v155, v156, s[6:7]
	v_cndmask_b32_e32 v156, 0, v222, vcc
	v_sub_f32_e32 v156, v155, v156
	v_min_f32_e32 v155, 0, v157
	v_mul_f32_e64 v157, |v157|, s88
	v_exp_f32_e32 v157, v157
	s_nop 0
	v_add_f32_e32 v157, 1.0, v157
	v_cmp_gt_f32_e32 vcc, s89, v157
	s_nop 1
	v_cndmask_b32_e64 v164, 0, 32, vcc
	v_ldexp_f32 v157, v157, v164
	v_log_f32_e32 v157, v157
	s_nop 0
	v_mul_f32_e32 v164, 0x3f317217, v157
	v_fma_f32 v164, v157, s90, -v164
; __device__ __forceinline__ v4u pack8(const f32x4 a, const f32x4 b) { v4u w; w.x = pk2(a[0], a[1]); w.y = pk2(a[2], a[3]); w.z = pk2(b[0], b[1]); w.w = pk2(b[2], b[3]); return w; }
; __device__ __forceinline__ float fast_exp(float x) { return __builtin_amdgcn_exp2f(x * LOG2E); }
;     __device__ __forceinline__ void operator()(const f32x4 (&acc)[2][2][4][2], const pg8::Unit& u, int wr, int wc, int fr, int fq) const {
;     ...
;             for (int ai = 0; ai < 2; ++ai)
; #pragma unroll
;                 for (int m = 0; m < 4; ++m) {
;                     const int rowa = 256 * pm + 128 * ai + 64 * wr + 16 * m + tt.rr;
;                     const float rs = rs8[ai][m];
;                     v4u pk[2];
; #pragma unroll
;                     for (int bj = 0; bj < 2; ++bj) {
;                         f32x4 r2[2];
; #pragma unroll
;                         for (int n = 0; n < 2; ++n) {
;                             const f32x4 z = acc[ai][bj][m][n] * rs + bg[bj][n];
; #pragma unroll
;                             for (int j = 0; j < 4; ++j) { const float az = fabsf(z[j]); r2[n][j] = (fminf(z[j], 0.f) - __logf(1.0f + fast_exp(-az))) * (1.0f / 16.0f); }
;                         }
;                         pk[bj] = pack8(r2[0], r2[1]);
;                     }
;                     v4u a, b; tt.bf(pk[0], pk[1], a, b);
;                     bf16* d = (bf16*)(ws + WS_LOGA) + (size_t)rowa * 256 + 64 * wc + 8 * tt.p; *(v4u*)d = a; *(v4u*)(d + 8 * 256) = b;
	v_fmac_f32_e32 v164, 0x3377d1cf, v157
	v_fmac_f32_e32 v164, 0x3f317217, v157
	v_cmp_lt_f32_e64 s[6:7], |v157|, s91
	s_nop 1
	v_cndmask_b32_e64 v157, v157, v164, s[6:7]
	v_cndmask_b32_e32 v164, 0, v222, vcc
	v_sub_f32_e32 v157, v157, v164
	v_pk_add_f32 v[154:155], v[154:155], v[156:157] neg_lo:[0,1] neg_hi:[0,1]
	v_fma_f32 v157, v98, v210, v130
	v_min_f32_e32 v156, 0, v157
	v_mul_f32_e64 v157, |v157|, s88
	v_exp_f32_e32 v157, v157
	v_pk_mul_f32 v[154:155], v[154:155], s[28:29] op_sel_hi:[1,0]
	v_add_f32_e32 v157, 1.0, v157
	v_cmp_gt_f32_e32 vcc, s89, v157
	v_cvt_pk_bf16_f32 v153, v154, v155
	s_nop 0
	v_cndmask_b32_e64 v164, 0, 32, vcc
	v_ldexp_f32 v157, v157, v164
	v_log_f32_e32 v157, v157
	s_nop 0
	v_mul_f32_e32 v164, 0x3f317217, v157
	v_fma_f32 v164, v157, s90, -v164
	v_fmac_f32_e32 v164, 0x3377d1cf, v157
	v_fmac_f32_e32 v164, 0x3f317217, v157
	v_cmp_lt_f32_e64 s[6:7], |v157|, s91
	s_nop 1
	v_cndmask_b32_e64 v157, v157, v164, s[6:7]
	v_cndmask_b32_e32 v164, 0, v222, vcc
	v_sub_f32_e32 v164, v157, v164
	v_min_f32_e32 v157, 0, v165
	v_mul_f32_e64 v165, |v165|, s88
	v_exp_f32_e32 v165, v165
	s_nop 0
	v_add_f32_e32 v165, 1.0, v165
	v_cmp_gt_f32_e32 vcc, s89, v165
	s_nop 1
	v_cndmask_b32_e64 v166, 0, 32, vcc
	v_ldexp_f32 v165, v165, v166
	v_log_f32_e32 v165, v165
	s_nop 0
	v_mul_f32_e32 v166, 0x3f317217, v165
	v_fma_f32 v166, v165, s90, -v166
	v_fmac_f32_e32 v166, 0x3377d1cf, v165
	v_fmac_f32_e32 v166, 0x3f317217, v165
	v_cmp_lt_f32_e64 s[6:7], |v165|, s91
	s_nop 1
	v_cndmask_b32_e64 v165, v165, v166, s[6:7]
	v_cndmask_b32_e32 v166, 0, v222, vcc
	v_sub_f32_e32 v165, v165, v166
	v_pk_add_f32 v[156:157], v[156:157], v[164:165] neg_lo:[0,1] neg_hi:[0,1]
	v_fma_f32 v165, v100, v210, v132
	v_min_f32_e32 v164, 0, v165
	v_mul_f32_e64 v165, |v165|, s88
	v_exp_f32_e32 v165, v165
	v_pk_mul_f32 v[156:157], v[156:157], s[28:29] op_sel_hi:[1,0]
	v_add_f32_e32 v165, 1.0, v165
	v_cmp_gt_f32_e32 vcc, s89, v165
	v_cvt_pk_bf16_f32 v154, v156, v157
	v_add_u32_e32 v156, 16, v150
	v_cndmask_b32_e64 v166, 0, 32, vcc
	v_ldexp_f32 v165, v165, v166
	v_log_f32_e32 v165, v165
	v_ashrrev_i32_e32 v157, 31, v156
	v_lshlrev_b64 v[156:157], 9, v[156:157]
	v_lshl_add_u64 v[156:157], s[24:25], 0, v[156:157]
	v_mul_f32_e32 v166, 0x3f317217, v165
	v_fma_f32 v166, v165, s90, -v166
	v_fmac_f32_e32 v166, 0x3377d1cf, v165
	v_fmac_f32_e32 v166, 0x3f317217, v165
	v_cmp_lt_f32_e64 s[6:7], |v165|, s91
	v_lshl_add_u64 v[156:157], v[156:157], 0, v[184:185]
	s_nop 0
	v_cndmask_b32_e64 v165, v165, v166, s[6:7]
	v_cndmask_b32_e32 v166, 0, v222, vcc
	v_sub_f32_e32 v166, v165, v166
	v_min_f32_e32 v165, 0, v167
	v_mul_f32_e64 v167, |v167|, s88
	v_exp_f32_e32 v167, v167
	s_nop 0
	v_add_f32_e32 v167, 1.0, v167
	v_cmp_gt_f32_e32 vcc, s89, v167
	s_nop 1
	v_cndmask_b32_e64 v168, 0, 32, vcc
	v_ldexp_f32 v167, v167, v168
	v_log_f32_e32 v167, v167
	s_nop 0
	v_mul_f32_e32 v168, 0x3f317217, v167
	v_fma_f32 v168, v167, s90, -v168
	v_fmac_f32_e32 v168, 0x3377d1cf, v167
	v_fmac_f32_e32 v168, 0x3f317217, v167
	v_cmp_lt_f32_e64 s[6:7], |v167|, s91
	s_nop 1
	v_cndmask_b32_e64 v167, v167, v168, s[6:7]
	v_cndmask_b32_e32 v168, 0, v222, vcc
	v_sub_f32_e32 v167, v167, v168
	v_pk_add_f32 v[164:165], v[164:165], v[166:167] neg_lo:[0,1] neg_hi:[0,1]
	v_fma_f32 v167, v85, v208, v133
	v_pk_mul_f32 v[164:165], v[164:165], s[28:29] op_sel_hi:[1,0]
	s_nop 0
	v_cvt_pk_bf16_f32 v155, v164, v165
	ds_write_b128 v160, v[146:149]
	ds_write_b128 v161, v[152:155]
	ds_read_b128 v[146:149], v163
	ds_read_b128 v[152:155], v163 offset:1024
	v_fma_f32 v165, v83, v208, v131
	s_waitcnt lgkmcnt(1)
	global_store_dwordx4 v[156:157], v[146:149], off sc1
	s_nop 1
	v_add_co_u32_e32 v146, vcc, s92, v156
	v_fma_f32 v149, v95, v208, v143
	s_nop 0
	v_addc_co_u32_e32 v147, vcc, 0, v157, vcc
	s_waitcnt lgkmcnt(0)
	global_store_dwordx4 v[146:147], v[152:155], off sc1
	v_fma_f32 v147, v94, v208, v142
	v_min_f32_e32 v146, 0, v147
	v_mul_f32_e64 v147, |v147|, s88
	v_exp_f32_e32 v147, v147
	v_fma_f32 v153, v97, v208, v145
	v_fma_f32 v155, v91, v208, v139
	v_fma_f32 v157, v93, v208, v141
	v_add_f32_e32 v147, 1.0, v147
	v_cmp_gt_f32_e32 vcc, s89, v147
	s_nop 1
	v_cndmask_b32_e64 v148, 0, 32, vcc
	v_ldexp_f32 v147, v147, v148
	v_log_f32_e32 v147, v147
	s_nop 0
	v_mul_f32_e32 v148, 0x3f317217, v147
	v_fma_f32 v148, v147, s90, -v148
	v_fmac_f32_e32 v148, 0x3377d1cf, v147
	v_fmac_f32_e32 v148, 0x3f317217, v147
	v_cmp_lt_f32_e64 s[6:7], |v147|, s91
	s_nop 1
	v_cndmask_b32_e64 v147, v147, v148, s[6:7]
	v_cndmask_b32_e32 v148, 0, v222, vcc
	v_sub_f32_e32 v148, v147, v148
	v_min_f32_e32 v147, 0, v149
	v_mul_f32_e64 v149, |v149|, s88
	v_exp_f32_e32 v149, v149
	s_nop 0
	v_add_f32_e32 v149, 1.0, v149
	v_cmp_gt_f32_e32 vcc, s89, v149
	s_nop 1
	v_cndmask_b32_e64 v152, 0, 32, vcc
	v_ldexp_f32 v149, v149, v152
	v_log_f32_e32 v149, v149
	s_nop 0
	v_mul_f32_e32 v152, 0x3f317217, v149
	v_fma_f32 v152, v149, s90, -v152
	v_fmac_f32_e32 v152, 0x3377d1cf, v149
	v_fmac_f32_e32 v152, 0x3f317217, v149
	v_cmp_lt_f32_e64 s[6:7], |v149|, s91
	s_nop 1
	v_cndmask_b32_e64 v149, v149, v152, s[6:7]
	v_cndmask_b32_e32 v152, 0, v222, vcc
	v_sub_f32_e32 v149, v149, v152
	v_pk_add_f32 v[146:147], v[146:147], v[148:149] neg_lo:[0,1] neg_hi:[0,1]
	v_fma_f32 v149, v96, v208, v144
	v_min_f32_e32 v148, 0, v149
	v_mul_f32_e64 v149, |v149|, s88
	v_exp_f32_e32 v149, v149
	v_pk_mul_f32 v[146:147], v[146:147], s[28:29] op_sel_hi:[1,0]
	v_add_f32_e32 v149, 1.0, v149
	v_cmp_gt_f32_e32 vcc, s89, v149
	v_cvt_pk_bf16_f32 v146, v146, v147
	s_nop 0
	v_cndmask_b32_e64 v152, 0, 32, vcc
	v_ldexp_f32 v149, v149, v152
	v_log_f32_e32 v149, v149
	s_nop 0
	v_mul_f32_e32 v152, 0x3f317217, v149
; __device__ __forceinline__ v4u pack8(const f32x4 a, const f32x4 b) { v4u w; w.x = pk2(a[0], a[1]); w.y = pk2(a[2], a[3]); w.z = pk2(b[0], b[1]); w.w = pk2(b[2], b[3]); return w; }
; __device__ __forceinline__ float fast_exp(float x) { return __builtin_amdgcn_exp2f(x * LOG2E); }
;     __device__ __forceinline__ void operator()(const f32x4 (&acc)[2][2][4][2], const pg8::Unit& u, int wr, int wc, int fr, int fq) const {
;     ...
;             for (int ai = 0; ai < 2; ++ai)
; #pragma unroll
;                 for (int m = 0; m < 4; ++m) {
;                     const int rowa = 256 * pm + 128 * ai + 64 * wr + 16 * m + tt.rr;
;                     const float rs = rs8[ai][m];
;                     v4u pk[2];
; #pragma unroll
;                     for (int bj = 0; bj < 2; ++bj) {
;                         f32x4 r2[2];
; #pragma unroll
;                         for (int n = 0; n < 2; ++n) {
;                             const f32x4 z = acc[ai][bj][m][n] * rs + bg[bj][n];
; #pragma unroll
;                             for (int j = 0; j < 4; ++j) { const float az = fabsf(z[j]); r2[n][j] = (fminf(z[j], 0.f) - __logf(1.0f + fast_exp(-az))) * (1.0f / 16.0f); }
;                         }
;                         pk[bj] = pack8(r2[0], r2[1]);
;                     }
;                     v4u a, b; tt.bf(pk[0], pk[1], a, b);
;                     bf16* d = (bf16*)(ws + WS_LOGA) + (size_t)rowa * 256 + 64 * wc + 8 * tt.p; *(v4u*)d = a; *(v4u*)(d + 8 * 256) = b;
	v_fma_f32 v152, v149, s90, -v152
	v_fmac_f32_e32 v152, 0x3377d1cf, v149
	v_fmac_f32_e32 v152, 0x3f317217, v149
	v_cmp_lt_f32_e64 s[6:7], |v149|, s91
	s_nop 1
	v_cndmask_b32_e64 v149, v149, v152, s[6:7]
	v_cndmask_b32_e32 v152, 0, v222, vcc
	v_sub_f32_e32 v152, v149, v152
	v_min_f32_e32 v149, 0, v153
	v_mul_f32_e64 v153, |v153|, s88
	v_exp_f32_e32 v153, v153
	s_nop 0
	v_add_f32_e32 v153, 1.0, v153
	v_cmp_gt_f32_e32 vcc, s89, v153
	s_nop 1
	v_cndmask_b32_e64 v154, 0, 32, vcc
	v_ldexp_f32 v153, v153, v154
	v_log_f32_e32 v153, v153
	s_nop 0
	v_mul_f32_e32 v154, 0x3f317217, v153
	v_fma_f32 v154, v153, s90, -v154
	v_fmac_f32_e32 v154, 0x3377d1cf, v153
	v_fmac_f32_e32 v154, 0x3f317217, v153
	v_cmp_lt_f32_e64 s[6:7], |v153|, s91
	s_nop 1
	v_cndmask_b32_e64 v153, v153, v154, s[6:7]
	v_cndmask_b32_e32 v154, 0, v222, vcc
	v_sub_f32_e32 v153, v153, v154
	v_pk_add_f32 v[148:149], v[148:149], v[152:153] neg_lo:[0,1] neg_hi:[0,1]
	v_fma_f32 v153, v90, v208, v138
	v_min_f32_e32 v152, 0, v153
	v_mul_f32_e64 v153, |v153|, s88
	v_exp_f32_e32 v153, v153
	v_pk_mul_f32 v[148:149], v[148:149], s[28:29] op_sel_hi:[1,0]
	v_add_f32_e32 v153, 1.0, v153
	v_cmp_gt_f32_e32 vcc, s89, v153
	v_cvt_pk_bf16_f32 v147, v148, v149
	s_nop 0
	v_cndmask_b32_e64 v154, 0, 32, vcc
	v_ldexp_f32 v153, v153, v154
	v_log_f32_e32 v153, v153
	s_nop 0
	v_mul_f32_e32 v154, 0x3f317217, v153
	v_fma_f32 v154, v153, s90, -v154
	v_fmac_f32_e32 v154, 0x3377d1cf, v153
	v_fmac_f32_e32 v154, 0x3f317217, v153
	v_cmp_lt_f32_e64 s[6:7], |v153|, s91
	s_nop 1
	v_cndmask_b32_e64 v153, v153, v154, s[6:7]
	v_cndmask_b32_e32 v154, 0, v222, vcc
	v_sub_f32_e32 v154, v153, v154
	v_min_f32_e32 v153, 0, v155
	v_mul_f32_e64 v155, |v155|, s88
	v_exp_f32_e32 v155, v155
	s_nop 0
	v_add_f32_e32 v155, 1.0, v155
	v_cmp_gt_f32_e32 vcc, s89, v155
	s_nop 1
	v_cndmask_b32_e64 v156, 0, 32, vcc
	v_ldexp_f32 v155, v155, v156
	v_log_f32_e32 v155, v155
	s_nop 0
	v_mul_f32_e32 v156, 0x3f317217, v155
	v_fma_f32 v156, v155, s90, -v156
	v_fmac_f32_e32 v156, 0x3377d1cf, v155
	v_fmac_f32_e32 v156, 0x3f317217, v155
	v_cmp_lt_f32_e64 s[6:7], |v155|, s91
	s_nop 1
	v_cndmask_b32_e64 v155, v155, v156, s[6:7]
	v_cndmask_b32_e32 v156, 0, v222, vcc
	v_sub_f32_e32 v155, v155, v156
	v_pk_add_f32 v[152:153], v[152:153], v[154:155] neg_lo:[0,1] neg_hi:[0,1]
	v_fma_f32 v155, v92, v208, v140
	v_min_f32_e32 v154, 0, v155
	v_mul_f32_e64 v155, |v155|, s88
	v_exp_f32_e32 v155, v155
	v_pk_mul_f32 v[152:153], v[152:153], s[28:29] op_sel_hi:[1,0]
	v_add_f32_e32 v155, 1.0, v155
	v_cmp_gt_f32_e32 vcc, s89, v155
	v_cvt_pk_bf16_f32 v148, v152, v153
	v_fma_f32 v153, v86, v208, v134
	v_cndmask_b32_e64 v156, 0, 32, vcc
	v_ldexp_f32 v155, v155, v156
	v_log_f32_e32 v155, v155
	v_min_f32_e32 v152, 0, v153
	v_mul_f32_e64 v153, |v153|, s88
	v_exp_f32_e32 v153, v153
	v_mul_f32_e32 v156, 0x3f317217, v155
	v_fma_f32 v156, v155, s90, -v156
	v_fmac_f32_e32 v156, 0x3377d1cf, v155
	v_fmac_f32_e32 v156, 0x3f317217, v155
	v_cmp_lt_f32_e64 s[6:7], |v155|, s91
	v_add_f32_e32 v153, 1.0, v153
	s_nop 0
	v_cndmask_b32_e64 v155, v155, v156, s[6:7]
	v_cndmask_b32_e32 v156, 0, v222, vcc
	v_sub_f32_e32 v156, v155, v156
	v_min_f32_e32 v155, 0, v157
	v_mul_f32_e64 v157, |v157|, s88
	v_exp_f32_e32 v157, v157
	s_nop 0
	v_add_f32_e32 v157, 1.0, v157
	v_cmp_gt_f32_e32 vcc, s89, v157
	s_nop 1
	v_cndmask_b32_e64 v164, 0, 32, vcc
	v_ldexp_f32 v157, v157, v164
	v_log_f32_e32 v157, v157
	s_nop 0
	v_mul_f32_e32 v164, 0x3f317217, v157
	v_fma_f32 v164, v157, s90, -v164
	v_fmac_f32_e32 v164, 0x3377d1cf, v157
	v_fmac_f32_e32 v164, 0x3f317217, v157
	v_cmp_lt_f32_e64 s[6:7], |v157|, s91
	s_nop 1
	v_cndmask_b32_e64 v157, v157, v164, s[6:7]
	v_cndmask_b32_e32 v164, 0, v222, vcc
	v_sub_f32_e32 v157, v157, v164
	v_pk_add_f32 v[154:155], v[154:155], v[156:157] neg_lo:[0,1] neg_hi:[0,1]
	v_cmp_gt_f32_e32 vcc, s89, v153
	v_pk_mul_f32 v[154:155], v[154:155], s[28:29] op_sel_hi:[1,0]
	v_fma_f32 v157, v89, v208, v137
	v_cvt_pk_bf16_f32 v149, v154, v155
	v_cndmask_b32_e64 v154, 0, 32, vcc
	v_ldexp_f32 v153, v153, v154
	v_log_f32_e32 v153, v153
	v_fma_f32 v155, v87, v208, v135
	v_mul_f32_e32 v154, 0x3f317217, v153
	v_fma_f32 v154, v153, s90, -v154
	v_fmac_f32_e32 v154, 0x3377d1cf, v153
	v_fmac_f32_e32 v154, 0x3f317217, v153
	v_cmp_lt_f32_e64 s[6:7], |v153|, s91
	s_nop 1
	v_cndmask_b32_e64 v153, v153, v154, s[6:7]
	v_cndmask_b32_e32 v154, 0, v222, vcc
	v_sub_f32_e32 v154, v153, v154
	v_min_f32_e32 v153, 0, v155
	v_mul_f32_e64 v155, |v155|, s88
	v_exp_f32_e32 v155, v155
	s_nop 0
	v_add_f32_e32 v155, 1.0, v155
	v_cmp_gt_f32_e32 vcc, s89, v155
	s_nop 1
	v_cndmask_b32_e64 v156, 0, 32, vcc
	v_ldexp_f32 v155, v155, v156
	v_log_f32_e32 v155, v155
	s_nop 0
	v_mul_f32_e32 v156, 0x3f317217, v155
	v_fma_f32 v156, v155, s90, -v156
	v_fmac_f32_e32 v156, 0x3377d1cf, v155
	v_fmac_f32_e32 v156, 0x3f317217, v155
	v_cmp_lt_f32_e64 s[6:7], |v155|, s91
	s_nop 1
	v_cndmask_b32_e64 v155, v155, v156, s[6:7]
	v_cndmask_b32_e32 v156, 0, v222, vcc
	v_sub_f32_e32 v155, v155, v156
	v_pk_add_f32 v[152:153], v[152:153], v[154:155] neg_lo:[0,1] neg_hi:[0,1]
	v_fma_f32 v155, v88, v208, v136
	v_min_f32_e32 v154, 0, v155
	v_mul_f32_e64 v155, |v155|, s88
	v_exp_f32_e32 v155, v155
	v_pk_mul_f32 v[152:153], v[152:153], s[28:29] op_sel_hi:[1,0]
	v_add_f32_e32 v155, 1.0, v155
	v_cmp_gt_f32_e32 vcc, s89, v155
	v_cvt_pk_bf16_f32 v152, v152, v153
	s_nop 0
	v_cndmask_b32_e64 v156, 0, 32, vcc
	v_ldexp_f32 v155, v155, v156
	v_log_f32_e32 v155, v155
	s_nop 0
	v_mul_f32_e32 v156, 0x3f317217, v155
	v_fma_f32 v156, v155, s90, -v156
	v_fmac_f32_e32 v156, 0x3377d1cf, v155
	v_fmac_f32_e32 v156, 0x3f317217, v155
	v_cmp_lt_f32_e64 s[6:7], |v155|, s91
	s_nop 1
; __device__ __forceinline__ v4u pack8(const f32x4 a, const f32x4 b) { v4u w; w.x = pk2(a[0], a[1]); w.y = pk2(a[2], a[3]); w.z = pk2(b[0], b[1]); w.w = pk2(b[2], b[3]); return w; }
; __device__ __forceinline__ float fast_exp(float x) { return __builtin_amdgcn_exp2f(x * LOG2E); }
;     __device__ __forceinline__ void operator()(const f32x4 (&acc)[2][2][4][2], const pg8::Unit& u, int wr, int wc, int fr, int fq) const {
;     ...
;             for (int ai = 0; ai < 2; ++ai)
; #pragma unroll
;                 for (int m = 0; m < 4; ++m) {
;                     const int rowa = 256 * pm + 128 * ai + 64 * wr + 16 * m + tt.rr;
;                     const float rs = rs8[ai][m];
;                     v4u pk[2];
; #pragma unroll
;                     for (int bj = 0; bj < 2; ++bj) {
;                         f32x4 r2[2];
; #pragma unroll
;                         for (int n = 0; n < 2; ++n) {
;                             const f32x4 z = acc[ai][bj][m][n] * rs + bg[bj][n];
; #pragma unroll
;                             for (int j = 0; j < 4; ++j) { const float az = fabsf(z[j]); r2[n][j] = (fminf(z[j], 0.f) - __logf(1.0f + fast_exp(-az))) * (1.0f / 16.0f); }
;                         }
;                         pk[bj] = pack8(r2[0], r2[1]);
;                     }
;                     v4u a, b; tt.bf(pk[0], pk[1], a, b);
;                     bf16* d = (bf16*)(ws + WS_LOGA) + (size_t)rowa * 256 + 64 * wc + 8 * tt.p; *(v4u*)d = a; *(v4u*)(d + 8 * 256) = b;
	v_cndmask_b32_e64 v155, v155, v156, s[6:7]
	v_cndmask_b32_e32 v156, 0, v222, vcc
	v_sub_f32_e32 v156, v155, v156
	v_min_f32_e32 v155, 0, v157
	v_mul_f32_e64 v157, |v157|, s88
	v_exp_f32_e32 v157, v157
	s_nop 0
	v_add_f32_e32 v157, 1.0, v157
	v_cmp_gt_f32_e32 vcc, s89, v157
	s_nop 1
	v_cndmask_b32_e64 v164, 0, 32, vcc
	v_ldexp_f32 v157, v157, v164
	v_log_f32_e32 v157, v157
	s_nop 0
	v_mul_f32_e32 v164, 0x3f317217, v157
	v_fma_f32 v164, v157, s90, -v164
	v_fmac_f32_e32 v164, 0x3377d1cf, v157
	v_fmac_f32_e32 v164, 0x3f317217, v157
	v_cmp_lt_f32_e64 s[6:7], |v157|, s91
	s_nop 1
	v_cndmask_b32_e64 v157, v157, v164, s[6:7]
	v_cndmask_b32_e32 v164, 0, v222, vcc
	v_sub_f32_e32 v157, v157, v164
	v_pk_add_f32 v[154:155], v[154:155], v[156:157] neg_lo:[0,1] neg_hi:[0,1]
	v_fma_f32 v157, v82, v208, v130
	v_min_f32_e32 v156, 0, v157
	v_mul_f32_e64 v157, |v157|, s88
	v_exp_f32_e32 v157, v157
	v_pk_mul_f32 v[154:155], v[154:155], s[28:29] op_sel_hi:[1,0]
	v_add_f32_e32 v157, 1.0, v157
	v_cmp_gt_f32_e32 vcc, s89, v157
	v_cvt_pk_bf16_f32 v153, v154, v155
	s_nop 0
	v_cndmask_b32_e64 v164, 0, 32, vcc
	v_ldexp_f32 v157, v157, v164
	v_log_f32_e32 v157, v157
	s_nop 0
	v_mul_f32_e32 v164, 0x3f317217, v157
	v_fma_f32 v164, v157, s90, -v164
	v_fmac_f32_e32 v164, 0x3377d1cf, v157
	v_fmac_f32_e32 v164, 0x3f317217, v157
	v_cmp_lt_f32_e64 s[6:7], |v157|, s91
	s_nop 1
	v_cndmask_b32_e64 v157, v157, v164, s[6:7]
	v_cndmask_b32_e32 v164, 0, v222, vcc
	v_sub_f32_e32 v164, v157, v164
	v_min_f32_e32 v157, 0, v165
	v_mul_f32_e64 v165, |v165|, s88
	v_exp_f32_e32 v165, v165
	s_nop 0
	v_add_f32_e32 v165, 1.0, v165
	v_cmp_gt_f32_e32 vcc, s89, v165
	s_nop 1
	v_cndmask_b32_e64 v166, 0, 32, vcc
	v_ldexp_f32 v165, v165, v166
	v_log_f32_e32 v165, v165
	s_nop 0
	v_mul_f32_e32 v166, 0x3f317217, v165
	v_fma_f32 v166, v165, s90, -v166
	v_fmac_f32_e32 v166, 0x3377d1cf, v165
	v_fmac_f32_e32 v166, 0x3f317217, v165
	v_cmp_lt_f32_e64 s[6:7], |v165|, s91
	s_nop 1
	v_cndmask_b32_e64 v165, v165, v166, s[6:7]
	v_cndmask_b32_e32 v166, 0, v222, vcc
	v_sub_f32_e32 v165, v165, v166
	v_pk_add_f32 v[156:157], v[156:157], v[164:165] neg_lo:[0,1] neg_hi:[0,1]
	v_fma_f32 v165, v84, v208, v132
	v_min_f32_e32 v164, 0, v165
	v_mul_f32_e64 v165, |v165|, s88
	v_exp_f32_e32 v165, v165
	v_pk_mul_f32 v[156:157], v[156:157], s[28:29] op_sel_hi:[1,0]
	v_add_f32_e32 v165, 1.0, v165
	v_cmp_gt_f32_e32 vcc, s89, v165
	v_cvt_pk_bf16_f32 v154, v156, v157
	v_add_u32_e32 v156, 32, v150
	v_cndmask_b32_e64 v166, 0, 32, vcc
	v_ldexp_f32 v165, v165, v166
	v_log_f32_e32 v165, v165
	v_ashrrev_i32_e32 v157, 31, v156
	v_lshlrev_b64 v[156:157], 9, v[156:157]
	v_lshl_add_u64 v[156:157], s[24:25], 0, v[156:157]
	v_mul_f32_e32 v166, 0x3f317217, v165
	v_fma_f32 v166, v165, s90, -v166
	v_fmac_f32_e32 v166, 0x3377d1cf, v165
	v_fmac_f32_e32 v166, 0x3f317217, v165
	v_cmp_lt_f32_e64 s[6:7], |v165|, s91
	v_lshl_add_u64 v[156:157], v[156:157], 0, v[184:185]
	s_nop 0
	v_cndmask_b32_e64 v165, v165, v166, s[6:7]
	v_cndmask_b32_e32 v166, 0, v222, vcc
	v_sub_f32_e32 v166, v165, v166
	v_min_f32_e32 v165, 0, v167
	v_mul_f32_e64 v167, |v167|, s88
	v_exp_f32_e32 v167, v167
	s_nop 0
	v_add_f32_e32 v167, 1.0, v167
	v_cmp_gt_f32_e32 vcc, s89, v167
	s_nop 1
	v_cndmask_b32_e64 v168, 0, 32, vcc
	v_ldexp_f32 v167, v167, v168
	v_log_f32_e32 v167, v167
	s_nop 0
	v_mul_f32_e32 v168, 0x3f317217, v167
	v_fma_f32 v168, v167, s90, -v168
	v_fmac_f32_e32 v168, 0x3377d1cf, v167
	v_fmac_f32_e32 v168, 0x3f317217, v167
	v_cmp_lt_f32_e64 s[6:7], |v167|, s91
	s_nop 1
	v_cndmask_b32_e64 v167, v167, v168, s[6:7]
	v_cndmask_b32_e32 v168, 0, v222, vcc
	v_sub_f32_e32 v167, v167, v168
	v_pk_add_f32 v[164:165], v[164:165], v[166:167] neg_lo:[0,1] neg_hi:[0,1]
	v_fma_f32 v167, v69, v206, v133
	v_pk_mul_f32 v[164:165], v[164:165], s[28:29] op_sel_hi:[1,0]
	s_nop 0
	v_cvt_pk_bf16_f32 v155, v164, v165
	ds_write_b128 v160, v[146:149]
	ds_write_b128 v161, v[152:155]
	ds_read_b128 v[146:149], v163
	ds_read_b128 v[152:155], v163 offset:1024
	v_fma_f32 v165, v67, v206, v131
	s_waitcnt lgkmcnt(1)
	global_store_dwordx4 v[156:157], v[146:149], off sc1
	s_nop 1
	v_add_co_u32_e32 v146, vcc, s92, v156
	v_fma_f32 v149, v79, v206, v143
	s_nop 0
	v_addc_co_u32_e32 v147, vcc, 0, v157, vcc
	s_waitcnt lgkmcnt(0)
; __device__ __forceinline__ v4u pack8(const f32x4 a, const f32x4 b) { v4u w; w.x = pk2(a[0], a[1]); w.y = pk2(a[2], a[3]); w.z = pk2(b[0], b[1]); w.w = pk2(b[2], b[3]); return w; }
; __device__ __forceinline__ float fast_exp(float x) { return __builtin_amdgcn_exp2f(x * LOG2E); }
;     __device__ __forceinline__ void operator()(const f32x4 (&acc)[2][2][4][2], const pg8::Unit& u, int wr, int wc, int fr, int fq) const {
;     ...
;             for (int ai = 0; ai < 2; ++ai)
; #pragma unroll
;                 for (int m = 0; m < 4; ++m) {
;                     const int rowa = 256 * pm + 128 * ai + 64 * wr + 16 * m + tt.rr;
;                     const float rs = rs8[ai][m];
;                     v4u pk[2];
; #pragma unroll
;                     for (int bj = 0; bj < 2; ++bj) {
;                         f32x4 r2[2];
; #pragma unroll
;                         for (int n = 0; n < 2; ++n) {
;                             const f32x4 z = acc[ai][bj][m][n] * rs + bg[bj][n];
; #pragma unroll
;                             for (int j = 0; j < 4; ++j) { const float az = fabsf(z[j]); r2[n][j] = (fminf(z[j], 0.f) - __logf(1.0f + fast_exp(-az))) * (1.0f / 16.0f); }
;                         }
;                         pk[bj] = pack8(r2[0], r2[1]);
;                     }
;                     v4u a, b; tt.bf(pk[0], pk[1], a, b);
;                     bf16* d = (bf16*)(ws + WS_LOGA) + (size_t)rowa * 256 + 64 * wc + 8 * tt.p; *(v4u*)d = a; *(v4u*)(d + 8 * 256) = b;
	global_store_dwordx4 v[146:147], v[152:155], off sc1
	v_fma_f32 v147, v78, v206, v142
	v_min_f32_e32 v146, 0, v147
	v_mul_f32_e64 v147, |v147|, s88
	v_exp_f32_e32 v147, v147
	v_fma_f32 v153, v81, v206, v145
	v_fma_f32 v155, v75, v206, v139
	v_fma_f32 v157, v77, v206, v141
	v_add_f32_e32 v147, 1.0, v147
	v_cmp_gt_f32_e32 vcc, s89, v147
	s_nop 1
	v_cndmask_b32_e64 v148, 0, 32, vcc
	v_ldexp_f32 v147, v147, v148
	v_log_f32_e32 v147, v147
	s_nop 0
	v_mul_f32_e32 v148, 0x3f317217, v147
	v_fma_f32 v148, v147, s90, -v148
	v_fmac_f32_e32 v148, 0x3377d1cf, v147
	v_fmac_f32_e32 v148, 0x3f317217, v147
	v_cmp_lt_f32_e64 s[6:7], |v147|, s91
	s_nop 1
	v_cndmask_b32_e64 v147, v147, v148, s[6:7]
	v_cndmask_b32_e32 v148, 0, v222, vcc
	v_sub_f32_e32 v148, v147, v148
	v_min_f32_e32 v147, 0, v149
	v_mul_f32_e64 v149, |v149|, s88
	v_exp_f32_e32 v149, v149
	s_nop 0
	v_add_f32_e32 v149, 1.0, v149
	v_cmp_gt_f32_e32 vcc, s89, v149
	s_nop 1
	v_cndmask_b32_e64 v152, 0, 32, vcc
	v_ldexp_f32 v149, v149, v152
	v_log_f32_e32 v149, v149
	s_nop 0
	v_mul_f32_e32 v152, 0x3f317217, v149
	v_fma_f32 v152, v149, s90, -v152
	v_fmac_f32_e32 v152, 0x3377d1cf, v149
	v_fmac_f32_e32 v152, 0x3f317217, v149
	v_cmp_lt_f32_e64 s[6:7], |v149|, s91
	s_nop 1
	v_cndmask_b32_e64 v149, v149, v152, s[6:7]
	v_cndmask_b32_e32 v152, 0, v222, vcc
	v_sub_f32_e32 v149, v149, v152
	v_pk_add_f32 v[146:147], v[146:147], v[148:149] neg_lo:[0,1] neg_hi:[0,1]
	v_fma_f32 v149, v80, v206, v144
	v_min_f32_e32 v148, 0, v149
	v_mul_f32_e64 v149, |v149|, s88
	v_exp_f32_e32 v149, v149
	v_pk_mul_f32 v[146:147], v[146:147], s[28:29] op_sel_hi:[1,0]
	v_add_f32_e32 v149, 1.0, v149
	v_cmp_gt_f32_e32 vcc, s89, v149
	v_cvt_pk_bf16_f32 v146, v146, v147
	s_nop 0
	v_cndmask_b32_e64 v152, 0, 32, vcc
	v_ldexp_f32 v149, v149, v152
	v_log_f32_e32 v149, v149
	s_nop 0
	v_mul_f32_e32 v152, 0x3f317217, v149
	v_fma_f32 v152, v149, s90, -v152
	v_fmac_f32_e32 v152, 0x3377d1cf, v149
	v_fmac_f32_e32 v152, 0x3f317217, v149
	v_cmp_lt_f32_e64 s[6:7], |v149|, s91
	s_nop 1
	v_cndmask_b32_e64 v149, v149, v152, s[6:7]
	v_cndmask_b32_e32 v152, 0, v222, vcc
	v_sub_f32_e32 v152, v149, v152
	v_min_f32_e32 v149, 0, v153
	v_mul_f32_e64 v153, |v153|, s88
	v_exp_f32_e32 v153, v153
	s_nop 0
	v_add_f32_e32 v153, 1.0, v153
	v_cmp_gt_f32_e32 vcc, s89, v153
	s_nop 1
	v_cndmask_b32_e64 v154, 0, 32, vcc
	v_ldexp_f32 v153, v153, v154
	v_log_f32_e32 v153, v153
	s_nop 0
	v_mul_f32_e32 v154, 0x3f317217, v153
	v_fma_f32 v154, v153, s90, -v154
	v_fmac_f32_e32 v154, 0x3377d1cf, v153
	v_fmac_f32_e32 v154, 0x3f317217, v153
	v_cmp_lt_f32_e64 s[6:7], |v153|, s91
	s_nop 1
	v_cndmask_b32_e64 v153, v153, v154, s[6:7]
	v_cndmask_b32_e32 v154, 0, v222, vcc
	v_sub_f32_e32 v153, v153, v154
	v_pk_add_f32 v[148:149], v[148:149], v[152:153] neg_lo:[0,1] neg_hi:[0,1]
	v_fma_f32 v153, v74, v206, v138
	v_min_f32_e32 v152, 0, v153
	v_mul_f32_e64 v153, |v153|, s88
	v_exp_f32_e32 v153, v153
	v_pk_mul_f32 v[148:149], v[148:149], s[28:29] op_sel_hi:[1,0]
	v_add_f32_e32 v153, 1.0, v153
	v_cmp_gt_f32_e32 vcc, s89, v153
	v_cvt_pk_bf16_f32 v147, v148, v149
	s_nop 0
	v_cndmask_b32_e64 v154, 0, 32, vcc
	v_ldexp_f32 v153, v153, v154
	v_log_f32_e32 v153, v153
	s_nop 0
	v_mul_f32_e32 v154, 0x3f317217, v153
	v_fma_f32 v154, v153, s90, -v154
	v_fmac_f32_e32 v154, 0x3377d1cf, v153
	v_fmac_f32_e32 v154, 0x3f317217, v153
	v_cmp_lt_f32_e64 s[6:7], |v153|, s91
	s_nop 1
	v_cndmask_b32_e64 v153, v153, v154, s[6:7]
	v_cndmask_b32_e32 v154, 0, v222, vcc
	v_sub_f32_e32 v154, v153, v154
	v_min_f32_e32 v153, 0, v155
	v_mul_f32_e64 v155, |v155|, s88
	v_exp_f32_e32 v155, v155
	s_nop 0
	v_add_f32_e32 v155, 1.0, v155
	v_cmp_gt_f32_e32 vcc, s89, v155
	s_nop 1
	v_cndmask_b32_e64 v156, 0, 32, vcc
	v_ldexp_f32 v155, v155, v156
	v_log_f32_e32 v155, v155
	s_nop 0
	v_mul_f32_e32 v156, 0x3f317217, v155
	v_fma_f32 v156, v155, s90, -v156
	v_fmac_f32_e32 v156, 0x3377d1cf, v155
	v_fmac_f32_e32 v156, 0x3f317217, v155
	v_cmp_lt_f32_e64 s[6:7], |v155|, s91
	s_nop 1
	v_cndmask_b32_e64 v155, v155, v156, s[6:7]
	v_cndmask_b32_e32 v156, 0, v222, vcc
	v_sub_f32_e32 v155, v155, v156
	v_pk_add_f32 v[152:153], v[152:153], v[154:155] neg_lo:[0,1] neg_hi:[0,1]
	v_fma_f32 v155, v76, v206, v140
	v_min_f32_e32 v154, 0, v155
	v_mul_f32_e64 v155, |v155|, s88
	v_exp_f32_e32 v155, v155
	v_pk_mul_f32 v[152:153], v[152:153], s[28:29] op_sel_hi:[1,0]
	v_add_f32_e32 v155, 1.0, v155
	v_cmp_gt_f32_e32 vcc, s89, v155
	v_cvt_pk_bf16_f32 v148, v152, v153
	v_fma_f32 v153, v70, v206, v134
	v_cndmask_b32_e64 v156, 0, 32, vcc
	v_ldexp_f32 v155, v155, v156
	v_log_f32_e32 v155, v155
	v_min_f32_e32 v152, 0, v153
	v_mul_f32_e64 v153, |v153|, s88
	v_exp_f32_e32 v153, v153
	v_mul_f32_e32 v156, 0x3f317217, v155
	v_fma_f32 v156, v155, s90, -v156
	v_fmac_f32_e32 v156, 0x3377d1cf, v155
	v_fmac_f32_e32 v156, 0x3f317217, v155
	v_cmp_lt_f32_e64 s[6:7], |v155|, s91
	v_add_f32_e32 v153, 1.0, v153
	s_nop 0
	v_cndmask_b32_e64 v155, v155, v156, s[6:7]
	v_cndmask_b32_e32 v156, 0, v222, vcc
	v_sub_f32_e32 v156, v155, v156
	v_min_f32_e32 v155, 0, v157
	v_mul_f32_e64 v157, |v157|, s88
	v_exp_f32_e32 v157, v157
	s_nop 0
	v_add_f32_e32 v157, 1.0, v157
	v_cmp_gt_f32_e32 vcc, s89, v157
	s_nop 1
	v_cndmask_b32_e64 v164, 0, 32, vcc
	v_ldexp_f32 v157, v157, v164
	v_log_f32_e32 v157, v157
	s_nop 0
	v_mul_f32_e32 v164, 0x3f317217, v157
	v_fma_f32 v164, v157, s90, -v164
	v_fmac_f32_e32 v164, 0x3377d1cf, v157
	v_fmac_f32_e32 v164, 0x3f317217, v157
	v_cmp_lt_f32_e64 s[6:7], |v157|, s91
	s_nop 1
	v_cndmask_b32_e64 v157, v157, v164, s[6:7]
	v_cndmask_b32_e32 v164, 0, v222, vcc
	v_sub_f32_e32 v157, v157, v164
	v_pk_add_f32 v[154:155], v[154:155], v[156:157] neg_lo:[0,1] neg_hi:[0,1]
; __device__ __forceinline__ v4u pack8(const f32x4 a, const f32x4 b) { v4u w; w.x = pk2(a[0], a[1]); w.y = pk2(a[2], a[3]); w.z = pk2(b[0], b[1]); w.w = pk2(b[2], b[3]); return w; }
; __device__ __forceinline__ float fast_exp(float x) { return __builtin_amdgcn_exp2f(x * LOG2E); }
;     __device__ __forceinline__ void operator()(const f32x4 (&acc)[2][2][4][2], const pg8::Unit& u, int wr, int wc, int fr, int fq) const {
;     ...
;             for (int ai = 0; ai < 2; ++ai)
; #pragma unroll
;                 for (int m = 0; m < 4; ++m) {
;                     const int rowa = 256 * pm + 128 * ai + 64 * wr + 16 * m + tt.rr;
;                     const float rs = rs8[ai][m];
;                     v4u pk[2];
; #pragma unroll
;                     for (int bj = 0; bj < 2; ++bj) {
;                         f32x4 r2[2];
; #pragma unroll
;                         for (int n = 0; n < 2; ++n) {
;                             const f32x4 z = acc[ai][bj][m][n] * rs + bg[bj][n];
; #pragma unroll
;                             for (int j = 0; j < 4; ++j) { const float az = fabsf(z[j]); r2[n][j] = (fminf(z[j], 0.f) - __logf(1.0f + fast_exp(-az))) * (1.0f / 16.0f); }
;                         }
;                         pk[bj] = pack8(r2[0], r2[1]);
;                     }
;                     v4u a, b; tt.bf(pk[0], pk[1], a, b);
;                     bf16* d = (bf16*)(ws + WS_LOGA) + (size_t)rowa * 256 + 64 * wc + 8 * tt.p; *(v4u*)d = a; *(v4u*)(d + 8 * 256) = b;
	v_cmp_gt_f32_e32 vcc, s89, v153
	v_pk_mul_f32 v[154:155], v[154:155], s[28:29] op_sel_hi:[1,0]
	v_fma_f32 v157, v73, v206, v137
	v_cvt_pk_bf16_f32 v149, v154, v155
	v_cndmask_b32_e64 v154, 0, 32, vcc
	v_ldexp_f32 v153, v153, v154
	v_log_f32_e32 v153, v153
	v_fma_f32 v155, v71, v206, v135
	v_mul_f32_e32 v154, 0x3f317217, v153
	v_fma_f32 v154, v153, s90, -v154
	v_fmac_f32_e32 v154, 0x3377d1cf, v153
	v_fmac_f32_e32 v154, 0x3f317217, v153
	v_cmp_lt_f32_e64 s[6:7], |v153|, s91
	s_nop 1
	v_cndmask_b32_e64 v153, v153, v154, s[6:7]
	v_cndmask_b32_e32 v154, 0, v222, vcc
	v_sub_f32_e32 v154, v153, v154
	v_min_f32_e32 v153, 0, v155
	v_mul_f32_e64 v155, |v155|, s88
	v_exp_f32_e32 v155, v155
	s_nop 0
	v_add_f32_e32 v155, 1.0, v155
	v_cmp_gt_f32_e32 vcc, s89, v155
	s_nop 1
	v_cndmask_b32_e64 v156, 0, 32, vcc
	v_ldexp_f32 v155, v155, v156
	v_log_f32_e32 v155, v155
	s_nop 0
	v_mul_f32_e32 v156, 0x3f317217, v155
	v_fma_f32 v156, v155, s90, -v156
	v_fmac_f32_e32 v156, 0x3377d1cf, v155
	v_fmac_f32_e32 v156, 0x3f317217, v155
	v_cmp_lt_f32_e64 s[6:7], |v155|, s91
	s_nop 1
	v_cndmask_b32_e64 v155, v155, v156, s[6:7]
	v_cndmask_b32_e32 v156, 0, v222, vcc
	v_sub_f32_e32 v155, v155, v156
	v_pk_add_f32 v[152:153], v[152:153], v[154:155] neg_lo:[0,1] neg_hi:[0,1]
	v_fma_f32 v155, v72, v206, v136
	v_min_f32_e32 v154, 0, v155
	v_mul_f32_e64 v155, |v155|, s88
	v_exp_f32_e32 v155, v155
	v_pk_mul_f32 v[152:153], v[152:153], s[28:29] op_sel_hi:[1,0]
	v_add_f32_e32 v155, 1.0, v155
	v_cmp_gt_f32_e32 vcc, s89, v155
	v_cvt_pk_bf16_f32 v152, v152, v153
	s_nop 0
	v_cndmask_b32_e64 v156, 0, 32, vcc
	v_ldexp_f32 v155, v155, v156
	v_log_f32_e32 v155, v155
	s_nop 0
	v_mul_f32_e32 v156, 0x3f317217, v155
	v_fma_f32 v156, v155, s90, -v156
	v_fmac_f32_e32 v156, 0x3377d1cf, v155
	v_fmac_f32_e32 v156, 0x3f317217, v155
	v_cmp_lt_f32_e64 s[6:7], |v155|, s91
	s_nop 1
	v_cndmask_b32_e64 v155, v155, v156, s[6:7]
	v_cndmask_b32_e32 v156, 0, v222, vcc
	v_sub_f32_e32 v156, v155, v156
	v_min_f32_e32 v155, 0, v157
	v_mul_f32_e64 v157, |v157|, s88
	v_exp_f32_e32 v157, v157
	s_nop 0
	v_add_f32_e32 v157, 1.0, v157
	v_cmp_gt_f32_e32 vcc, s89, v157
	s_nop 1
	v_cndmask_b32_e64 v164, 0, 32, vcc
	v_ldexp_f32 v157, v157, v164
	v_log_f32_e32 v157, v157
	s_nop 0
	v_mul_f32_e32 v164, 0x3f317217, v157
	v_fma_f32 v164, v157, s90, -v164
	v_fmac_f32_e32 v164, 0x3377d1cf, v157
	v_fmac_f32_e32 v164, 0x3f317217, v157
	v_cmp_lt_f32_e64 s[6:7], |v157|, s91
	s_nop 1
	v_cndmask_b32_e64 v157, v157, v164, s[6:7]
	v_cndmask_b32_e32 v164, 0, v222, vcc
	v_sub_f32_e32 v157, v157, v164
	v_pk_add_f32 v[154:155], v[154:155], v[156:157] neg_lo:[0,1] neg_hi:[0,1]
	v_fma_f32 v157, v66, v206, v130
	v_min_f32_e32 v156, 0, v157
	v_mul_f32_e64 v157, |v157|, s88
	v_exp_f32_e32 v157, v157
	v_pk_mul_f32 v[154:155], v[154:155], s[28:29] op_sel_hi:[1,0]
	v_add_f32_e32 v157, 1.0, v157
	v_cmp_gt_f32_e32 vcc, s89, v157
	v_cvt_pk_bf16_f32 v153, v154, v155
	s_nop 0
	v_cndmask_b32_e64 v164, 0, 32, vcc
	v_ldexp_f32 v157, v157, v164
	v_log_f32_e32 v157, v157
	s_nop 0
	v_mul_f32_e32 v164, 0x3f317217, v157
	v_fma_f32 v164, v157, s90, -v164
	v_fmac_f32_e32 v164, 0x3377d1cf, v157
	v_fmac_f32_e32 v164, 0x3f317217, v157
	v_cmp_lt_f32_e64 s[6:7], |v157|, s91
	s_nop 1
	v_cndmask_b32_e64 v157, v157, v164, s[6:7]
	v_cndmask_b32_e32 v164, 0, v222, vcc
	v_sub_f32_e32 v164, v157, v164
	v_min_f32_e32 v157, 0, v165
	v_mul_f32_e64 v165, |v165|, s88
	v_exp_f32_e32 v165, v165
	s_nop 0
	v_add_f32_e32 v165, 1.0, v165
	v_cmp_gt_f32_e32 vcc, s89, v165
	s_nop 1
	v_cndmask_b32_e64 v166, 0, 32, vcc
	v_ldexp_f32 v165, v165, v166
	v_log_f32_e32 v165, v165
	s_nop 0
	v_mul_f32_e32 v166, 0x3f317217, v165
	v_fma_f32 v166, v165, s90, -v166
	v_fmac_f32_e32 v166, 0x3377d1cf, v165
	v_fmac_f32_e32 v166, 0x3f317217, v165
	v_cmp_lt_f32_e64 s[6:7], |v165|, s91
	s_nop 1
	v_cndmask_b32_e64 v165, v165, v166, s[6:7]
	v_cndmask_b32_e32 v166, 0, v222, vcc
	v_sub_f32_e32 v165, v165, v166
	v_pk_add_f32 v[156:157], v[156:157], v[164:165] neg_lo:[0,1] neg_hi:[0,1]
	v_fma_f32 v165, v68, v206, v132
	v_min_f32_e32 v164, 0, v165
	v_mul_f32_e64 v165, |v165|, s88
	v_exp_f32_e32 v165, v165
	v_pk_mul_f32 v[156:157], v[156:157], s[28:29] op_sel_hi:[1,0]
	v_add_f32_e32 v165, 1.0, v165
	v_cmp_gt_f32_e32 vcc, s89, v165
	v_cvt_pk_bf16_f32 v154, v156, v157
	v_add_u32_e32 v156, 48, v150
	v_cndmask_b32_e64 v166, 0, 32, vcc
	v_ldexp_f32 v165, v165, v166
	v_log_f32_e32 v165, v165
	v_ashrrev_i32_e32 v157, 31, v156
	v_lshlrev_b64 v[156:157], 9, v[156:157]
	v_lshl_add_u64 v[156:157], s[24:25], 0, v[156:157]
	v_mul_f32_e32 v166, 0x3f317217, v165
	v_fma_f32 v166, v165, s90, -v166
	v_fmac_f32_e32 v166, 0x3377d1cf, v165
	v_fmac_f32_e32 v166, 0x3f317217, v165
	v_cmp_lt_f32_e64 s[6:7], |v165|, s91
	v_lshl_add_u64 v[156:157], v[156:157], 0, v[184:185]
	s_nop 0
	v_cndmask_b32_e64 v165, v165, v166, s[6:7]
	v_cndmask_b32_e32 v166, 0, v222, vcc
	v_sub_f32_e32 v166, v165, v166
	v_min_f32_e32 v165, 0, v167
	v_mul_f32_e64 v167, |v167|, s88
	v_exp_f32_e32 v167, v167
	s_nop 0
	v_add_f32_e32 v167, 1.0, v167
	v_cmp_gt_f32_e32 vcc, s89, v167
	s_nop 1
	v_cndmask_b32_e64 v168, 0, 32, vcc
	v_ldexp_f32 v167, v167, v168
	v_log_f32_e32 v167, v167
	s_nop 0
	v_mul_f32_e32 v168, 0x3f317217, v167
	v_fma_f32 v168, v167, s90, -v168
	v_fmac_f32_e32 v168, 0x3377d1cf, v167
	v_fmac_f32_e32 v168, 0x3f317217, v167
	v_cmp_lt_f32_e64 s[6:7], |v167|, s91
	s_nop 1
	v_cndmask_b32_e64 v167, v167, v168, s[6:7]
	v_cndmask_b32_e32 v168, 0, v222, vcc
	v_sub_f32_e32 v167, v167, v168
	v_pk_add_f32 v[164:165], v[164:165], v[166:167] neg_lo:[0,1] neg_hi:[0,1]
	s_nop 0
	v_pk_mul_f32 v[164:165], v[164:165], s[28:29] op_sel_hi:[1,0]
	s_nop 0
	v_cvt_pk_bf16_f32 v155, v164, v165
	ds_write_b128 v160, v[146:149]
	ds_write_b128 v161, v[152:155]
	ds_read_b128 v[146:149], v163
	ds_read_b128 v[152:155], v163 offset:1024
	s_waitcnt lgkmcnt(1)
; __device__ __forceinline__ v4u pack8(const f32x4 a, const f32x4 b) { v4u w; w.x = pk2(a[0], a[1]); w.y = pk2(a[2], a[3]); w.z = pk2(b[0], b[1]); w.w = pk2(b[2], b[3]); return w; }
; __device__ __forceinline__ float fast_exp(float x) { return __builtin_amdgcn_exp2f(x * LOG2E); }
;     __device__ __forceinline__ void operator()(const f32x4 (&acc)[2][2][4][2], const pg8::Unit& u, int wr, int wc, int fr, int fq) const {
;     ...
;             for (int ai = 0; ai < 2; ++ai)
; #pragma unroll
;                 for (int m = 0; m < 4; ++m) {
;                     const int rowa = 256 * pm + 128 * ai + 64 * wr + 16 * m + tt.rr;
;                     const float rs = rs8[ai][m];
;                     v4u pk[2];
; #pragma unroll
;                     for (int bj = 0; bj < 2; ++bj) {
;                         f32x4 r2[2];
; #pragma unroll
;                         for (int n = 0; n < 2; ++n) {
;                             const f32x4 z = acc[ai][bj][m][n] * rs + bg[bj][n];
; #pragma unroll
;                             for (int j = 0; j < 4; ++j) { const float az = fabsf(z[j]); r2[n][j] = (fminf(z[j], 0.f) - __logf(1.0f + fast_exp(-az))) * (1.0f / 16.0f); }
;                         }
;                         pk[bj] = pack8(r2[0], r2[1]);
;                     }
;                     v4u a, b; tt.bf(pk[0], pk[1], a, b);
;                     bf16* d = (bf16*)(ws + WS_LOGA) + (size_t)rowa * 256 + 64 * wc + 8 * tt.p; *(v4u*)d = a; *(v4u*)(d + 8 * 256) = b;
	global_store_dwordx4 v[156:157], v[146:149], off sc1
	s_nop 1
	v_add_co_u32_e32 v146, vcc, s92, v156
	v_fma_f32 v149, v63, v204, v143
	s_nop 0
	v_addc_co_u32_e32 v147, vcc, 0, v157, vcc
	s_waitcnt lgkmcnt(0)
	global_store_dwordx4 v[146:147], v[152:155], off sc1
	v_fma_f32 v147, v62, v204, v142
	v_min_f32_e32 v146, 0, v147
	v_mul_f32_e64 v147, |v147|, s88
	v_exp_f32_e32 v147, v147
	v_add_u32_e32 v152, 0x80, v150
	v_add_f32_e32 v147, 1.0, v147
	v_cmp_gt_f32_e32 vcc, s89, v147
	s_nop 1
	v_cndmask_b32_e64 v148, 0, 32, vcc
	v_ldexp_f32 v147, v147, v148
	v_log_f32_e32 v147, v147
	s_nop 0
	v_mul_f32_e32 v148, 0x3f317217, v147
	v_fma_f32 v148, v147, s90, -v148
	v_fmac_f32_e32 v148, 0x3377d1cf, v147
	v_fmac_f32_e32 v148, 0x3f317217, v147
	v_cmp_lt_f32_e64 s[6:7], |v147|, s91
	s_nop 1
	v_cndmask_b32_e64 v147, v147, v148, s[6:7]
	v_cndmask_b32_e32 v148, 0, v222, vcc
	v_sub_f32_e32 v148, v147, v148
	v_min_f32_e32 v147, 0, v149
	v_mul_f32_e64 v149, |v149|, s88
	v_exp_f32_e32 v149, v149
	s_nop 0
	v_add_f32_e32 v149, 1.0, v149
	v_cmp_gt_f32_e32 vcc, s89, v149
	s_nop 1
	v_cndmask_b32_e64 v153, 0, 32, vcc
	v_ldexp_f32 v149, v149, v153
	v_log_f32_e32 v149, v149
	s_nop 0
	v_mul_f32_e32 v153, 0x3f317217, v149
	v_fma_f32 v153, v149, s90, -v153
	v_fmac_f32_e32 v153, 0x3377d1cf, v149
	v_fmac_f32_e32 v153, 0x3f317217, v149
	v_cmp_lt_f32_e64 s[6:7], |v149|, s91
	s_nop 1
	v_cndmask_b32_e64 v149, v149, v153, s[6:7]
	v_cndmask_b32_e32 v153, 0, v222, vcc
	v_sub_f32_e32 v149, v149, v153
	v_pk_add_f32 v[146:147], v[146:147], v[148:149] neg_lo:[0,1] neg_hi:[0,1]
	v_fma_f32 v149, v64, v204, v144
	v_min_f32_e32 v148, 0, v149
	v_mul_f32_e64 v149, |v149|, s88
	v_exp_f32_e32 v149, v149
	v_pk_mul_f32 v[146:147], v[146:147], s[28:29] op_sel_hi:[1,0]
	v_add_f32_e32 v149, 1.0, v149
	v_cmp_gt_f32_e32 vcc, s89, v149
	v_cvt_pk_bf16_f32 v146, v146, v147
	s_nop 0
	v_cndmask_b32_e64 v153, 0, 32, vcc
	v_ldexp_f32 v149, v149, v153
	v_log_f32_e32 v149, v149
	s_nop 0
	v_mul_f32_e32 v153, 0x3f317217, v149
	v_fma_f32 v153, v149, s90, -v153
	v_fmac_f32_e32 v153, 0x3377d1cf, v149
	v_fmac_f32_e32 v153, 0x3f317217, v149
	v_cmp_lt_f32_e64 s[6:7], |v149|, s91
	s_nop 1
	v_cndmask_b32_e64 v149, v149, v153, s[6:7]
	v_cndmask_b32_e32 v153, 0, v222, vcc
	v_sub_f32_e32 v154, v149, v153
	v_fma_f32 v153, v65, v204, v145
	v_min_f32_e32 v149, 0, v153
	v_mul_f32_e64 v153, |v153|, s88
	v_exp_f32_e32 v153, v153
	s_nop 0
	v_add_f32_e32 v153, 1.0, v153
	v_cmp_gt_f32_e32 vcc, s89, v153
	s_nop 1
	v_cndmask_b32_e64 v155, 0, 32, vcc
	v_ldexp_f32 v153, v153, v155
	v_log_f32_e32 v153, v153
	s_nop 0
	v_mul_f32_e32 v155, 0x3f317217, v153
	v_fma_f32 v155, v153, s90, -v155
	v_fmac_f32_e32 v155, 0x3377d1cf, v153
	v_fmac_f32_e32 v155, 0x3f317217, v153
	v_cmp_lt_f32_e64 s[6:7], |v153|, s91
	s_nop 1
	v_cndmask_b32_e64 v153, v153, v155, s[6:7]
	v_cndmask_b32_e32 v155, 0, v222, vcc
	v_sub_f32_e32 v155, v153, v155
	v_fma_f32 v153, v58, v204, v138
	v_pk_add_f32 v[148:149], v[148:149], v[154:155] neg_lo:[0,1] neg_hi:[0,1]
	v_min_f32_e32 v154, 0, v153
	v_mul_f32_e64 v153, |v153|, s88
	v_exp_f32_e32 v153, v153
	v_pk_mul_f32 v[148:149], v[148:149], s[28:29] op_sel_hi:[1,0]
	v_add_f32_e32 v153, 1.0, v153
	v_cmp_gt_f32_e32 vcc, s89, v153
	v_cvt_pk_bf16_f32 v147, v148, v149
	s_nop 0
	v_cndmask_b32_e64 v155, 0, 32, vcc
	v_ldexp_f32 v153, v153, v155
	v_log_f32_e32 v153, v153
	s_nop 0
	v_mul_f32_e32 v155, 0x3f317217, v153
	v_fma_f32 v155, v153, s90, -v155
	v_fmac_f32_e32 v155, 0x3377d1cf, v153
	v_fmac_f32_e32 v155, 0x3f317217, v153
	v_cmp_lt_f32_e64 s[6:7], |v153|, s91
	s_nop 1
	v_cndmask_b32_e64 v153, v153, v155, s[6:7]
	v_cndmask_b32_e32 v155, 0, v222, vcc
	v_sub_f32_e32 v156, v153, v155
	v_fma_f32 v153, v59, v204, v139
	v_min_f32_e32 v155, 0, v153
	v_mul_f32_e64 v153, |v153|, s88
	v_exp_f32_e32 v153, v153
	s_nop 0
	v_add_f32_e32 v153, 1.0, v153
	v_cmp_gt_f32_e32 vcc, s89, v153
	s_nop 1
	v_cndmask_b32_e64 v157, 0, 32, vcc
	v_ldexp_f32 v153, v153, v157
	v_log_f32_e32 v153, v153
	s_nop 0
	v_mul_f32_e32 v157, 0x3f317217, v153
	v_fma_f32 v157, v153, s90, -v157
	v_fmac_f32_e32 v157, 0x3377d1cf, v153
	v_fmac_f32_e32 v157, 0x3f317217, v153
	v_cmp_lt_f32_e64 s[6:7], |v153|, s91
	s_nop 1
	v_cndmask_b32_e64 v153, v153, v157, s[6:7]
	v_cndmask_b32_e32 v157, 0, v222, vcc
	v_sub_f32_e32 v157, v153, v157
	v_fma_f32 v153, v60, v204, v140
	v_pk_add_f32 v[154:155], v[154:155], v[156:157] neg_lo:[0,1] neg_hi:[0,1]
	v_min_f32_e32 v156, 0, v153
	v_mul_f32_e64 v153, |v153|, s88
	v_exp_f32_e32 v153, v153
	v_pk_mul_f32 v[154:155], v[154:155], s[28:29] op_sel_hi:[1,0]
	v_add_f32_e32 v153, 1.0, v153
	v_cmp_gt_f32_e32 vcc, s89, v153
	v_cvt_pk_bf16_f32 v148, v154, v155
	s_nop 0
	v_cndmask_b32_e64 v157, 0, 32, vcc
	v_ldexp_f32 v153, v153, v157
	v_log_f32_e32 v153, v153
	s_nop 0
	v_mul_f32_e32 v157, 0x3f317217, v153
	v_fma_f32 v157, v153, s90, -v157
	v_fmac_f32_e32 v157, 0x3377d1cf, v153
	v_fmac_f32_e32 v157, 0x3f317217, v153
	v_cmp_lt_f32_e64 s[6:7], |v153|, s91
	s_nop 1
	v_cndmask_b32_e64 v153, v153, v157, s[6:7]
	v_cndmask_b32_e32 v157, 0, v222, vcc
	v_sub_f32_e32 v164, v153, v157
	v_fma_f32 v153, v61, v204, v141
	v_min_f32_e32 v157, 0, v153
	v_mul_f32_e64 v153, |v153|, s88
	v_exp_f32_e32 v153, v153
	s_nop 0
	v_add_f32_e32 v153, 1.0, v153
	v_cmp_gt_f32_e32 vcc, s89, v153
	s_nop 1
	v_cndmask_b32_e64 v165, 0, 32, vcc
	v_ldexp_f32 v153, v153, v165
	v_log_f32_e32 v153, v153
	s_nop 0
	v_mul_f32_e32 v165, 0x3f317217, v153
	v_fma_f32 v165, v153, s90, -v165
	v_fmac_f32_e32 v165, 0x3377d1cf, v153
	v_fmac_f32_e32 v165, 0x3f317217, v153
	v_cmp_lt_f32_e64 s[6:7], |v153|, s91
	s_nop 1
	v_cndmask_b32_e64 v153, v153, v165, s[6:7]
	v_cndmask_b32_e32 v165, 0, v222, vcc
; __device__ __forceinline__ v4u pack8(const f32x4 a, const f32x4 b) { v4u w; w.x = pk2(a[0], a[1]); w.y = pk2(a[2], a[3]); w.z = pk2(b[0], b[1]); w.w = pk2(b[2], b[3]); return w; }
; __device__ __forceinline__ float fast_exp(float x) { return __builtin_amdgcn_exp2f(x * LOG2E); }
;     __device__ __forceinline__ void operator()(const f32x4 (&acc)[2][2][4][2], const pg8::Unit& u, int wr, int wc, int fr, int fq) const {
;     ...
;             for (int ai = 0; ai < 2; ++ai)
; #pragma unroll
;                 for (int m = 0; m < 4; ++m) {
;                     const int rowa = 256 * pm + 128 * ai + 64 * wr + 16 * m + tt.rr;
;                     const float rs = rs8[ai][m];
;                     v4u pk[2];
; #pragma unroll
;                     for (int bj = 0; bj < 2; ++bj) {
;                         f32x4 r2[2];
; #pragma unroll
;                         for (int n = 0; n < 2; ++n) {
;                             const f32x4 z = acc[ai][bj][m][n] * rs + bg[bj][n];
; #pragma unroll
;                             for (int j = 0; j < 4; ++j) { const float az = fabsf(z[j]); r2[n][j] = (fminf(z[j], 0.f) - __logf(1.0f + fast_exp(-az))) * (1.0f / 16.0f); }
;                         }
;                         pk[bj] = pack8(r2[0], r2[1]);
;                     }
;                     v4u a, b; tt.bf(pk[0], pk[1], a, b);
;                     bf16* d = (bf16*)(ws + WS_LOGA) + (size_t)rowa * 256 + 64 * wc + 8 * tt.p; *(v4u*)d = a; *(v4u*)(d + 8 * 256) = b;
	v_sub_f32_e32 v165, v153, v165
	v_fma_f32 v153, v54, v204, v134
	v_min_f32_e32 v154, 0, v153
	v_mul_f32_e64 v153, |v153|, s88
	v_exp_f32_e32 v153, v153
	v_pk_add_f32 v[156:157], v[156:157], v[164:165] neg_lo:[0,1] neg_hi:[0,1]
	v_add_f32_e32 v153, 1.0, v153
	v_cmp_gt_f32_e32 vcc, s89, v153
	v_pk_mul_f32 v[156:157], v[156:157], s[28:29] op_sel_hi:[1,0]
	s_nop 0
	v_cndmask_b32_e64 v155, 0, 32, vcc
	v_ldexp_f32 v153, v153, v155
	v_log_f32_e32 v153, v153
	v_cvt_pk_bf16_f32 v149, v156, v157
	v_mul_f32_e32 v155, 0x3f317217, v153
	v_fma_f32 v155, v153, s90, -v155
	v_fmac_f32_e32 v155, 0x3377d1cf, v153
	v_fmac_f32_e32 v155, 0x3f317217, v153
	v_cmp_lt_f32_e64 s[6:7], |v153|, s91
	s_nop 1
	v_cndmask_b32_e64 v153, v153, v155, s[6:7]
	v_cndmask_b32_e32 v155, 0, v222, vcc
	v_sub_f32_e32 v156, v153, v155
	v_fma_f32 v153, v55, v204, v135
	v_min_f32_e32 v155, 0, v153
	v_mul_f32_e64 v153, |v153|, s88
	v_exp_f32_e32 v153, v153
	s_nop 0
	v_add_f32_e32 v153, 1.0, v153
	v_cmp_gt_f32_e32 vcc, s89, v153
	s_nop 1
	v_cndmask_b32_e64 v157, 0, 32, vcc
	v_ldexp_f32 v153, v153, v157
	v_log_f32_e32 v153, v153
	s_nop 0
	v_mul_f32_e32 v157, 0x3f317217, v153
	v_fma_f32 v157, v153, s90, -v157
	v_fmac_f32_e32 v157, 0x3377d1cf, v153
	v_fmac_f32_e32 v157, 0x3f317217, v153
	v_cmp_lt_f32_e64 s[6:7], |v153|, s91
	s_nop 1
	v_cndmask_b32_e64 v153, v153, v157, s[6:7]
	v_cndmask_b32_e32 v157, 0, v222, vcc
	v_sub_f32_e32 v157, v153, v157
	v_fma_f32 v153, v56, v204, v136
	v_pk_add_f32 v[154:155], v[154:155], v[156:157] neg_lo:[0,1] neg_hi:[0,1]
	v_min_f32_e32 v156, 0, v153
	v_mul_f32_e64 v153, |v153|, s88
	v_exp_f32_e32 v153, v153
	v_pk_mul_f32 v[154:155], v[154:155], s[28:29] op_sel_hi:[1,0]
	v_add_f32_e32 v153, 1.0, v153
	v_cmp_gt_f32_e32 vcc, s89, v153
	v_cvt_pk_bf16_f32 v154, v154, v155
	s_nop 0
	v_cndmask_b32_e64 v157, 0, 32, vcc
	v_ldexp_f32 v153, v153, v157
	v_log_f32_e32 v153, v153
	s_nop 0
	v_mul_f32_e32 v157, 0x3f317217, v153
	v_fma_f32 v157, v153, s90, -v157
	v_fmac_f32_e32 v157, 0x3377d1cf, v153
	v_fmac_f32_e32 v157, 0x3f317217, v153
	v_cmp_lt_f32_e64 s[6:7], |v153|, s91
	s_nop 1
	v_cndmask_b32_e64 v153, v153, v157, s[6:7]
	v_cndmask_b32_e32 v157, 0, v222, vcc
	v_sub_f32_e32 v164, v153, v157
	v_fma_f32 v153, v57, v204, v137
	v_min_f32_e32 v157, 0, v153
	v_mul_f32_e64 v153, |v153|, s88
	v_exp_f32_e32 v153, v153
	s_nop 0
	v_add_f32_e32 v153, 1.0, v153
	v_cmp_gt_f32_e32 vcc, s89, v153
	s_nop 1
	v_cndmask_b32_e64 v165, 0, 32, vcc
	v_ldexp_f32 v153, v153, v165
	v_log_f32_e32 v153, v153
	s_nop 0
	v_mul_f32_e32 v165, 0x3f317217, v153
	v_fma_f32 v165, v153, s90, -v165
	v_fmac_f32_e32 v165, 0x3377d1cf, v153
	v_fmac_f32_e32 v165, 0x3f317217, v153
	v_cmp_lt_f32_e64 s[6:7], |v153|, s91
	s_nop 1
	v_cndmask_b32_e64 v153, v153, v165, s[6:7]
	v_cndmask_b32_e32 v165, 0, v222, vcc
	v_sub_f32_e32 v165, v153, v165
	v_fma_f32 v153, v50, v204, v130
	v_pk_add_f32 v[156:157], v[156:157], v[164:165] neg_lo:[0,1] neg_hi:[0,1]
	v_min_f32_e32 v164, 0, v153
	v_mul_f32_e64 v153, |v153|, s88
	v_exp_f32_e32 v153, v153
	v_pk_mul_f32 v[156:157], v[156:157], s[28:29] op_sel_hi:[1,0]
	v_add_f32_e32 v153, 1.0, v153
	v_cmp_gt_f32_e32 vcc, s89, v153
	v_cvt_pk_bf16_f32 v155, v156, v157
	s_nop 0
	v_cndmask_b32_e64 v165, 0, 32, vcc
	v_ldexp_f32 v153, v153, v165
	v_log_f32_e32 v153, v153
	s_nop 0
	v_mul_f32_e32 v165, 0x3f317217, v153
	v_fma_f32 v165, v153, s90, -v165
	v_fmac_f32_e32 v165, 0x3377d1cf, v153
	v_fmac_f32_e32 v165, 0x3f317217, v153
	v_cmp_lt_f32_e64 s[6:7], |v153|, s91
	s_nop 1
	v_cndmask_b32_e64 v153, v153, v165, s[6:7]
	v_cndmask_b32_e32 v165, 0, v222, vcc
	v_sub_f32_e32 v166, v153, v165
	v_fma_f32 v153, v51, v204, v131
	v_min_f32_e32 v165, 0, v153
	v_mul_f32_e64 v153, |v153|, s88
	v_exp_f32_e32 v153, v153
	s_nop 0
	v_add_f32_e32 v153, 1.0, v153
	v_cmp_gt_f32_e32 vcc, s89, v153
	s_nop 1
	v_cndmask_b32_e64 v167, 0, 32, vcc
	v_ldexp_f32 v153, v153, v167
	v_log_f32_e32 v153, v153
	s_nop 0
	v_mul_f32_e32 v167, 0x3f317217, v153
	v_fma_f32 v167, v153, s90, -v167
	v_fmac_f32_e32 v167, 0x3377d1cf, v153
	v_fmac_f32_e32 v167, 0x3f317217, v153
	v_cmp_lt_f32_e64 s[6:7], |v153|, s91
	s_nop 1
	v_cndmask_b32_e64 v153, v153, v167, s[6:7]
	v_cndmask_b32_e32 v167, 0, v222, vcc
	v_sub_f32_e32 v167, v153, v167
	v_fma_f32 v153, v52, v204, v132
	v_pk_add_f32 v[164:165], v[164:165], v[166:167] neg_lo:[0,1] neg_hi:[0,1]
	v_min_f32_e32 v166, 0, v153
	v_mul_f32_e64 v153, |v153|, s88
	v_exp_f32_e32 v153, v153
	v_pk_mul_f32 v[164:165], v[164:165], s[28:29] op_sel_hi:[1,0]
	v_add_f32_e32 v153, 1.0, v153
	v_cmp_gt_f32_e32 vcc, s89, v153
	v_cvt_pk_bf16_f32 v156, v164, v165
	v_fma_f32 v165, v35, v202, v131
	v_cndmask_b32_e64 v167, 0, 32, vcc
	v_ldexp_f32 v153, v153, v167
	v_log_f32_e32 v153, v153
	s_nop 0
	v_mul_f32_e32 v167, 0x3f317217, v153
	v_fma_f32 v167, v153, s90, -v167
	v_fmac_f32_e32 v167, 0x3377d1cf, v153
	v_fmac_f32_e32 v167, 0x3f317217, v153
	v_cmp_lt_f32_e64 s[6:7], |v153|, s91
	s_nop 1
	v_cndmask_b32_e64 v153, v153, v167, s[6:7]
	v_cndmask_b32_e32 v167, 0, v222, vcc
	v_sub_f32_e32 v168, v153, v167
	v_fma_f32 v153, v53, v204, v133
	v_min_f32_e32 v167, 0, v153
	v_mul_f32_e64 v153, |v153|, s88
	v_exp_f32_e32 v153, v153
	s_nop 0
	v_add_f32_e32 v153, 1.0, v153
	v_cmp_gt_f32_e32 vcc, s89, v153
	s_nop 1
	v_cndmask_b32_e64 v169, 0, 32, vcc
	v_ldexp_f32 v153, v153, v169
	v_log_f32_e32 v153, v153
	s_nop 0
	v_mul_f32_e32 v169, 0x3f317217, v153
	v_fma_f32 v169, v153, s90, -v169
	v_fmac_f32_e32 v169, 0x3377d1cf, v153
	v_fmac_f32_e32 v169, 0x3f317217, v153
	v_cmp_lt_f32_e64 s[6:7], |v153|, s91
	s_nop 1
	v_cndmask_b32_e64 v153, v153, v169, s[6:7]
	v_cndmask_b32_e32 v169, 0, v222, vcc
	v_sub_f32_e32 v169, v153, v169
	v_pk_add_f32 v[166:167], v[166:167], v[168:169] neg_lo:[0,1] neg_hi:[0,1]
	v_ashrrev_i32_e32 v153, 31, v152
	v_pk_mul_f32 v[166:167], v[166:167], s[28:29] op_sel_hi:[1,0]
	v_lshlrev_b64 v[152:153], 9, v[152:153]
	v_cvt_pk_bf16_f32 v157, v166, v167
	ds_write_b128 v160, v[146:149]
	ds_write_b128 v161, v[154:157]
	ds_read_b128 v[146:149], v163
	ds_read_b128 v[154:157], v163 offset:1024
	v_lshl_add_u64 v[152:153], s[24:25], 0, v[152:153]
	v_lshl_add_u64 v[152:153], v[152:153], 0, v[184:185]
	v_fma_f32 v167, v37, v202, v133
	s_waitcnt lgkmcnt(1)
; __device__ __forceinline__ v4u pack8(const f32x4 a, const f32x4 b) { v4u w; w.x = pk2(a[0], a[1]); w.y = pk2(a[2], a[3]); w.z = pk2(b[0], b[1]); w.w = pk2(b[2], b[3]); return w; }
; __device__ __forceinline__ float fast_exp(float x) { return __builtin_amdgcn_exp2f(x * LOG2E); }
;     __device__ __forceinline__ void operator()(const f32x4 (&acc)[2][2][4][2], const pg8::Unit& u, int wr, int wc, int fr, int fq) const {
;     ...
;             for (int ai = 0; ai < 2; ++ai)
; #pragma unroll
;                 for (int m = 0; m < 4; ++m) {
;                     const int rowa = 256 * pm + 128 * ai + 64 * wr + 16 * m + tt.rr;
;                     const float rs = rs8[ai][m];
;                     v4u pk[2];
; #pragma unroll
;                     for (int bj = 0; bj < 2; ++bj) {
;                         f32x4 r2[2];
; #pragma unroll
;                         for (int n = 0; n < 2; ++n) {
;                             const f32x4 z = acc[ai][bj][m][n] * rs + bg[bj][n];
; #pragma unroll
;                             for (int j = 0; j < 4; ++j) { const float az = fabsf(z[j]); r2[n][j] = (fminf(z[j], 0.f) - __logf(1.0f + fast_exp(-az))) * (1.0f / 16.0f); }
;                         }
;                         pk[bj] = pack8(r2[0], r2[1]);
;                     }
;                     v4u a, b; tt.bf(pk[0], pk[1], a, b);
;                     bf16* d = (bf16*)(ws + WS_LOGA) + (size_t)rowa * 256 + 64 * wc + 8 * tt.p; *(v4u*)d = a; *(v4u*)(d + 8 * 256) = b;
	global_store_dwordx4 v[152:153], v[146:149], off sc1
	s_nop 1
	v_add_co_u32_e32 v146, vcc, s92, v152
	v_fma_f32 v149, v47, v202, v143
	s_nop 0
	v_addc_co_u32_e32 v147, vcc, 0, v153, vcc
	s_waitcnt lgkmcnt(0)
	global_store_dwordx4 v[146:147], v[154:157], off sc1
	v_fma_f32 v147, v46, v202, v142
	v_min_f32_e32 v146, 0, v147
	v_mul_f32_e64 v147, |v147|, s88
	v_exp_f32_e32 v147, v147
	v_fma_f32 v153, v49, v202, v145
	v_fma_f32 v155, v43, v202, v139
	v_fma_f32 v157, v45, v202, v141
	v_add_f32_e32 v147, 1.0, v147
	v_cmp_gt_f32_e32 vcc, s89, v147
	s_nop 1
	v_cndmask_b32_e64 v148, 0, 32, vcc
	v_ldexp_f32 v147, v147, v148
	v_log_f32_e32 v147, v147
	s_nop 0
	v_mul_f32_e32 v148, 0x3f317217, v147
	v_fma_f32 v148, v147, s90, -v148
	v_fmac_f32_e32 v148, 0x3377d1cf, v147
	v_fmac_f32_e32 v148, 0x3f317217, v147
	v_cmp_lt_f32_e64 s[6:7], |v147|, s91
	s_nop 1
	v_cndmask_b32_e64 v147, v147, v148, s[6:7]
	v_cndmask_b32_e32 v148, 0, v222, vcc
	v_sub_f32_e32 v148, v147, v148
	v_min_f32_e32 v147, 0, v149
	v_mul_f32_e64 v149, |v149|, s88
	v_exp_f32_e32 v149, v149
	s_nop 0
	v_add_f32_e32 v149, 1.0, v149
	v_cmp_gt_f32_e32 vcc, s89, v149
	s_nop 1
	v_cndmask_b32_e64 v152, 0, 32, vcc
	v_ldexp_f32 v149, v149, v152
	v_log_f32_e32 v149, v149
	s_nop 0
	v_mul_f32_e32 v152, 0x3f317217, v149
	v_fma_f32 v152, v149, s90, -v152
	v_fmac_f32_e32 v152, 0x3377d1cf, v149
	v_fmac_f32_e32 v152, 0x3f317217, v149
	v_cmp_lt_f32_e64 s[6:7], |v149|, s91
	s_nop 1
	v_cndmask_b32_e64 v149, v149, v152, s[6:7]
	v_cndmask_b32_e32 v152, 0, v222, vcc
	v_sub_f32_e32 v149, v149, v152
	v_pk_add_f32 v[146:147], v[146:147], v[148:149] neg_lo:[0,1] neg_hi:[0,1]
	v_fma_f32 v149, v48, v202, v144
	v_min_f32_e32 v148, 0, v149
	v_mul_f32_e64 v149, |v149|, s88
	v_exp_f32_e32 v149, v149
	v_pk_mul_f32 v[146:147], v[146:147], s[28:29] op_sel_hi:[1,0]
	v_add_f32_e32 v149, 1.0, v149
	v_cmp_gt_f32_e32 vcc, s89, v149
	v_cvt_pk_bf16_f32 v146, v146, v147
	s_nop 0
	v_cndmask_b32_e64 v152, 0, 32, vcc
	v_ldexp_f32 v149, v149, v152
	v_log_f32_e32 v149, v149
	s_nop 0
	v_mul_f32_e32 v152, 0x3f317217, v149
	v_fma_f32 v152, v149, s90, -v152
	v_fmac_f32_e32 v152, 0x3377d1cf, v149
	v_fmac_f32_e32 v152, 0x3f317217, v149
	v_cmp_lt_f32_e64 s[6:7], |v149|, s91
	s_nop 1
	v_cndmask_b32_e64 v149, v149, v152, s[6:7]
	v_cndmask_b32_e32 v152, 0, v222, vcc
	v_sub_f32_e32 v152, v149, v152
	v_min_f32_e32 v149, 0, v153
	v_mul_f32_e64 v153, |v153|, s88
	v_exp_f32_e32 v153, v153
	s_nop 0
	v_add_f32_e32 v153, 1.0, v153
	v_cmp_gt_f32_e32 vcc, s89, v153
	s_nop 1
	v_cndmask_b32_e64 v154, 0, 32, vcc
	v_ldexp_f32 v153, v153, v154
	v_log_f32_e32 v153, v153
	s_nop 0
	v_mul_f32_e32 v154, 0x3f317217, v153
	v_fma_f32 v154, v153, s90, -v154
	v_fmac_f32_e32 v154, 0x3377d1cf, v153
	v_fmac_f32_e32 v154, 0x3f317217, v153
	v_cmp_lt_f32_e64 s[6:7], |v153|, s91
	s_nop 1
	v_cndmask_b32_e64 v153, v153, v154, s[6:7]
	v_cndmask_b32_e32 v154, 0, v222, vcc
	v_sub_f32_e32 v153, v153, v154
	v_pk_add_f32 v[148:149], v[148:149], v[152:153] neg_lo:[0,1] neg_hi:[0,1]
	v_fma_f32 v153, v42, v202, v138
	v_min_f32_e32 v152, 0, v153
	v_mul_f32_e64 v153, |v153|, s88
	v_exp_f32_e32 v153, v153
	v_pk_mul_f32 v[148:149], v[148:149], s[28:29] op_sel_hi:[1,0]
	v_add_f32_e32 v153, 1.0, v153
	v_cmp_gt_f32_e32 vcc, s89, v153
	v_cvt_pk_bf16_f32 v147, v148, v149
	s_nop 0
	v_cndmask_b32_e64 v154, 0, 32, vcc
	v_ldexp_f32 v153, v153, v154
	v_log_f32_e32 v153, v153
	s_nop 0
	v_mul_f32_e32 v154, 0x3f317217, v153
	v_fma_f32 v154, v153, s90, -v154
	v_fmac_f32_e32 v154, 0x3377d1cf, v153
	v_fmac_f32_e32 v154, 0x3f317217, v153
	v_cmp_lt_f32_e64 s[6:7], |v153|, s91
	s_nop 1
	v_cndmask_b32_e64 v153, v153, v154, s[6:7]
	v_cndmask_b32_e32 v154, 0, v222, vcc
	v_sub_f32_e32 v154, v153, v154
	v_min_f32_e32 v153, 0, v155
	v_mul_f32_e64 v155, |v155|, s88
	v_exp_f32_e32 v155, v155
	s_nop 0
	v_add_f32_e32 v155, 1.0, v155
	v_cmp_gt_f32_e32 vcc, s89, v155
	s_nop 1
	v_cndmask_b32_e64 v156, 0, 32, vcc
	v_ldexp_f32 v155, v155, v156
	v_log_f32_e32 v155, v155
	s_nop 0
	v_mul_f32_e32 v156, 0x3f317217, v155
	v_fma_f32 v156, v155, s90, -v156
	v_fmac_f32_e32 v156, 0x3377d1cf, v155
	v_fmac_f32_e32 v156, 0x3f317217, v155
	v_cmp_lt_f32_e64 s[6:7], |v155|, s91
	s_nop 1
	v_cndmask_b32_e64 v155, v155, v156, s[6:7]
	v_cndmask_b32_e32 v156, 0, v222, vcc
	v_sub_f32_e32 v155, v155, v156
	v_pk_add_f32 v[152:153], v[152:153], v[154:155] neg_lo:[0,1] neg_hi:[0,1]
	v_fma_f32 v155, v44, v202, v140
	v_min_f32_e32 v154, 0, v155
	v_mul_f32_e64 v155, |v155|, s88
	v_exp_f32_e32 v155, v155
	v_pk_mul_f32 v[152:153], v[152:153], s[28:29] op_sel_hi:[1,0]
	v_add_f32_e32 v155, 1.0, v155
	v_cmp_gt_f32_e32 vcc, s89, v155
	v_cvt_pk_bf16_f32 v148, v152, v153
	v_fma_f32 v153, v38, v202, v134
	v_cndmask_b32_e64 v156, 0, 32, vcc
	v_ldexp_f32 v155, v155, v156
	v_log_f32_e32 v155, v155
	v_min_f32_e32 v152, 0, v153
	v_mul_f32_e64 v153, |v153|, s88
	v_exp_f32_e32 v153, v153
	v_mul_f32_e32 v156, 0x3f317217, v155
	v_fma_f32 v156, v155, s90, -v156
	v_fmac_f32_e32 v156, 0x3377d1cf, v155
	v_fmac_f32_e32 v156, 0x3f317217, v155
	v_cmp_lt_f32_e64 s[6:7], |v155|, s91
	v_add_f32_e32 v153, 1.0, v153
	s_nop 0
	v_cndmask_b32_e64 v155, v155, v156, s[6:7]
	v_cndmask_b32_e32 v156, 0, v222, vcc
	v_sub_f32_e32 v156, v155, v156
	v_min_f32_e32 v155, 0, v157
	v_mul_f32_e64 v157, |v157|, s88
	v_exp_f32_e32 v157, v157
	s_nop 0
	v_add_f32_e32 v157, 1.0, v157
	v_cmp_gt_f32_e32 vcc, s89, v157
	s_nop 1
	v_cndmask_b32_e64 v164, 0, 32, vcc
	v_ldexp_f32 v157, v157, v164
	v_log_f32_e32 v157, v157
	s_nop 0
	v_mul_f32_e32 v164, 0x3f317217, v157
	v_fma_f32 v164, v157, s90, -v164
	v_fmac_f32_e32 v164, 0x3377d1cf, v157
	v_fmac_f32_e32 v164, 0x3f317217, v157
	v_cmp_lt_f32_e64 s[6:7], |v157|, s91
; __device__ __forceinline__ v4u pack8(const f32x4 a, const f32x4 b) { v4u w; w.x = pk2(a[0], a[1]); w.y = pk2(a[2], a[3]); w.z = pk2(b[0], b[1]); w.w = pk2(b[2], b[3]); return w; }
; __device__ __forceinline__ float fast_exp(float x) { return __builtin_amdgcn_exp2f(x * LOG2E); }
;     __device__ __forceinline__ void operator()(const f32x4 (&acc)[2][2][4][2], const pg8::Unit& u, int wr, int wc, int fr, int fq) const {
;     ...
;             for (int ai = 0; ai < 2; ++ai)
; #pragma unroll
;                 for (int m = 0; m < 4; ++m) {
;                     const int rowa = 256 * pm + 128 * ai + 64 * wr + 16 * m + tt.rr;
;                     const float rs = rs8[ai][m];
;                     v4u pk[2];
; #pragma unroll
;                     for (int bj = 0; bj < 2; ++bj) {
;                         f32x4 r2[2];
; #pragma unroll
;                         for (int n = 0; n < 2; ++n) {
;                             const f32x4 z = acc[ai][bj][m][n] * rs + bg[bj][n];
; #pragma unroll
;                             for (int j = 0; j < 4; ++j) { const float az = fabsf(z[j]); r2[n][j] = (fminf(z[j], 0.f) - __logf(1.0f + fast_exp(-az))) * (1.0f / 16.0f); }
;                         }
;                         pk[bj] = pack8(r2[0], r2[1]);
;                     }
;                     v4u a, b; tt.bf(pk[0], pk[1], a, b);
;                     bf16* d = (bf16*)(ws + WS_LOGA) + (size_t)rowa * 256 + 64 * wc + 8 * tt.p; *(v4u*)d = a; *(v4u*)(d + 8 * 256) = b;
	s_nop 1
	v_cndmask_b32_e64 v157, v157, v164, s[6:7]
	v_cndmask_b32_e32 v164, 0, v222, vcc
	v_sub_f32_e32 v157, v157, v164
	v_pk_add_f32 v[154:155], v[154:155], v[156:157] neg_lo:[0,1] neg_hi:[0,1]
	v_cmp_gt_f32_e32 vcc, s89, v153
	v_pk_mul_f32 v[154:155], v[154:155], s[28:29] op_sel_hi:[1,0]
	v_fma_f32 v157, v41, v202, v137
	v_cvt_pk_bf16_f32 v149, v154, v155
	v_cndmask_b32_e64 v154, 0, 32, vcc
	v_ldexp_f32 v153, v153, v154
	v_log_f32_e32 v153, v153
	v_fma_f32 v155, v39, v202, v135
	v_mul_f32_e32 v154, 0x3f317217, v153
	v_fma_f32 v154, v153, s90, -v154
	v_fmac_f32_e32 v154, 0x3377d1cf, v153
	v_fmac_f32_e32 v154, 0x3f317217, v153
	v_cmp_lt_f32_e64 s[6:7], |v153|, s91
	s_nop 1
	v_cndmask_b32_e64 v153, v153, v154, s[6:7]
	v_cndmask_b32_e32 v154, 0, v222, vcc
	v_sub_f32_e32 v154, v153, v154
	v_min_f32_e32 v153, 0, v155
	v_mul_f32_e64 v155, |v155|, s88
	v_exp_f32_e32 v155, v155
	s_nop 0
	v_add_f32_e32 v155, 1.0, v155
	v_cmp_gt_f32_e32 vcc, s89, v155
	s_nop 1
	v_cndmask_b32_e64 v156, 0, 32, vcc
	v_ldexp_f32 v155, v155, v156
	v_log_f32_e32 v155, v155
	s_nop 0
	v_mul_f32_e32 v156, 0x3f317217, v155
	v_fma_f32 v156, v155, s90, -v156
	v_fmac_f32_e32 v156, 0x3377d1cf, v155
	v_fmac_f32_e32 v156, 0x3f317217, v155
	v_cmp_lt_f32_e64 s[6:7], |v155|, s91
	s_nop 1
	v_cndmask_b32_e64 v155, v155, v156, s[6:7]
	v_cndmask_b32_e32 v156, 0, v222, vcc
	v_sub_f32_e32 v155, v155, v156
	v_pk_add_f32 v[152:153], v[152:153], v[154:155] neg_lo:[0,1] neg_hi:[0,1]
	v_fma_f32 v155, v40, v202, v136
	v_min_f32_e32 v154, 0, v155
	v_mul_f32_e64 v155, |v155|, s88
	v_exp_f32_e32 v155, v155
	v_pk_mul_f32 v[152:153], v[152:153], s[28:29] op_sel_hi:[1,0]
	v_add_f32_e32 v155, 1.0, v155
	v_cmp_gt_f32_e32 vcc, s89, v155
	v_cvt_pk_bf16_f32 v152, v152, v153
	s_nop 0
	v_cndmask_b32_e64 v156, 0, 32, vcc
	v_ldexp_f32 v155, v155, v156
	v_log_f32_e32 v155, v155
	s_nop 0
	v_mul_f32_e32 v156, 0x3f317217, v155
	v_fma_f32 v156, v155, s90, -v156
	v_fmac_f32_e32 v156, 0x3377d1cf, v155
	v_fmac_f32_e32 v156, 0x3f317217, v155
	v_cmp_lt_f32_e64 s[6:7], |v155|, s91
	s_nop 1
	v_cndmask_b32_e64 v155, v155, v156, s[6:7]
	v_cndmask_b32_e32 v156, 0, v222, vcc
	v_sub_f32_e32 v156, v155, v156
	v_min_f32_e32 v155, 0, v157
	v_mul_f32_e64 v157, |v157|, s88
	v_exp_f32_e32 v157, v157
	s_nop 0
	v_add_f32_e32 v157, 1.0, v157
	v_cmp_gt_f32_e32 vcc, s89, v157
	s_nop 1
	v_cndmask_b32_e64 v164, 0, 32, vcc
	v_ldexp_f32 v157, v157, v164
	v_log_f32_e32 v157, v157
	s_nop 0
	v_mul_f32_e32 v164, 0x3f317217, v157
	v_fma_f32 v164, v157, s90, -v164
	v_fmac_f32_e32 v164, 0x3377d1cf, v157
	v_fmac_f32_e32 v164, 0x3f317217, v157
	v_cmp_lt_f32_e64 s[6:7], |v157|, s91
	s_nop 1
	v_cndmask_b32_e64 v157, v157, v164, s[6:7]
	v_cndmask_b32_e32 v164, 0, v222, vcc
	v_sub_f32_e32 v157, v157, v164
	v_pk_add_f32 v[154:155], v[154:155], v[156:157] neg_lo:[0,1] neg_hi:[0,1]
	v_fma_f32 v157, v34, v202, v130
	v_min_f32_e32 v156, 0, v157
	v_mul_f32_e64 v157, |v157|, s88
	v_exp_f32_e32 v157, v157
	v_pk_mul_f32 v[154:155], v[154:155], s[28:29] op_sel_hi:[1,0]
	v_add_f32_e32 v157, 1.0, v157
	v_cmp_gt_f32_e32 vcc, s89, v157
	v_cvt_pk_bf16_f32 v153, v154, v155
	s_nop 0
	v_cndmask_b32_e64 v164, 0, 32, vcc
	v_ldexp_f32 v157, v157, v164
	v_log_f32_e32 v157, v157
	s_nop 0
	v_mul_f32_e32 v164, 0x3f317217, v157
	v_fma_f32 v164, v157, s90, -v164
	v_fmac_f32_e32 v164, 0x3377d1cf, v157
	v_fmac_f32_e32 v164, 0x3f317217, v157
	v_cmp_lt_f32_e64 s[6:7], |v157|, s91
	s_nop 1
	v_cndmask_b32_e64 v157, v157, v164, s[6:7]
	v_cndmask_b32_e32 v164, 0, v222, vcc
	v_sub_f32_e32 v164, v157, v164
	v_min_f32_e32 v157, 0, v165
	v_mul_f32_e64 v165, |v165|, s88
	v_exp_f32_e32 v165, v165
	s_nop 0
	v_add_f32_e32 v165, 1.0, v165
	v_cmp_gt_f32_e32 vcc, s89, v165
	s_nop 1
	v_cndmask_b32_e64 v166, 0, 32, vcc
	v_ldexp_f32 v165, v165, v166
	v_log_f32_e32 v165, v165
	s_nop 0
	v_mul_f32_e32 v166, 0x3f317217, v165
	v_fma_f32 v166, v165, s90, -v166
	v_fmac_f32_e32 v166, 0x3377d1cf, v165
	v_fmac_f32_e32 v166, 0x3f317217, v165
	v_cmp_lt_f32_e64 s[6:7], |v165|, s91
	s_nop 1
	v_cndmask_b32_e64 v165, v165, v166, s[6:7]
	v_cndmask_b32_e32 v166, 0, v222, vcc
	v_sub_f32_e32 v165, v165, v166
	v_pk_add_f32 v[156:157], v[156:157], v[164:165] neg_lo:[0,1] neg_hi:[0,1]
	v_fma_f32 v165, v36, v202, v132
	v_min_f32_e32 v164, 0, v165
	v_mul_f32_e64 v165, |v165|, s88
	v_exp_f32_e32 v165, v165
	v_pk_mul_f32 v[156:157], v[156:157], s[28:29] op_sel_hi:[1,0]
	v_add_f32_e32 v165, 1.0, v165
	v_cmp_gt_f32_e32 vcc, s89, v165
	v_cvt_pk_bf16_f32 v154, v156, v157
	v_add_u32_e32 v156, 0x90, v150
	v_cndmask_b32_e64 v166, 0, 32, vcc
	v_ldexp_f32 v165, v165, v166
	v_log_f32_e32 v165, v165
	v_ashrrev_i32_e32 v157, 31, v156
	v_lshlrev_b64 v[156:157], 9, v[156:157]
	v_lshl_add_u64 v[156:157], s[24:25], 0, v[156:157]
	v_mul_f32_e32 v166, 0x3f317217, v165
	v_fma_f32 v166, v165, s90, -v166
	v_fmac_f32_e32 v166, 0x3377d1cf, v165
	v_fmac_f32_e32 v166, 0x3f317217, v165
	v_cmp_lt_f32_e64 s[6:7], |v165|, s91
	v_lshl_add_u64 v[156:157], v[156:157], 0, v[184:185]
	s_nop 0
	v_cndmask_b32_e64 v165, v165, v166, s[6:7]
	v_cndmask_b32_e32 v166, 0, v222, vcc
	v_sub_f32_e32 v166, v165, v166
	v_min_f32_e32 v165, 0, v167
	v_mul_f32_e64 v167, |v167|, s88
	v_exp_f32_e32 v167, v167
	s_nop 0
	v_add_f32_e32 v167, 1.0, v167
	v_cmp_gt_f32_e32 vcc, s89, v167
	s_nop 1
	v_cndmask_b32_e64 v168, 0, 32, vcc
	v_ldexp_f32 v167, v167, v168
	v_log_f32_e32 v167, v167
	s_nop 0
	v_mul_f32_e32 v168, 0x3f317217, v167
	v_fma_f32 v168, v167, s90, -v168
	v_fmac_f32_e32 v168, 0x3377d1cf, v167
	v_fmac_f32_e32 v168, 0x3f317217, v167
	v_cmp_lt_f32_e64 s[6:7], |v167|, s91
	s_nop 1
	v_cndmask_b32_e64 v167, v167, v168, s[6:7]
	v_cndmask_b32_e32 v168, 0, v222, vcc
	v_sub_f32_e32 v167, v167, v168
	v_pk_add_f32 v[164:165], v[164:165], v[166:167] neg_lo:[0,1] neg_hi:[0,1]
	v_fma_f32 v167, v21, v198, v133
	v_pk_mul_f32 v[164:165], v[164:165], s[28:29] op_sel_hi:[1,0]
	v_fmac_f32_e32 v133, v5, v196
	v_cvt_pk_bf16_f32 v155, v164, v165
	ds_write_b128 v160, v[146:149]
	ds_write_b128 v161, v[152:155]
	ds_read_b128 v[146:149], v163
	ds_read_b128 v[152:155], v163 offset:1024
	v_fma_f32 v165, v19, v198, v131
	s_waitcnt lgkmcnt(1)
; __device__ __forceinline__ v4u pack8(const f32x4 a, const f32x4 b) { v4u w; w.x = pk2(a[0], a[1]); w.y = pk2(a[2], a[3]); w.z = pk2(b[0], b[1]); w.w = pk2(b[2], b[3]); return w; }
; __device__ __forceinline__ float fast_exp(float x) { return __builtin_amdgcn_exp2f(x * LOG2E); }
;     __device__ __forceinline__ void operator()(const f32x4 (&acc)[2][2][4][2], const pg8::Unit& u, int wr, int wc, int fr, int fq) const {
;     ...
;             for (int ai = 0; ai < 2; ++ai)
; #pragma unroll
;                 for (int m = 0; m < 4; ++m) {
;                     const int rowa = 256 * pm + 128 * ai + 64 * wr + 16 * m + tt.rr;
;                     const float rs = rs8[ai][m];
;                     v4u pk[2];
; #pragma unroll
;                     for (int bj = 0; bj < 2; ++bj) {
;                         f32x4 r2[2];
; #pragma unroll
;                         for (int n = 0; n < 2; ++n) {
;                             const f32x4 z = acc[ai][bj][m][n] * rs + bg[bj][n];
; #pragma unroll
;                             for (int j = 0; j < 4; ++j) { const float az = fabsf(z[j]); r2[n][j] = (fminf(z[j], 0.f) - __logf(1.0f + fast_exp(-az))) * (1.0f / 16.0f); }
;                         }
;                         pk[bj] = pack8(r2[0], r2[1]);
;                     }
;                     v4u a, b; tt.bf(pk[0], pk[1], a, b);
;                     bf16* d = (bf16*)(ws + WS_LOGA) + (size_t)rowa * 256 + 64 * wc + 8 * tt.p; *(v4u*)d = a; *(v4u*)(d + 8 * 256) = b;
	global_store_dwordx4 v[156:157], v[146:149], off sc1
	s_nop 1
	v_add_co_u32_e32 v146, vcc, s92, v156
	v_fma_f32 v149, v31, v198, v143
	s_nop 0
	v_addc_co_u32_e32 v147, vcc, 0, v157, vcc
	s_waitcnt lgkmcnt(0)
	global_store_dwordx4 v[146:147], v[152:155], off sc1
	v_fma_f32 v147, v30, v198, v142
	v_min_f32_e32 v146, 0, v147
	v_mul_f32_e64 v147, |v147|, s88
	v_exp_f32_e32 v147, v147
	v_fma_f32 v153, v33, v198, v145
	v_fma_f32 v155, v27, v198, v139
	v_fma_f32 v157, v29, v198, v141
	v_add_f32_e32 v147, 1.0, v147
	v_cmp_gt_f32_e32 vcc, s89, v147
	v_fmac_f32_e32 v145, v17, v196
	v_fmac_f32_e32 v141, v13, v196
	v_cndmask_b32_e64 v148, 0, 32, vcc
	v_ldexp_f32 v147, v147, v148
	v_log_f32_e32 v147, v147
	s_nop 0
	v_mul_f32_e32 v148, 0x3f317217, v147
	v_fma_f32 v148, v147, s90, -v148
	v_fmac_f32_e32 v148, 0x3377d1cf, v147
	v_fmac_f32_e32 v148, 0x3f317217, v147
	v_cmp_lt_f32_e64 s[6:7], |v147|, s91
	s_nop 1
	v_cndmask_b32_e64 v147, v147, v148, s[6:7]
	v_cndmask_b32_e32 v148, 0, v222, vcc
	v_sub_f32_e32 v148, v147, v148
	v_min_f32_e32 v147, 0, v149
	v_mul_f32_e64 v149, |v149|, s88
	v_exp_f32_e32 v149, v149
	s_nop 0
	v_add_f32_e32 v149, 1.0, v149
	v_cmp_gt_f32_e32 vcc, s89, v149
	s_nop 1
	v_cndmask_b32_e64 v152, 0, 32, vcc
	v_ldexp_f32 v149, v149, v152
	v_log_f32_e32 v149, v149
	s_nop 0
	v_mul_f32_e32 v152, 0x3f317217, v149
	v_fma_f32 v152, v149, s90, -v152
	v_fmac_f32_e32 v152, 0x3377d1cf, v149
	v_fmac_f32_e32 v152, 0x3f317217, v149
	v_cmp_lt_f32_e64 s[6:7], |v149|, s91
	s_nop 1
	v_cndmask_b32_e64 v149, v149, v152, s[6:7]
	v_cndmask_b32_e32 v152, 0, v222, vcc
	v_sub_f32_e32 v149, v149, v152
	v_pk_add_f32 v[146:147], v[146:147], v[148:149] neg_lo:[0,1] neg_hi:[0,1]
	v_fma_f32 v149, v32, v198, v144
	v_min_f32_e32 v148, 0, v149
	v_mul_f32_e64 v149, |v149|, s88
	v_exp_f32_e32 v149, v149
	v_pk_mul_f32 v[146:147], v[146:147], s[28:29] op_sel_hi:[1,0]
	v_fma_f32 v144, v16, v196, v144
	v_cvt_pk_bf16_f32 v146, v146, v147
	v_add_f32_e32 v149, 1.0, v149
	v_cmp_gt_f32_e32 vcc, s89, v149
	s_nop 1
	v_cndmask_b32_e64 v152, 0, 32, vcc
	v_ldexp_f32 v149, v149, v152
	v_log_f32_e32 v149, v149
	s_nop 0
	v_mul_f32_e32 v152, 0x3f317217, v149
	v_fma_f32 v152, v149, s90, -v152
	v_fmac_f32_e32 v152, 0x3377d1cf, v149
	v_fmac_f32_e32 v152, 0x3f317217, v149
	v_cmp_lt_f32_e64 s[6:7], |v149|, s91
	s_nop 1
	v_cndmask_b32_e64 v149, v149, v152, s[6:7]
	v_cndmask_b32_e32 v152, 0, v222, vcc
	v_sub_f32_e32 v152, v149, v152
	v_min_f32_e32 v149, 0, v153
	v_mul_f32_e64 v153, |v153|, s88
	v_exp_f32_e32 v153, v153
	s_nop 0
	v_add_f32_e32 v153, 1.0, v153
	v_cmp_gt_f32_e32 vcc, s89, v153
	s_nop 1
	v_cndmask_b32_e64 v154, 0, 32, vcc
	v_ldexp_f32 v153, v153, v154
	v_log_f32_e32 v153, v153
	s_nop 0
	v_mul_f32_e32 v154, 0x3f317217, v153
	v_fma_f32 v154, v153, s90, -v154
	v_fmac_f32_e32 v154, 0x3377d1cf, v153
	v_fmac_f32_e32 v154, 0x3f317217, v153
	v_cmp_lt_f32_e64 s[6:7], |v153|, s91
	s_nop 1
	v_cndmask_b32_e64 v153, v153, v154, s[6:7]
	v_cndmask_b32_e32 v154, 0, v222, vcc
	v_sub_f32_e32 v153, v153, v154
	v_pk_add_f32 v[148:149], v[148:149], v[152:153] neg_lo:[0,1] neg_hi:[0,1]
	v_fma_f32 v153, v26, v198, v138
	v_min_f32_e32 v152, 0, v153
	v_mul_f32_e64 v153, |v153|, s88
	v_exp_f32_e32 v153, v153
	v_pk_mul_f32 v[148:149], v[148:149], s[28:29] op_sel_hi:[1,0]
	v_add_f32_e32 v153, 1.0, v153
	v_cmp_gt_f32_e32 vcc, s89, v153
	v_cvt_pk_bf16_f32 v147, v148, v149
	s_nop 0
	v_cndmask_b32_e64 v154, 0, 32, vcc
	v_ldexp_f32 v153, v153, v154
	v_log_f32_e32 v153, v153
	s_nop 0
	v_mul_f32_e32 v154, 0x3f317217, v153
	v_fma_f32 v154, v153, s90, -v154
	v_fmac_f32_e32 v154, 0x3377d1cf, v153
	v_fmac_f32_e32 v154, 0x3f317217, v153
	v_cmp_lt_f32_e64 s[6:7], |v153|, s91
	s_nop 1
	v_cndmask_b32_e64 v153, v153, v154, s[6:7]
	v_cndmask_b32_e32 v154, 0, v222, vcc
	v_sub_f32_e32 v154, v153, v154
	v_min_f32_e32 v153, 0, v155
	v_mul_f32_e64 v155, |v155|, s88
	v_exp_f32_e32 v155, v155
	s_nop 0
	v_add_f32_e32 v155, 1.0, v155
	v_cmp_gt_f32_e32 vcc, s89, v155
	s_nop 1
	v_cndmask_b32_e64 v156, 0, 32, vcc
	v_ldexp_f32 v155, v155, v156
	v_log_f32_e32 v155, v155
	s_nop 0
	v_mul_f32_e32 v156, 0x3f317217, v155
	v_fma_f32 v156, v155, s90, -v156
	v_fmac_f32_e32 v156, 0x3377d1cf, v155
	v_fmac_f32_e32 v156, 0x3f317217, v155
	v_cmp_lt_f32_e64 s[6:7], |v155|, s91
	s_nop 1
	v_cndmask_b32_e64 v155, v155, v156, s[6:7]
	v_cndmask_b32_e32 v156, 0, v222, vcc
	v_sub_f32_e32 v155, v155, v156
	v_pk_add_f32 v[152:153], v[152:153], v[154:155] neg_lo:[0,1] neg_hi:[0,1]
	v_fma_f32 v155, v28, v198, v140
	v_min_f32_e32 v154, 0, v155
	v_mul_f32_e64 v155, |v155|, s88
	v_exp_f32_e32 v155, v155
	v_pk_mul_f32 v[152:153], v[152:153], s[28:29] op_sel_hi:[1,0]
	v_add_f32_e32 v155, 1.0, v155
	v_cmp_gt_f32_e32 vcc, s89, v155
	v_cvt_pk_bf16_f32 v148, v152, v153
	v_fma_f32 v153, v22, v198, v134
	v_cndmask_b32_e64 v156, 0, 32, vcc
	v_ldexp_f32 v155, v155, v156
	v_log_f32_e32 v155, v155
	v_min_f32_e32 v152, 0, v153
	v_mul_f32_e64 v153, |v153|, s88
	v_exp_f32_e32 v153, v153
	v_mul_f32_e32 v156, 0x3f317217, v155
	v_fma_f32 v156, v155, s90, -v156
	v_fmac_f32_e32 v156, 0x3377d1cf, v155
	v_fmac_f32_e32 v156, 0x3f317217, v155
	v_cmp_lt_f32_e64 s[6:7], |v155|, s91
	v_add_f32_e32 v153, 1.0, v153
	s_nop 0
	v_cndmask_b32_e64 v155, v155, v156, s[6:7]
	v_cndmask_b32_e32 v156, 0, v222, vcc
	v_sub_f32_e32 v156, v155, v156
	v_min_f32_e32 v155, 0, v157
	v_mul_f32_e64 v157, |v157|, s88
	v_exp_f32_e32 v157, v157
	s_nop 0
	v_add_f32_e32 v157, 1.0, v157
	v_cmp_gt_f32_e32 vcc, s89, v157
	s_nop 1
	v_cndmask_b32_e64 v164, 0, 32, vcc
	v_ldexp_f32 v157, v157, v164
	v_log_f32_e32 v157, v157
	s_nop 0
	v_mul_f32_e32 v164, 0x3f317217, v157
	v_fma_f32 v164, v157, s90, -v164
	v_fmac_f32_e32 v164, 0x3377d1cf, v157
; __device__ __forceinline__ v4u pack8(const f32x4 a, const f32x4 b) { v4u w; w.x = pk2(a[0], a[1]); w.y = pk2(a[2], a[3]); w.z = pk2(b[0], b[1]); w.w = pk2(b[2], b[3]); return w; }
; __device__ __forceinline__ float fast_exp(float x) { return __builtin_amdgcn_exp2f(x * LOG2E); }
;     __device__ __forceinline__ void operator()(const f32x4 (&acc)[2][2][4][2], const pg8::Unit& u, int wr, int wc, int fr, int fq) const {
;     ...
;             for (int ai = 0; ai < 2; ++ai)
; #pragma unroll
;                 for (int m = 0; m < 4; ++m) {
;                     const int rowa = 256 * pm + 128 * ai + 64 * wr + 16 * m + tt.rr;
;                     const float rs = rs8[ai][m];
;                     v4u pk[2];
; #pragma unroll
;                     for (int bj = 0; bj < 2; ++bj) {
;                         f32x4 r2[2];
; #pragma unroll
;                         for (int n = 0; n < 2; ++n) {
;                             const f32x4 z = acc[ai][bj][m][n] * rs + bg[bj][n];
; #pragma unroll
;                             for (int j = 0; j < 4; ++j) { const float az = fabsf(z[j]); r2[n][j] = (fminf(z[j], 0.f) - __logf(1.0f + fast_exp(-az))) * (1.0f / 16.0f); }
;                         }
;                         pk[bj] = pack8(r2[0], r2[1]);
;                     }
;                     v4u a, b; tt.bf(pk[0], pk[1], a, b);
;                     bf16* d = (bf16*)(ws + WS_LOGA) + (size_t)rowa * 256 + 64 * wc + 8 * tt.p; *(v4u*)d = a; *(v4u*)(d + 8 * 256) = b;
	v_fmac_f32_e32 v164, 0x3f317217, v157
	v_cmp_lt_f32_e64 s[6:7], |v157|, s91
	s_nop 1
	v_cndmask_b32_e64 v157, v157, v164, s[6:7]
	v_cndmask_b32_e32 v164, 0, v222, vcc
	v_sub_f32_e32 v157, v157, v164
	v_pk_add_f32 v[154:155], v[154:155], v[156:157] neg_lo:[0,1] neg_hi:[0,1]
	v_cmp_gt_f32_e32 vcc, s89, v153
	v_pk_mul_f32 v[154:155], v[154:155], s[28:29] op_sel_hi:[1,0]
	v_fma_f32 v157, v25, v198, v137
	v_cvt_pk_bf16_f32 v149, v154, v155
	v_cndmask_b32_e64 v154, 0, 32, vcc
	v_ldexp_f32 v153, v153, v154
	v_log_f32_e32 v153, v153
	v_fma_f32 v155, v23, v198, v135
	v_fmac_f32_e32 v137, v9, v196
	v_mul_f32_e32 v154, 0x3f317217, v153
	v_fma_f32 v154, v153, s90, -v154
	v_fmac_f32_e32 v154, 0x3377d1cf, v153
	v_fmac_f32_e32 v154, 0x3f317217, v153
	v_cmp_lt_f32_e64 s[6:7], |v153|, s91
	s_nop 1
	v_cndmask_b32_e64 v153, v153, v154, s[6:7]
	v_cndmask_b32_e32 v154, 0, v222, vcc
	v_sub_f32_e32 v154, v153, v154
	v_min_f32_e32 v153, 0, v155
	v_mul_f32_e64 v155, |v155|, s88
	v_exp_f32_e32 v155, v155
	s_nop 0
	v_add_f32_e32 v155, 1.0, v155
	v_cmp_gt_f32_e32 vcc, s89, v155
	s_nop 1
	v_cndmask_b32_e64 v156, 0, 32, vcc
	v_ldexp_f32 v155, v155, v156
	v_log_f32_e32 v155, v155
	s_nop 0
	v_mul_f32_e32 v156, 0x3f317217, v155
	v_fma_f32 v156, v155, s90, -v156
	v_fmac_f32_e32 v156, 0x3377d1cf, v155
	v_fmac_f32_e32 v156, 0x3f317217, v155
	v_cmp_lt_f32_e64 s[6:7], |v155|, s91
	s_nop 1
	v_cndmask_b32_e64 v155, v155, v156, s[6:7]
	v_cndmask_b32_e32 v156, 0, v222, vcc
	v_sub_f32_e32 v155, v155, v156
	v_pk_add_f32 v[152:153], v[152:153], v[154:155] neg_lo:[0,1] neg_hi:[0,1]
	v_fma_f32 v155, v24, v198, v136
	v_min_f32_e32 v154, 0, v155
	v_mul_f32_e64 v155, |v155|, s88
	v_exp_f32_e32 v155, v155
	v_pk_mul_f32 v[152:153], v[152:153], s[28:29] op_sel_hi:[1,0]
	v_fma_f32 v136, v8, v196, v136
	v_cvt_pk_bf16_f32 v152, v152, v153
	v_add_f32_e32 v155, 1.0, v155
	v_cmp_gt_f32_e32 vcc, s89, v155
	s_nop 1
	v_cndmask_b32_e64 v156, 0, 32, vcc
	v_ldexp_f32 v155, v155, v156
	v_log_f32_e32 v155, v155
	s_nop 0
	v_mul_f32_e32 v156, 0x3f317217, v155
	v_fma_f32 v156, v155, s90, -v156
	v_fmac_f32_e32 v156, 0x3377d1cf, v155
	v_fmac_f32_e32 v156, 0x3f317217, v155
	v_cmp_lt_f32_e64 s[6:7], |v155|, s91
	s_nop 1
	v_cndmask_b32_e64 v155, v155, v156, s[6:7]
	v_cndmask_b32_e32 v156, 0, v222, vcc
	v_sub_f32_e32 v156, v155, v156
	v_min_f32_e32 v155, 0, v157
	v_mul_f32_e64 v157, |v157|, s88
	v_exp_f32_e32 v157, v157
	s_nop 0
	v_add_f32_e32 v157, 1.0, v157
	v_cmp_gt_f32_e32 vcc, s89, v157
	s_nop 1
	v_cndmask_b32_e64 v164, 0, 32, vcc
	v_ldexp_f32 v157, v157, v164
	v_log_f32_e32 v157, v157
	s_nop 0
	v_mul_f32_e32 v164, 0x3f317217, v157
	v_fma_f32 v164, v157, s90, -v164
	v_fmac_f32_e32 v164, 0x3377d1cf, v157
	v_fmac_f32_e32 v164, 0x3f317217, v157
	v_cmp_lt_f32_e64 s[6:7], |v157|, s91
	s_nop 1
	v_cndmask_b32_e64 v157, v157, v164, s[6:7]
	v_cndmask_b32_e32 v164, 0, v222, vcc
	v_sub_f32_e32 v157, v157, v164
	v_pk_add_f32 v[154:155], v[154:155], v[156:157] neg_lo:[0,1] neg_hi:[0,1]
	v_fma_f32 v157, v18, v198, v130
	v_min_f32_e32 v156, 0, v157
	v_mul_f32_e64 v157, |v157|, s88
	v_exp_f32_e32 v157, v157
	v_pk_mul_f32 v[154:155], v[154:155], s[28:29] op_sel_hi:[1,0]
	v_add_f32_e32 v157, 1.0, v157
	v_cmp_gt_f32_e32 vcc, s89, v157
	v_cvt_pk_bf16_f32 v153, v154, v155
	s_nop 0
	v_cndmask_b32_e64 v164, 0, 32, vcc
	v_ldexp_f32 v157, v157, v164
	v_log_f32_e32 v157, v157
	s_nop 0
	v_mul_f32_e32 v164, 0x3f317217, v157
	v_fma_f32 v164, v157, s90, -v164
	v_fmac_f32_e32 v164, 0x3377d1cf, v157
	v_fmac_f32_e32 v164, 0x3f317217, v157
	v_cmp_lt_f32_e64 s[6:7], |v157|, s91
	s_nop 1
	v_cndmask_b32_e64 v157, v157, v164, s[6:7]
	v_cndmask_b32_e32 v164, 0, v222, vcc
	v_sub_f32_e32 v164, v157, v164
	v_min_f32_e32 v157, 0, v165
	v_mul_f32_e64 v165, |v165|, s88
	v_exp_f32_e32 v165, v165
	s_nop 0
	v_add_f32_e32 v165, 1.0, v165
	v_cmp_gt_f32_e32 vcc, s89, v165
	s_nop 1
	v_cndmask_b32_e64 v166, 0, 32, vcc
	v_ldexp_f32 v165, v165, v166
	v_log_f32_e32 v165, v165
	s_nop 0
	v_mul_f32_e32 v166, 0x3f317217, v165
	v_fma_f32 v166, v165, s90, -v166
	v_fmac_f32_e32 v166, 0x3377d1cf, v165
	v_fmac_f32_e32 v166, 0x3f317217, v165
	v_cmp_lt_f32_e64 s[6:7], |v165|, s91
	s_nop 1
	v_cndmask_b32_e64 v165, v165, v166, s[6:7]
	v_cndmask_b32_e32 v166, 0, v222, vcc
	v_sub_f32_e32 v165, v165, v166
	v_pk_add_f32 v[156:157], v[156:157], v[164:165] neg_lo:[0,1] neg_hi:[0,1]
	v_fma_f32 v165, v20, v198, v132
	v_min_f32_e32 v164, 0, v165
	v_mul_f32_e64 v165, |v165|, s88
	v_exp_f32_e32 v165, v165
	v_pk_mul_f32 v[156:157], v[156:157], s[28:29] op_sel_hi:[1,0]
	v_add_f32_e32 v165, 1.0, v165
	v_cmp_gt_f32_e32 vcc, s89, v165
	v_cvt_pk_bf16_f32 v154, v156, v157
	v_add_u32_e32 v156, 0xa0, v150
	v_cndmask_b32_e64 v166, 0, 32, vcc
	v_ldexp_f32 v165, v165, v166
	v_log_f32_e32 v165, v165
	v_ashrrev_i32_e32 v157, 31, v156
	v_lshlrev_b64 v[156:157], 9, v[156:157]
	v_lshl_add_u64 v[156:157], s[24:25], 0, v[156:157]
	v_mul_f32_e32 v166, 0x3f317217, v165
	v_fma_f32 v166, v165, s90, -v166
	v_fmac_f32_e32 v166, 0x3377d1cf, v165
	v_fmac_f32_e32 v166, 0x3f317217, v165
	v_cmp_lt_f32_e64 s[6:7], |v165|, s91
	v_lshl_add_u64 v[156:157], v[156:157], 0, v[184:185]
	s_nop 0
	v_cndmask_b32_e64 v165, v165, v166, s[6:7]
	v_cndmask_b32_e32 v166, 0, v222, vcc
	v_sub_f32_e32 v166, v165, v166
	v_min_f32_e32 v165, 0, v167
	v_mul_f32_e64 v167, |v167|, s88
	v_exp_f32_e32 v167, v167
	s_nop 0
	v_add_f32_e32 v167, 1.0, v167
	v_cmp_gt_f32_e32 vcc, s89, v167
	s_nop 1
	v_cndmask_b32_e64 v168, 0, 32, vcc
	v_ldexp_f32 v167, v167, v168
	v_log_f32_e32 v167, v167
	s_nop 0
	v_mul_f32_e32 v168, 0x3f317217, v167
	v_fma_f32 v168, v167, s90, -v168
	v_fmac_f32_e32 v168, 0x3377d1cf, v167
	v_fmac_f32_e32 v168, 0x3f317217, v167
	v_cmp_lt_f32_e64 s[6:7], |v167|, s91
	s_nop 1
	v_cndmask_b32_e64 v167, v167, v168, s[6:7]
	v_cndmask_b32_e32 v168, 0, v222, vcc
	v_sub_f32_e32 v167, v167, v168
	v_pk_add_f32 v[164:165], v[164:165], v[166:167] neg_lo:[0,1] neg_hi:[0,1]
	s_nop 0
	v_pk_mul_f32 v[164:165], v[164:165], s[28:29] op_sel_hi:[1,0]
	s_nop 0
	v_cvt_pk_bf16_f32 v155, v164, v165
	ds_write_b128 v160, v[146:149]
	ds_write_b128 v161, v[152:155]
	ds_read_b128 v[146:149], v163
	ds_read_b128 v[152:155], v163 offset:1024
	s_waitcnt lgkmcnt(1)
; __device__ __forceinline__ v4u pack8(const f32x4 a, const f32x4 b) { v4u w; w.x = pk2(a[0], a[1]); w.y = pk2(a[2], a[3]); w.z = pk2(b[0], b[1]); w.w = pk2(b[2], b[3]); return w; }
; __device__ __forceinline__ float fast_exp(float x) { return __builtin_amdgcn_exp2f(x * LOG2E); }
;     __device__ __forceinline__ void operator()(const f32x4 (&acc)[2][2][4][2], const pg8::Unit& u, int wr, int wc, int fr, int fq) const {
;     ...
;             for (int ai = 0; ai < 2; ++ai)
; #pragma unroll
;                 for (int m = 0; m < 4; ++m) {
;                     const int rowa = 256 * pm + 128 * ai + 64 * wr + 16 * m + tt.rr;
;                     const float rs = rs8[ai][m];
;                     v4u pk[2];
; #pragma unroll
;                     for (int bj = 0; bj < 2; ++bj) {
;                         f32x4 r2[2];
; #pragma unroll
;                         for (int n = 0; n < 2; ++n) {
;                             const f32x4 z = acc[ai][bj][m][n] * rs + bg[bj][n];
; #pragma unroll
;                             for (int j = 0; j < 4; ++j) { const float az = fabsf(z[j]); r2[n][j] = (fminf(z[j], 0.f) - __logf(1.0f + fast_exp(-az))) * (1.0f / 16.0f); }
;                         }
;                         pk[bj] = pack8(r2[0], r2[1]);
;                     }
;                     v4u a, b; tt.bf(pk[0], pk[1], a, b);
;                     bf16* d = (bf16*)(ws + WS_LOGA) + (size_t)rowa * 256 + 64 * wc + 8 * tt.p; *(v4u*)d = a; *(v4u*)(d + 8 * 256) = b;
	global_store_dwordx4 v[156:157], v[146:149], off sc1
	s_nop 1
	v_add_co_u32_e32 v146, vcc, s92, v156
	s_nop 1
	v_addc_co_u32_e32 v147, vcc, 0, v157, vcc
	s_waitcnt lgkmcnt(0)
	global_store_dwordx4 v[146:147], v[152:155], off sc1
	v_fma_f32 v146, v14, v196, v142
	v_min_f32_e32 v142, 0, v146
	v_mul_f32_e64 v146, |v146|, s88
	v_exp_f32_e32 v146, v146
	s_nop 0
	v_add_f32_e32 v146, 1.0, v146
	v_cmp_gt_f32_e32 vcc, s89, v146
	s_nop 1
	v_cndmask_b32_e64 v147, 0, 32, vcc
	v_ldexp_f32 v146, v146, v147
	v_log_f32_e32 v146, v146
	s_nop 0
	v_mul_f32_e32 v147, 0x3f317217, v146
	v_fma_f32 v147, v146, s90, -v147
	v_fmac_f32_e32 v147, 0x3377d1cf, v146
	v_fmac_f32_e32 v147, 0x3f317217, v146
	v_cmp_lt_f32_e64 s[6:7], |v146|, s91
	s_nop 1
	v_cndmask_b32_e64 v146, v146, v147, s[6:7]
	v_cndmask_b32_e32 v147, 0, v222, vcc
	v_sub_f32_e32 v146, v146, v147
	v_fma_f32 v147, v15, v196, v143
	v_min_f32_e32 v143, 0, v147
	v_mul_f32_e64 v147, |v147|, s88
	v_exp_f32_e32 v147, v147
	s_nop 0
	v_add_f32_e32 v147, 1.0, v147
	v_cmp_gt_f32_e32 vcc, s89, v147
	s_nop 1
	v_cndmask_b32_e64 v148, 0, 32, vcc
	v_ldexp_f32 v147, v147, v148
	v_log_f32_e32 v147, v147
	s_nop 0
	v_mul_f32_e32 v148, 0x3f317217, v147
	v_fma_f32 v148, v147, s90, -v148
	v_fmac_f32_e32 v148, 0x3377d1cf, v147
	v_fmac_f32_e32 v148, 0x3f317217, v147
	v_cmp_lt_f32_e64 s[6:7], |v147|, s91
	s_nop 1
	v_cndmask_b32_e64 v147, v147, v148, s[6:7]
	v_cndmask_b32_e32 v148, 0, v222, vcc
	v_sub_f32_e32 v147, v147, v148
	v_pk_add_f32 v[142:143], v[142:143], v[146:147] neg_lo:[0,1] neg_hi:[0,1]
	v_min_f32_e32 v146, 0, v144
	v_mul_f32_e64 v144, |v144|, s88
	v_exp_f32_e32 v144, v144
	v_pk_mul_f32 v[142:143], v[142:143], s[28:29] op_sel_hi:[1,0]
	v_add_f32_e32 v144, 1.0, v144
	v_cmp_gt_f32_e32 vcc, s89, v144
	s_nop 1
	v_cndmask_b32_e64 v147, 0, 32, vcc
	v_ldexp_f32 v144, v144, v147
	v_log_f32_e32 v144, v144
	s_nop 0
	v_mul_f32_e32 v147, 0x3f317217, v144
	v_fma_f32 v147, v144, s90, -v147
	v_fmac_f32_e32 v147, 0x3377d1cf, v144
	v_fmac_f32_e32 v147, 0x3f317217, v144
	v_cmp_lt_f32_e64 s[6:7], |v144|, s91
	s_nop 1
	v_cndmask_b32_e64 v144, v144, v147, s[6:7]
	v_cndmask_b32_e32 v147, 0, v222, vcc
	v_sub_f32_e32 v144, v144, v147
	v_min_f32_e32 v147, 0, v145
	v_mul_f32_e64 v145, |v145|, s88
	v_exp_f32_e32 v145, v145
	s_nop 0
	v_add_f32_e32 v145, 1.0, v145
	v_cmp_gt_f32_e32 vcc, s89, v145
	s_nop 1
	v_cndmask_b32_e64 v148, 0, 32, vcc
	v_ldexp_f32 v145, v145, v148
	v_log_f32_e32 v145, v145
	s_nop 0
	v_mul_f32_e32 v148, 0x3f317217, v145
	v_fma_f32 v148, v145, s90, -v148
	v_fmac_f32_e32 v148, 0x3377d1cf, v145
	v_fmac_f32_e32 v148, 0x3f317217, v145
	v_cmp_lt_f32_e64 s[6:7], |v145|, s91
	s_nop 1
	v_cndmask_b32_e64 v145, v145, v148, s[6:7]
	v_cndmask_b32_e32 v148, 0, v222, vcc
	v_sub_f32_e32 v145, v145, v148
	v_pk_add_f32 v[144:145], v[146:147], v[144:145] neg_lo:[0,1] neg_hi:[0,1]
	v_fma_f32 v146, v10, v196, v138
	v_min_f32_e32 v138, 0, v146
	v_mul_f32_e64 v146, |v146|, s88
	v_exp_f32_e32 v146, v146
	v_pk_mul_f32 v[144:145], v[144:145], s[28:29] op_sel_hi:[1,0]
	v_add_f32_e32 v146, 1.0, v146
	v_cmp_gt_f32_e32 vcc, s89, v146
	s_nop 1
	v_cndmask_b32_e64 v147, 0, 32, vcc
	v_ldexp_f32 v146, v146, v147
	v_log_f32_e32 v146, v146
	s_nop 0
	v_mul_f32_e32 v147, 0x3f317217, v146
	v_fma_f32 v147, v146, s90, -v147
	v_fmac_f32_e32 v147, 0x3377d1cf, v146
	v_fmac_f32_e32 v147, 0x3f317217, v146
	v_cmp_lt_f32_e64 s[6:7], |v146|, s91
	s_nop 1
	v_cndmask_b32_e64 v146, v146, v147, s[6:7]
	v_cndmask_b32_e32 v147, 0, v222, vcc
	v_sub_f32_e32 v146, v146, v147
	v_fma_f32 v147, v11, v196, v139
	v_min_f32_e32 v139, 0, v147
	v_mul_f32_e64 v147, |v147|, s88
	v_exp_f32_e32 v147, v147
	s_nop 0
	v_add_f32_e32 v147, 1.0, v147
	v_cmp_gt_f32_e32 vcc, s89, v147
	s_nop 1
	v_cndmask_b32_e64 v148, 0, 32, vcc
	v_ldexp_f32 v147, v147, v148
	v_log_f32_e32 v147, v147
	s_nop 0
	v_mul_f32_e32 v148, 0x3f317217, v147
	v_fma_f32 v148, v147, s90, -v148
	v_fmac_f32_e32 v148, 0x3377d1cf, v147
	v_fmac_f32_e32 v148, 0x3f317217, v147
	v_cmp_lt_f32_e64 s[6:7], |v147|, s91
	s_nop 1
	v_cndmask_b32_e64 v147, v147, v148, s[6:7]
	v_cndmask_b32_e32 v148, 0, v222, vcc
	v_sub_f32_e32 v147, v147, v148
	v_pk_add_f32 v[138:139], v[138:139], v[146:147] neg_lo:[0,1] neg_hi:[0,1]
	s_nop 0
	v_pk_mul_f32 v[146:147], v[138:139], s[28:29] op_sel_hi:[1,0]
	v_fma_f32 v139, v12, v196, v140
	v_min_f32_e32 v138, 0, v139
	v_mul_f32_e64 v139, |v139|, s88
	v_exp_f32_e32 v139, v139
	s_nop 0
	v_add_f32_e32 v139, 1.0, v139
	v_cmp_gt_f32_e32 vcc, s89, v139
	s_nop 1
	v_cndmask_b32_e64 v140, 0, 32, vcc
	v_ldexp_f32 v139, v139, v140
	v_log_f32_e32 v139, v139
	s_nop 0
	v_mul_f32_e32 v140, 0x3f317217, v139
	v_fma_f32 v140, v139, s90, -v140
	v_fmac_f32_e32 v140, 0x3377d1cf, v139
	v_fmac_f32_e32 v140, 0x3f317217, v139
	v_cmp_lt_f32_e64 s[6:7], |v139|, s91
	s_nop 1
	v_cndmask_b32_e64 v139, v139, v140, s[6:7]
	v_cndmask_b32_e32 v140, 0, v222, vcc
	v_sub_f32_e32 v140, v139, v140
	v_min_f32_e32 v139, 0, v141
	v_mul_f32_e64 v141, |v141|, s88
	v_exp_f32_e32 v141, v141
	s_nop 0
	v_add_f32_e32 v141, 1.0, v141
	v_cmp_gt_f32_e32 vcc, s89, v141
	s_nop 1
	v_cndmask_b32_e64 v148, 0, 32, vcc
	v_ldexp_f32 v141, v141, v148
	v_log_f32_e32 v141, v141
	s_nop 0
	v_mul_f32_e32 v148, 0x3f317217, v141
	v_fma_f32 v148, v141, s90, -v148
	v_fmac_f32_e32 v148, 0x3377d1cf, v141
	v_fmac_f32_e32 v148, 0x3f317217, v141
	v_cmp_lt_f32_e64 s[6:7], |v141|, s91
	s_nop 1
	v_cndmask_b32_e64 v141, v141, v148, s[6:7]
	v_cndmask_b32_e32 v148, 0, v222, vcc
	v_sub_f32_e32 v141, v141, v148
	v_pk_add_f32 v[138:139], v[138:139], v[140:141] neg_lo:[0,1] neg_hi:[0,1]
	v_cvt_pk_bf16_f32 v140, v146, v147
	v_pk_mul_f32 v[148:149], v[138:139], s[28:29] op_sel_hi:[1,0]
; __device__ __forceinline__ v4u pack8(const f32x4 a, const f32x4 b) { v4u w; w.x = pk2(a[0], a[1]); w.y = pk2(a[2], a[3]); w.z = pk2(b[0], b[1]); w.w = pk2(b[2], b[3]); return w; }
; __device__ __forceinline__ float fast_exp(float x) { return __builtin_amdgcn_exp2f(x * LOG2E); }
;     __device__ __forceinline__ void operator()(const f32x4 (&acc)[2][2][4][2], const pg8::Unit& u, int wr, int wc, int fr, int fq) const {
;     ...
;             for (int ai = 0; ai < 2; ++ai)
; #pragma unroll
;                 for (int m = 0; m < 4; ++m) {
;                     const int rowa = 256 * pm + 128 * ai + 64 * wr + 16 * m + tt.rr;
;                     const float rs = rs8[ai][m];
;                     v4u pk[2];
; #pragma unroll
;                     for (int bj = 0; bj < 2; ++bj) {
;                         f32x4 r2[2];
; #pragma unroll
;                         for (int n = 0; n < 2; ++n) {
;                             const f32x4 z = acc[ai][bj][m][n] * rs + bg[bj][n];
; #pragma unroll
;                             for (int j = 0; j < 4; ++j) { const float az = fabsf(z[j]); r2[n][j] = (fminf(z[j], 0.f) - __logf(1.0f + fast_exp(-az))) * (1.0f / 16.0f); }
;                         }
;                         pk[bj] = pack8(r2[0], r2[1]);
;                     }
;                     v4u a, b; tt.bf(pk[0], pk[1], a, b);
;                     bf16* d = (bf16*)(ws + WS_LOGA) + (size_t)rowa * 256 + 64 * wc + 8 * tt.p; *(v4u*)d = a; *(v4u*)(d + 8 * 256) = b;
	v_cvt_pk_bf16_f32 v138, v142, v143
	v_fma_f32 v142, v6, v196, v134
	v_min_f32_e32 v134, 0, v142
	v_mul_f32_e64 v142, |v142|, s88
	v_exp_f32_e32 v142, v142
	v_cvt_pk_bf16_f32 v139, v144, v145
	v_cvt_pk_bf16_f32 v141, v148, v149
	v_add_f32_e32 v142, 1.0, v142
	v_cmp_gt_f32_e32 vcc, s89, v142
	s_nop 1
	v_cndmask_b32_e64 v143, 0, 32, vcc
	v_ldexp_f32 v142, v142, v143
	v_log_f32_e32 v142, v142
	s_nop 0
	v_mul_f32_e32 v143, 0x3f317217, v142
	v_fma_f32 v143, v142, s90, -v143
	v_fmac_f32_e32 v143, 0x3377d1cf, v142
	v_fmac_f32_e32 v143, 0x3f317217, v142
	v_cmp_lt_f32_e64 s[6:7], |v142|, s91
	s_nop 1
	v_cndmask_b32_e64 v142, v142, v143, s[6:7]
	v_cndmask_b32_e32 v143, 0, v222, vcc
	v_sub_f32_e32 v142, v142, v143
	v_fma_f32 v143, v7, v196, v135
	v_min_f32_e32 v135, 0, v143
	v_mul_f32_e64 v143, |v143|, s88
	v_exp_f32_e32 v143, v143
	s_nop 0
	v_add_f32_e32 v143, 1.0, v143
	v_cmp_gt_f32_e32 vcc, s89, v143
	s_nop 1
	v_cndmask_b32_e64 v144, 0, 32, vcc
	v_ldexp_f32 v143, v143, v144
	v_log_f32_e32 v143, v143
	s_nop 0
	v_mul_f32_e32 v144, 0x3f317217, v143
	v_fma_f32 v144, v143, s90, -v144
	v_fmac_f32_e32 v144, 0x3377d1cf, v143
	v_fmac_f32_e32 v144, 0x3f317217, v143
	v_cmp_lt_f32_e64 s[6:7], |v143|, s91
	s_nop 1
	v_cndmask_b32_e64 v143, v143, v144, s[6:7]
	v_cndmask_b32_e32 v144, 0, v222, vcc
	v_sub_f32_e32 v143, v143, v144
	v_pk_add_f32 v[134:135], v[134:135], v[142:143] neg_lo:[0,1] neg_hi:[0,1]
	v_min_f32_e32 v142, 0, v136
	v_mul_f32_e64 v136, |v136|, s88
	v_exp_f32_e32 v136, v136
	v_pk_mul_f32 v[134:135], v[134:135], s[28:29] op_sel_hi:[1,0]
	v_add_f32_e32 v136, 1.0, v136
	v_cmp_gt_f32_e32 vcc, s89, v136
	s_nop 1
	v_cndmask_b32_e64 v143, 0, 32, vcc
	v_ldexp_f32 v136, v136, v143
	v_log_f32_e32 v136, v136
	s_nop 0
	v_mul_f32_e32 v143, 0x3f317217, v136
	v_fma_f32 v143, v136, s90, -v143
	v_fmac_f32_e32 v143, 0x3377d1cf, v136
	v_fmac_f32_e32 v143, 0x3f317217, v136
	v_cmp_lt_f32_e64 s[6:7], |v136|, s91
	s_nop 1
	v_cndmask_b32_e64 v136, v136, v143, s[6:7]
	v_cndmask_b32_e32 v143, 0, v222, vcc
	v_sub_f32_e32 v136, v136, v143
	v_min_f32_e32 v143, 0, v137
	v_mul_f32_e64 v137, |v137|, s88
	v_exp_f32_e32 v137, v137
	s_nop 0
	v_add_f32_e32 v137, 1.0, v137
	v_cmp_gt_f32_e32 vcc, s89, v137
	s_nop 1
	v_cndmask_b32_e64 v144, 0, 32, vcc
	v_ldexp_f32 v137, v137, v144
	v_log_f32_e32 v137, v137
	s_nop 0
	v_mul_f32_e32 v144, 0x3f317217, v137
	v_fma_f32 v144, v137, s90, -v144
	v_fmac_f32_e32 v144, 0x3377d1cf, v137
	v_fmac_f32_e32 v144, 0x3f317217, v137
	v_cmp_lt_f32_e64 s[6:7], |v137|, s91
	s_nop 1
	v_cndmask_b32_e64 v137, v137, v144, s[6:7]
	v_cndmask_b32_e32 v144, 0, v222, vcc
	v_sub_f32_e32 v137, v137, v144
	v_pk_add_f32 v[136:137], v[142:143], v[136:137] neg_lo:[0,1] neg_hi:[0,1]
	v_fma_f32 v142, v2, v196, v130
	v_min_f32_e32 v130, 0, v142
	v_mul_f32_e64 v142, |v142|, s88
	v_exp_f32_e32 v142, v142
	v_pk_mul_f32 v[136:137], v[136:137], s[28:29] op_sel_hi:[1,0]
	v_add_f32_e32 v142, 1.0, v142
	v_cmp_gt_f32_e32 vcc, s89, v142
	s_nop 1
	v_cndmask_b32_e64 v143, 0, 32, vcc
	v_ldexp_f32 v142, v142, v143
	v_log_f32_e32 v142, v142
	s_nop 0
	v_mul_f32_e32 v143, 0x3f317217, v142
	v_fma_f32 v143, v142, s90, -v143
	v_fmac_f32_e32 v143, 0x3377d1cf, v142
	v_fmac_f32_e32 v143, 0x3f317217, v142
	v_cmp_lt_f32_e64 s[6:7], |v142|, s91
	s_nop 1
	v_cndmask_b32_e64 v142, v142, v143, s[6:7]
	v_cndmask_b32_e32 v143, 0, v222, vcc
	v_sub_f32_e32 v142, v142, v143
	v_fma_f32 v143, v3, v196, v131
	v_min_f32_e32 v131, 0, v143
	v_mul_f32_e64 v143, |v143|, s88
	v_exp_f32_e32 v143, v143
	s_nop 0
	v_add_f32_e32 v143, 1.0, v143
	v_cmp_gt_f32_e32 vcc, s89, v143
	s_nop 1
	v_cndmask_b32_e64 v144, 0, 32, vcc
	v_ldexp_f32 v143, v143, v144
	v_log_f32_e32 v143, v143
	s_nop 0
	v_mul_f32_e32 v144, 0x3f317217, v143
	v_fma_f32 v144, v143, s90, -v144
	v_fmac_f32_e32 v144, 0x3377d1cf, v143
	v_fmac_f32_e32 v144, 0x3f317217, v143
	v_cmp_lt_f32_e64 s[6:7], |v143|, s91
	s_nop 1
	v_cndmask_b32_e64 v143, v143, v144, s[6:7]
	v_cndmask_b32_e32 v144, 0, v222, vcc
	v_sub_f32_e32 v143, v143, v144
	v_pk_add_f32 v[130:131], v[130:131], v[142:143] neg_lo:[0,1] neg_hi:[0,1]
	s_nop 0
	v_pk_mul_f32 v[142:143], v[130:131], s[28:29] op_sel_hi:[1,0]
	v_fma_f32 v131, v4, v196, v132
	v_min_f32_e32 v130, 0, v131
	v_mul_f32_e64 v131, |v131|, s88
	v_exp_f32_e32 v131, v131
	s_nop 0
	v_add_f32_e32 v131, 1.0, v131
	v_cmp_gt_f32_e32 vcc, s89, v131
	s_nop 1
	v_cndmask_b32_e64 v132, 0, 32, vcc
	v_ldexp_f32 v131, v131, v132
	v_log_f32_e32 v131, v131
	s_nop 0
	v_mul_f32_e32 v132, 0x3f317217, v131
	v_fma_f32 v132, v131, s90, -v132
	v_fmac_f32_e32 v132, 0x3377d1cf, v131
	v_fmac_f32_e32 v132, 0x3f317217, v131
	v_cmp_lt_f32_e64 s[6:7], |v131|, s91
	s_nop 1
	v_cndmask_b32_e64 v131, v131, v132, s[6:7]
	v_cndmask_b32_e32 v132, 0, v222, vcc
	v_sub_f32_e32 v132, v131, v132
	v_min_f32_e32 v131, 0, v133
	v_mul_f32_e64 v133, |v133|, s88
	v_exp_f32_e32 v133, v133
	s_nop 0
	v_add_f32_e32 v133, 1.0, v133
	v_cmp_gt_f32_e32 vcc, s89, v133
	s_nop 1
	v_cndmask_b32_e64 v144, 0, 32, vcc
	v_ldexp_f32 v133, v133, v144
	v_log_f32_e32 v133, v133
	s_nop 0
	v_mul_f32_e32 v144, 0x3f317217, v133
	v_fma_f32 v144, v133, s90, -v144
	v_fmac_f32_e32 v144, 0x3377d1cf, v133
	v_fmac_f32_e32 v144, 0x3f317217, v133
	v_cmp_lt_f32_e64 s[6:7], |v133|, s91
	s_nop 1
	v_cndmask_b32_e64 v133, v133, v144, s[6:7]
	v_cndmask_b32_e32 v144, 0, v222, vcc
	v_sub_f32_e32 v133, v133, v144
	v_pk_add_f32 v[130:131], v[130:131], v[132:133] neg_lo:[0,1] neg_hi:[0,1]
	v_cvt_pk_bf16_f32 v132, v142, v143
	v_pk_mul_f32 v[144:145], v[130:131], s[28:29] op_sel_hi:[1,0]
	v_cvt_pk_bf16_f32 v130, v134, v135
	v_cvt_pk_bf16_f32 v131, v136, v137
	v_cvt_pk_bf16_f32 v133, v144, v145
	v_add_u32_e32 v142, 0xb0, v150
	ds_write_b128 v160, v[138:141]
	ds_write_b128 v161, v[130:133]
	ds_read_b128 v[130:133], v163
	ds_read_b128 v[134:137], v163 offset:1024
	v_ashrrev_i32_e32 v143, 31, v142
	v_lshlrev_b64 v[138:139], 9, v[142:143]
	v_lshl_add_u64 v[138:139], s[24:25], 0, v[138:139]
	v_lshl_add_u64 v[138:139], v[138:139], 0, v[184:185]
	s_waitcnt lgkmcnt(1)
	global_store_dwordx4 v[138:139], v[130:133], off sc1
	s_mov_b64 s[6:7], 0
	s_nop 0
	v_add_co_u32_e32 v130, vcc, 0x1000, v138
	s_nop 1
	v_addc_co_u32_e32 v131, vcc, 0, v139, vcc
	s_waitcnt lgkmcnt(0)
	global_store_dwordx4 v[130:131], v[134:137], off sc1

; __device__ __forceinline__ v4u pack8(const f32x4 a, const f32x4 b) { v4u w; w.x = pk2(a[0], a[1]); w.y = pk2(a[2], a[3]); w.z = pk2(b[0], b[1]); w.w = pk2(b[2], b[3]); return w; }
; __device__ __forceinline__ float silu_f(float x) { return x * __builtin_amdgcn_rcpf(1.0f + fast_exp(-x)); }
;     __device__ __forceinline__ void operator()(const f32x4 (&acc)[2][2][4][2], const pg8::Unit& u, int wr, int wc, int fr, int fq) const {
;     ...
;         } else if (pn < 14) {
;             bf16* dst = (bf16*)(ws + (pn < 10 ? WS_VB : (pn < 12 ? WS_GA : WS_GB))); const bool act = pn >= 10;
;             const int cb = 256 * (pn & 1) + 64 * wc + 8 * tt.p;
; #pragma unroll
;             for (int ai = 0; ai < 2; ++ai)
; #pragma unroll
;                 for (int m = 0; m < 4; ++m) {
;                     const int rowa = 256 * pm + 128 * ai + 64 * wr + 16 * m + tt.rr;
;                     const float rs = rs8[ai][m];
;                     v4u pk[2];
; #pragma unroll
;                     for (int bj = 0; bj < 2; ++bj) {
;                         f32x4 a = acc[ai][bj][m][0] * rs, b = acc[ai][bj][m][1] * rs;
;                         if (act) {
; #pragma unroll
;                             for (int j = 0; j < 4; ++j) { a[j] = silu_f(a[j]); b[j] = silu_f(b[j]); }
;                         }
;                         pk[bj] = pack8(a, b);
;                     }
;                     v4u a, b; tt.bf(pk[0], pk[1], a, b);
;                     bf16* d = dst + (size_t)rowa * 512 + cb; *(v4u*)d = a; *(v4u*)(d + 8 * 512) = b;
;                 }
.LBB0_424:
	s_cmp_lt_u32 s42, 12
	s_mov_b32 s0, 0x23800000
	s_cselect_b32 s0, s0, 0x27c00000
	s_cmp_gt_u32 s42, 9
	s_cselect_b32 s0, s0, 0x1b000000
	s_add_u32 s0, s58, s0
	s_addc_u32 s1, s59, 0
	s_lshl_b32 s12, s42, 8
	s_and_b32 s12, s12, 0x100
	v_cvt_pk_bf16_f32 v153, v130, v131
	v_lshl_or_b32 v130, v213, 3, s12
	v_or_b32_e32 v130, s69, v130
	v_cvt_pk_bf16_f32 v152, v132, v133
	v_cvt_pk_bf16_f32 v154, v136, v137
	v_cvt_pk_bf16_f32 v155, v134, v135
	v_lshlrev_b32_e32 v184, 1, v130
	v_cvt_pk_bf16_f32 v130, v140, v141
	v_cvt_pk_bf16_f32 v131, v138, v139
	v_cvt_pk_bf16_f32 v132, v144, v145
	v_cvt_pk_bf16_f32 v133, v142, v143
	v_add_u32_e32 v148, s77, v229
	v_add_u32_e32 v149, s77, v228
	ds_write_b128 v148, v[152:155]
	ds_write_b128 v149, v[130:133]
	v_add_u32_e32 v152, s77, v230
	ds_read_b128 v[132:135], v152
	ds_read_b128 v[136:139], v152 offset:1024
	v_lshl_add_u64 v[130:131], s[0:1], 0, v[184:185]
	v_lshlrev_b64 v[140:141], 10, v[150:151]
	v_lshl_add_u64 v[140:141], v[130:131], 0, v[140:141]
	s_waitcnt lgkmcnt(1)
	global_store_dwordx4 v[140:141], v[132:135], off sc1
	s_nop 1
	v_add_co_u32_e32 v132, vcc, s55, v140
	v_pk_mul_f32 v[134:135], v[110:111], v[210:211] op_sel_hi:[1,0]
	s_nop 0
	v_addc_co_u32_e32 v133, vcc, 0, v141, vcc
	s_waitcnt lgkmcnt(0)
	global_store_dwordx4 v[132:133], v[136:139], off sc1
	v_pk_mul_f32 v[132:133], v[112:113], v[210:211] op_sel_hi:[1,0]
	s_and_b64 vcc, exec, s[6:7]
	v_pk_mul_f32 v[136:137], v[108:109], v[210:211] op_sel_hi:[1,0]
	v_pk_mul_f32 v[138:139], v[106:107], v[210:211] op_sel_hi:[1,0]
	s_cbranch_vccnz .LBB0_426
	v_mul_f32_e32 v141, 0xbfb8aa3b, v138
	v_mul_f32_e32 v142, 0xbfb8aa3b, v135
	v_exp_f32_e32 v141, v141
	v_exp_f32_e32 v143, v142
	v_mul_f32_e32 v145, 0xbfb8aa3b, v136
	v_mul_f32_e32 v146, 0xbfb8aa3b, v133
	v_add_f32_e32 v141, 1.0, v141
	v_mul_f32_e32 v140, 0xbfb8aa3b, v134
	v_rcp_f32_e32 v142, v141
	v_add_f32_e32 v141, 1.0, v143
	v_mul_f32_e32 v143, 0xbfb8aa3b, v139
	v_mul_f32_e32 v144, 0xbfb8aa3b, v132
	v_exp_f32_e32 v145, v145
	v_exp_f32_e32 v147, v146
	v_mul_f32_e32 v146, 0xbfb8aa3b, v137
	v_exp_f32_e32 v140, v140
	v_exp_f32_e32 v143, v143
	v_exp_f32_e32 v144, v144
	v_exp_f32_e32 v151, v146
	v_add_f32_e32 v145, 1.0, v145
	v_add_f32_e32 v140, 1.0, v140
	v_add_f32_e32 v143, 1.0, v143
	v_add_f32_e32 v144, 1.0, v144
	v_rcp_f32_e32 v146, v145
	v_add_f32_e32 v145, 1.0, v147
	v_add_f32_e32 v147, 1.0, v151
	v_rcp_f32_e32 v140, v140
	v_rcp_f32_e32 v141, v141
	v_rcp_f32_e32 v144, v144
	v_rcp_f32_e32 v145, v145
	v_rcp_f32_e32 v147, v147
	v_rcp_f32_e32 v143, v143
	v_pk_mul_f32 v[134:135], v[134:135], v[140:141]
	v_pk_mul_f32 v[132:133], v[132:133], v[144:145]
	v_pk_mul_f32 v[136:137], v[136:137], v[146:147]
	v_pk_mul_f32 v[138:139], v[138:139], v[142:143]

; __device__ __forceinline__ v4u pack8(const f32x4 a, const f32x4 b) { v4u w; w.x = pk2(a[0], a[1]); w.y = pk2(a[2], a[3]); w.z = pk2(b[0], b[1]); w.w = pk2(b[2], b[3]); return w; }
; __device__ __forceinline__ float silu_f(float x) { return x * __builtin_amdgcn_rcpf(1.0f + fast_exp(-x)); }
;     __device__ __forceinline__ void operator()(const f32x4 (&acc)[2][2][4][2], const pg8::Unit& u, int wr, int wc, int fr, int fq) const {
;     ...
;             for (int ai = 0; ai < 2; ++ai)
; #pragma unroll
;                 for (int m = 0; m < 4; ++m) {
;                     const int rowa = 256 * pm + 128 * ai + 64 * wr + 16 * m + tt.rr;
;                     const float rs = rs8[ai][m];
;                     v4u pk[2];
; #pragma unroll
;                     for (int bj = 0; bj < 2; ++bj) {
;                         f32x4 a = acc[ai][bj][m][0] * rs, b = acc[ai][bj][m][1] * rs;
;                         if (act) {
; #pragma unroll
;                             for (int j = 0; j < 4; ++j) { a[j] = silu_f(a[j]); b[j] = silu_f(b[j]); }
;                         }
;                         pk[bj] = pack8(a, b);
;                     }
;                     v4u a, b; tt.bf(pk[0], pk[1], a, b);
;                     bf16* d = dst + (size_t)rowa * 512 + cb; *(v4u*)d = a; *(v4u*)(d + 8 * 512) = b;
.LBB0_428:
	v_cvt_pk_bf16_f32 v154, v134, v135
	v_cvt_pk_bf16_f32 v155, v132, v133
	v_cvt_pk_bf16_f32 v156, v138, v139
	v_cvt_pk_bf16_f32 v157, v136, v137
	v_cvt_pk_bf16_f32 v132, v142, v143
	v_cvt_pk_bf16_f32 v133, v140, v141
	v_cvt_pk_bf16_f32 v134, v146, v147
	v_cvt_pk_bf16_f32 v135, v144, v145
	ds_write_b128 v148, v[154:157]
	ds_write_b128 v149, v[132:135]
	v_add_u32_e32 v140, 16, v150
	ds_read_b128 v[132:135], v152
	ds_read_b128 v[136:139], v152 offset:1024
	v_ashrrev_i32_e32 v141, 31, v140
	v_lshlrev_b64 v[140:141], 10, v[140:141]
	v_lshl_add_u64 v[140:141], v[130:131], 0, v[140:141]
	s_waitcnt lgkmcnt(1)
	global_store_dwordx4 v[140:141], v[132:135], off sc1
	s_nop 1
	v_add_co_u32_e32 v132, vcc, s55, v140
	v_pk_mul_f32 v[134:135], v[94:95], v[208:209] op_sel_hi:[1,0]
	s_nop 0
	v_addc_co_u32_e32 v133, vcc, 0, v141, vcc
	s_waitcnt lgkmcnt(0)
	global_store_dwordx4 v[132:133], v[136:139], off sc1
	v_pk_mul_f32 v[132:133], v[96:97], v[208:209] op_sel_hi:[1,0]
	s_and_b64 vcc, exec, s[6:7]
	v_pk_mul_f32 v[136:137], v[92:93], v[208:209] op_sel_hi:[1,0]
	v_pk_mul_f32 v[138:139], v[90:91], v[208:209] op_sel_hi:[1,0]
	s_cbranch_vccnz .LBB0_430
	v_mul_f32_e32 v141, 0xbfb8aa3b, v138
	v_mul_f32_e32 v142, 0xbfb8aa3b, v135
	v_exp_f32_e32 v141, v141
	v_exp_f32_e32 v143, v142
	v_mul_f32_e32 v145, 0xbfb8aa3b, v136
	v_mul_f32_e32 v146, 0xbfb8aa3b, v133
	v_add_f32_e32 v141, 1.0, v141
	v_mul_f32_e32 v140, 0xbfb8aa3b, v134
	v_rcp_f32_e32 v142, v141
	v_add_f32_e32 v141, 1.0, v143
	v_mul_f32_e32 v143, 0xbfb8aa3b, v139
	v_mul_f32_e32 v144, 0xbfb8aa3b, v132
	v_exp_f32_e32 v145, v145
	v_exp_f32_e32 v147, v146
	v_mul_f32_e32 v146, 0xbfb8aa3b, v137
	v_exp_f32_e32 v140, v140
	v_exp_f32_e32 v143, v143
	v_exp_f32_e32 v144, v144
	v_exp_f32_e32 v151, v146
	v_add_f32_e32 v145, 1.0, v145
	v_add_f32_e32 v140, 1.0, v140
	v_add_f32_e32 v143, 1.0, v143
	v_add_f32_e32 v144, 1.0, v144
	v_rcp_f32_e32 v146, v145
	v_add_f32_e32 v145, 1.0, v147
	v_add_f32_e32 v147, 1.0, v151
	v_rcp_f32_e32 v140, v140
	v_rcp_f32_e32 v141, v141
	v_rcp_f32_e32 v144, v144
	v_rcp_f32_e32 v145, v145
	v_rcp_f32_e32 v147, v147
	v_rcp_f32_e32 v143, v143
	v_pk_mul_f32 v[134:135], v[134:135], v[140:141]
	v_pk_mul_f32 v[132:133], v[132:133], v[144:145]
	v_pk_mul_f32 v[136:137], v[136:137], v[146:147]
	v_pk_mul_f32 v[138:139], v[138:139], v[142:143]

; __device__ __forceinline__ v4u pack8(const f32x4 a, const f32x4 b) { v4u w; w.x = pk2(a[0], a[1]); w.y = pk2(a[2], a[3]); w.z = pk2(b[0], b[1]); w.w = pk2(b[2], b[3]); return w; }
; __device__ __forceinline__ float silu_f(float x) { return x * __builtin_amdgcn_rcpf(1.0f + fast_exp(-x)); }
;     __device__ __forceinline__ void operator()(const f32x4 (&acc)[2][2][4][2], const pg8::Unit& u, int wr, int wc, int fr, int fq) const {
;     ...
;             for (int ai = 0; ai < 2; ++ai)
; #pragma unroll
;                 for (int m = 0; m < 4; ++m) {
;                     const int rowa = 256 * pm + 128 * ai + 64 * wr + 16 * m + tt.rr;
;                     const float rs = rs8[ai][m];
;                     v4u pk[2];
; #pragma unroll
;                     for (int bj = 0; bj < 2; ++bj) {
;                         f32x4 a = acc[ai][bj][m][0] * rs, b = acc[ai][bj][m][1] * rs;
;                         if (act) {
; #pragma unroll
;                             for (int j = 0; j < 4; ++j) { a[j] = silu_f(a[j]); b[j] = silu_f(b[j]); }
;                         }
;                         pk[bj] = pack8(a, b);
;                     }
;                     v4u a, b; tt.bf(pk[0], pk[1], a, b);
;                     bf16* d = dst + (size_t)rowa * 512 + cb; *(v4u*)d = a; *(v4u*)(d + 8 * 512) = b;
.LBB0_432:
	v_cvt_pk_bf16_f32 v154, v134, v135
	v_cvt_pk_bf16_f32 v155, v132, v133
	v_cvt_pk_bf16_f32 v156, v138, v139
	v_cvt_pk_bf16_f32 v157, v136, v137
	v_cvt_pk_bf16_f32 v132, v142, v143
	v_cvt_pk_bf16_f32 v133, v140, v141
	v_cvt_pk_bf16_f32 v134, v146, v147
	v_cvt_pk_bf16_f32 v135, v144, v145
	ds_write_b128 v148, v[154:157]
	ds_write_b128 v149, v[132:135]
	v_add_u32_e32 v140, 32, v150
	ds_read_b128 v[132:135], v152
	ds_read_b128 v[136:139], v152 offset:1024
	v_ashrrev_i32_e32 v141, 31, v140
	v_lshlrev_b64 v[140:141], 10, v[140:141]
	v_lshl_add_u64 v[140:141], v[130:131], 0, v[140:141]
	s_waitcnt lgkmcnt(1)
	global_store_dwordx4 v[140:141], v[132:135], off sc1
	s_nop 1
	v_add_co_u32_e32 v132, vcc, s55, v140
	v_pk_mul_f32 v[134:135], v[78:79], v[206:207] op_sel_hi:[1,0]
	s_nop 0
	v_addc_co_u32_e32 v133, vcc, 0, v141, vcc
	s_waitcnt lgkmcnt(0)
	global_store_dwordx4 v[132:133], v[136:139], off sc1
	v_pk_mul_f32 v[132:133], v[80:81], v[206:207] op_sel_hi:[1,0]
	s_and_b64 vcc, exec, s[6:7]
	v_pk_mul_f32 v[136:137], v[76:77], v[206:207] op_sel_hi:[1,0]
	v_pk_mul_f32 v[138:139], v[74:75], v[206:207] op_sel_hi:[1,0]
	s_cbranch_vccnz .LBB0_434
	v_mul_f32_e32 v141, 0xbfb8aa3b, v138
	v_mul_f32_e32 v142, 0xbfb8aa3b, v135
	v_exp_f32_e32 v141, v141
	v_exp_f32_e32 v143, v142
	v_mul_f32_e32 v145, 0xbfb8aa3b, v136
	v_mul_f32_e32 v146, 0xbfb8aa3b, v133
	v_add_f32_e32 v141, 1.0, v141
	v_mul_f32_e32 v140, 0xbfb8aa3b, v134
	v_rcp_f32_e32 v142, v141
	v_add_f32_e32 v141, 1.0, v143
	v_mul_f32_e32 v143, 0xbfb8aa3b, v139
	v_mul_f32_e32 v144, 0xbfb8aa3b, v132
	v_exp_f32_e32 v145, v145
	v_exp_f32_e32 v147, v146
	v_mul_f32_e32 v146, 0xbfb8aa3b, v137
	v_exp_f32_e32 v140, v140
	v_exp_f32_e32 v143, v143
	v_exp_f32_e32 v144, v144
	v_exp_f32_e32 v151, v146
	v_add_f32_e32 v145, 1.0, v145
	v_add_f32_e32 v140, 1.0, v140
	v_add_f32_e32 v143, 1.0, v143
	v_add_f32_e32 v144, 1.0, v144
	v_rcp_f32_e32 v146, v145
	v_add_f32_e32 v145, 1.0, v147
	v_add_f32_e32 v147, 1.0, v151
	v_rcp_f32_e32 v140, v140
	v_rcp_f32_e32 v141, v141
	v_rcp_f32_e32 v144, v144
	v_rcp_f32_e32 v145, v145
	v_rcp_f32_e32 v147, v147
	v_rcp_f32_e32 v143, v143
	v_pk_mul_f32 v[134:135], v[134:135], v[140:141]
	v_pk_mul_f32 v[132:133], v[132:133], v[144:145]
	v_pk_mul_f32 v[136:137], v[136:137], v[146:147]
	v_pk_mul_f32 v[138:139], v[138:139], v[142:143]

; __device__ __forceinline__ v4u pack8(const f32x4 a, const f32x4 b) { v4u w; w.x = pk2(a[0], a[1]); w.y = pk2(a[2], a[3]); w.z = pk2(b[0], b[1]); w.w = pk2(b[2], b[3]); return w; }
; __device__ __forceinline__ float silu_f(float x) { return x * __builtin_amdgcn_rcpf(1.0f + fast_exp(-x)); }
;     __device__ __forceinline__ void operator()(const f32x4 (&acc)[2][2][4][2], const pg8::Unit& u, int wr, int wc, int fr, int fq) const {
;     ...
;             for (int ai = 0; ai < 2; ++ai)
; #pragma unroll
;                 for (int m = 0; m < 4; ++m) {
;                     const int rowa = 256 * pm + 128 * ai + 64 * wr + 16 * m + tt.rr;
;                     const float rs = rs8[ai][m];
;                     v4u pk[2];
; #pragma unroll
;                     for (int bj = 0; bj < 2; ++bj) {
;                         f32x4 a = acc[ai][bj][m][0] * rs, b = acc[ai][bj][m][1] * rs;
;                         if (act) {
; #pragma unroll
;                             for (int j = 0; j < 4; ++j) { a[j] = silu_f(a[j]); b[j] = silu_f(b[j]); }
;                         }
;                         pk[bj] = pack8(a, b);
;                     }
;                     v4u a, b; tt.bf(pk[0], pk[1], a, b);
;                     bf16* d = dst + (size_t)rowa * 512 + cb; *(v4u*)d = a; *(v4u*)(d + 8 * 512) = b;
.LBB0_436:
	v_cvt_pk_bf16_f32 v154, v134, v135
	v_cvt_pk_bf16_f32 v155, v132, v133
	v_cvt_pk_bf16_f32 v156, v138, v139
	v_cvt_pk_bf16_f32 v157, v136, v137
	v_cvt_pk_bf16_f32 v132, v142, v143
	v_cvt_pk_bf16_f32 v133, v140, v141
	v_cvt_pk_bf16_f32 v134, v146, v147
	v_cvt_pk_bf16_f32 v135, v144, v145
	ds_write_b128 v148, v[154:157]
	ds_write_b128 v149, v[132:135]
	v_add_u32_e32 v140, 48, v150
	ds_read_b128 v[132:135], v152
	ds_read_b128 v[136:139], v152 offset:1024
	v_ashrrev_i32_e32 v141, 31, v140
	v_lshlrev_b64 v[140:141], 10, v[140:141]
	v_lshl_add_u64 v[140:141], v[130:131], 0, v[140:141]
	s_waitcnt lgkmcnt(1)
	global_store_dwordx4 v[140:141], v[132:135], off sc1
	s_nop 1
	v_add_co_u32_e32 v132, vcc, s55, v140
	v_pk_mul_f32 v[134:135], v[62:63], v[204:205] op_sel_hi:[1,0]
	s_nop 0
	v_addc_co_u32_e32 v133, vcc, 0, v141, vcc
	s_waitcnt lgkmcnt(0)
	global_store_dwordx4 v[132:133], v[136:139], off sc1
	v_pk_mul_f32 v[132:133], v[64:65], v[204:205] op_sel_hi:[1,0]
	s_and_b64 vcc, exec, s[6:7]
	v_pk_mul_f32 v[136:137], v[60:61], v[204:205] op_sel_hi:[1,0]
	v_pk_mul_f32 v[138:139], v[58:59], v[204:205] op_sel_hi:[1,0]
	s_cbranch_vccnz .LBB0_438
	v_mul_f32_e32 v141, 0xbfb8aa3b, v138
	v_mul_f32_e32 v142, 0xbfb8aa3b, v135
	v_exp_f32_e32 v141, v141
	v_exp_f32_e32 v143, v142
	v_mul_f32_e32 v145, 0xbfb8aa3b, v136
	v_mul_f32_e32 v146, 0xbfb8aa3b, v133
	v_add_f32_e32 v141, 1.0, v141
	v_mul_f32_e32 v140, 0xbfb8aa3b, v134
	v_rcp_f32_e32 v142, v141
	v_add_f32_e32 v141, 1.0, v143
	v_mul_f32_e32 v143, 0xbfb8aa3b, v139
	v_mul_f32_e32 v144, 0xbfb8aa3b, v132
	v_exp_f32_e32 v145, v145
	v_exp_f32_e32 v147, v146
	v_mul_f32_e32 v146, 0xbfb8aa3b, v137
	v_exp_f32_e32 v140, v140
	v_exp_f32_e32 v143, v143
	v_exp_f32_e32 v144, v144
	v_exp_f32_e32 v151, v146
	v_add_f32_e32 v145, 1.0, v145
	v_add_f32_e32 v140, 1.0, v140
	v_add_f32_e32 v143, 1.0, v143
	v_add_f32_e32 v144, 1.0, v144
	v_rcp_f32_e32 v146, v145
	v_add_f32_e32 v145, 1.0, v147
	v_add_f32_e32 v147, 1.0, v151
	v_rcp_f32_e32 v140, v140
	v_rcp_f32_e32 v141, v141
	v_rcp_f32_e32 v144, v144
	v_rcp_f32_e32 v145, v145
	v_rcp_f32_e32 v147, v147
	v_rcp_f32_e32 v143, v143
	v_pk_mul_f32 v[134:135], v[134:135], v[140:141]
	v_pk_mul_f32 v[132:133], v[132:133], v[144:145]
	v_pk_mul_f32 v[136:137], v[136:137], v[146:147]
	v_pk_mul_f32 v[138:139], v[138:139], v[142:143]

; __device__ __forceinline__ v4u pack8(const f32x4 a, const f32x4 b) { v4u w; w.x = pk2(a[0], a[1]); w.y = pk2(a[2], a[3]); w.z = pk2(b[0], b[1]); w.w = pk2(b[2], b[3]); return w; }
; __device__ __forceinline__ float silu_f(float x) { return x * __builtin_amdgcn_rcpf(1.0f + fast_exp(-x)); }
;     __device__ __forceinline__ void operator()(const f32x4 (&acc)[2][2][4][2], const pg8::Unit& u, int wr, int wc, int fr, int fq) const {
;     ...
;             for (int ai = 0; ai < 2; ++ai)
; #pragma unroll
;                 for (int m = 0; m < 4; ++m) {
;                     const int rowa = 256 * pm + 128 * ai + 64 * wr + 16 * m + tt.rr;
;                     const float rs = rs8[ai][m];
;                     v4u pk[2];
; #pragma unroll
;                     for (int bj = 0; bj < 2; ++bj) {
;                         f32x4 a = acc[ai][bj][m][0] * rs, b = acc[ai][bj][m][1] * rs;
;                         if (act) {
; #pragma unroll
;                             for (int j = 0; j < 4; ++j) { a[j] = silu_f(a[j]); b[j] = silu_f(b[j]); }
;                         }
;                         pk[bj] = pack8(a, b);
;                     }
;                     v4u a, b; tt.bf(pk[0], pk[1], a, b);
;                     bf16* d = dst + (size_t)rowa * 512 + cb; *(v4u*)d = a; *(v4u*)(d + 8 * 512) = b;
.LBB0_440:
	v_cvt_pk_bf16_f32 v154, v134, v135
	v_cvt_pk_bf16_f32 v155, v132, v133
	v_cvt_pk_bf16_f32 v156, v138, v139
	v_cvt_pk_bf16_f32 v157, v136, v137
	v_cvt_pk_bf16_f32 v132, v142, v143
	v_cvt_pk_bf16_f32 v133, v140, v141
	v_cvt_pk_bf16_f32 v134, v146, v147
	v_cvt_pk_bf16_f32 v135, v144, v145
	ds_write_b128 v148, v[154:157]
	ds_write_b128 v149, v[132:135]
	v_add_u32_e32 v160, 0x80, v150
	ds_read_b128 v[132:135], v152
	ds_read_b128 v[136:139], v152 offset:1024
	v_ashrrev_i32_e32 v161, 31, v160
	v_lshlrev_b64 v[140:141], 10, v[160:161]
	v_lshl_add_u64 v[140:141], v[130:131], 0, v[140:141]
	s_waitcnt lgkmcnt(1)
	global_store_dwordx4 v[140:141], v[132:135], off sc1
	s_nop 1
	v_add_co_u32_e32 v132, vcc, s55, v140
	v_pk_mul_f32 v[134:135], v[46:47], v[202:203] op_sel_hi:[1,0]
	s_nop 0
	v_addc_co_u32_e32 v133, vcc, 0, v141, vcc
	s_waitcnt lgkmcnt(0)
	global_store_dwordx4 v[132:133], v[136:139], off sc1
	v_pk_mul_f32 v[132:133], v[48:49], v[202:203] op_sel_hi:[1,0]
	s_and_b64 vcc, exec, s[6:7]
	v_pk_mul_f32 v[136:137], v[44:45], v[202:203] op_sel_hi:[1,0]
	v_pk_mul_f32 v[138:139], v[42:43], v[202:203] op_sel_hi:[1,0]
	s_cbranch_vccnz .LBB0_442
	v_mul_f32_e32 v141, 0xbfb8aa3b, v138
	v_mul_f32_e32 v142, 0xbfb8aa3b, v135
	v_exp_f32_e32 v141, v141
	v_exp_f32_e32 v143, v142
	v_mul_f32_e32 v145, 0xbfb8aa3b, v136
	v_mul_f32_e32 v146, 0xbfb8aa3b, v133
	v_add_f32_e32 v141, 1.0, v141
	v_mul_f32_e32 v140, 0xbfb8aa3b, v134
	v_rcp_f32_e32 v142, v141
	v_add_f32_e32 v141, 1.0, v143
	v_mul_f32_e32 v143, 0xbfb8aa3b, v139
	v_mul_f32_e32 v144, 0xbfb8aa3b, v132
	v_exp_f32_e32 v145, v145
	v_exp_f32_e32 v147, v146
	v_mul_f32_e32 v146, 0xbfb8aa3b, v137
	v_exp_f32_e32 v140, v140
	v_exp_f32_e32 v143, v143
	v_exp_f32_e32 v144, v144
	v_exp_f32_e32 v151, v146
	v_add_f32_e32 v145, 1.0, v145
	v_add_f32_e32 v140, 1.0, v140
	v_add_f32_e32 v143, 1.0, v143
	v_add_f32_e32 v144, 1.0, v144
	v_rcp_f32_e32 v146, v145
	v_add_f32_e32 v145, 1.0, v147
	v_add_f32_e32 v147, 1.0, v151
	v_rcp_f32_e32 v140, v140
	v_rcp_f32_e32 v141, v141
	v_rcp_f32_e32 v144, v144
	v_rcp_f32_e32 v145, v145
	v_rcp_f32_e32 v147, v147
	v_rcp_f32_e32 v143, v143
	v_pk_mul_f32 v[134:135], v[134:135], v[140:141]
	v_pk_mul_f32 v[132:133], v[132:133], v[144:145]
	v_pk_mul_f32 v[136:137], v[136:137], v[146:147]
	v_pk_mul_f32 v[138:139], v[138:139], v[142:143]

; __device__ __forceinline__ v4u pack8(const f32x4 a, const f32x4 b) { v4u w; w.x = pk2(a[0], a[1]); w.y = pk2(a[2], a[3]); w.z = pk2(b[0], b[1]); w.w = pk2(b[2], b[3]); return w; }
; __device__ __forceinline__ float silu_f(float x) { return x * __builtin_amdgcn_rcpf(1.0f + fast_exp(-x)); }
;     __device__ __forceinline__ void operator()(const f32x4 (&acc)[2][2][4][2], const pg8::Unit& u, int wr, int wc, int fr, int fq) const {
;     ...
;             for (int ai = 0; ai < 2; ++ai)
; #pragma unroll
;                 for (int m = 0; m < 4; ++m) {
;                     const int rowa = 256 * pm + 128 * ai + 64 * wr + 16 * m + tt.rr;
;                     const float rs = rs8[ai][m];
;                     v4u pk[2];
; #pragma unroll
;                     for (int bj = 0; bj < 2; ++bj) {
;                         f32x4 a = acc[ai][bj][m][0] * rs, b = acc[ai][bj][m][1] * rs;
;                         if (act) {
; #pragma unroll
;                             for (int j = 0; j < 4; ++j) { a[j] = silu_f(a[j]); b[j] = silu_f(b[j]); }
;                         }
;                         pk[bj] = pack8(a, b);
;                     }
;                     v4u a, b; tt.bf(pk[0], pk[1], a, b);
;                     bf16* d = dst + (size_t)rowa * 512 + cb; *(v4u*)d = a; *(v4u*)(d + 8 * 512) = b;
.LBB0_444:
	v_cvt_pk_bf16_f32 v154, v134, v135
	v_cvt_pk_bf16_f32 v155, v132, v133
	v_cvt_pk_bf16_f32 v156, v138, v139
	v_cvt_pk_bf16_f32 v157, v136, v137
	v_cvt_pk_bf16_f32 v132, v142, v143
	v_cvt_pk_bf16_f32 v133, v140, v141
	v_cvt_pk_bf16_f32 v134, v146, v147
	v_cvt_pk_bf16_f32 v135, v144, v145
	ds_write_b128 v148, v[154:157]
	ds_write_b128 v149, v[132:135]
	v_add_u32_e32 v140, 0x90, v150
	ds_read_b128 v[132:135], v152
	ds_read_b128 v[136:139], v152 offset:1024
	v_ashrrev_i32_e32 v141, 31, v140
	v_lshlrev_b64 v[140:141], 10, v[140:141]
	v_lshl_add_u64 v[140:141], v[130:131], 0, v[140:141]
	s_waitcnt lgkmcnt(1)
	global_store_dwordx4 v[140:141], v[132:135], off sc1
	s_nop 1
	v_add_co_u32_e32 v132, vcc, s55, v140
	v_pk_mul_f32 v[134:135], v[30:31], v[198:199] op_sel_hi:[1,0]
	s_nop 0
	v_addc_co_u32_e32 v133, vcc, 0, v141, vcc
	s_waitcnt lgkmcnt(0)
	global_store_dwordx4 v[132:133], v[136:139], off sc1
	v_pk_mul_f32 v[132:133], v[32:33], v[198:199] op_sel_hi:[1,0]
	s_and_b64 vcc, exec, s[6:7]
	v_pk_mul_f32 v[136:137], v[28:29], v[198:199] op_sel_hi:[1,0]
	v_pk_mul_f32 v[138:139], v[26:27], v[198:199] op_sel_hi:[1,0]
	s_cbranch_vccnz .LBB0_446
	v_mul_f32_e32 v141, 0xbfb8aa3b, v138
	v_mul_f32_e32 v142, 0xbfb8aa3b, v135
	v_exp_f32_e32 v141, v141
	v_exp_f32_e32 v143, v142
	v_mul_f32_e32 v145, 0xbfb8aa3b, v136
	v_mul_f32_e32 v146, 0xbfb8aa3b, v133
	v_add_f32_e32 v141, 1.0, v141
	v_mul_f32_e32 v140, 0xbfb8aa3b, v134
	v_rcp_f32_e32 v142, v141
	v_add_f32_e32 v141, 1.0, v143
	v_mul_f32_e32 v143, 0xbfb8aa3b, v139
	v_mul_f32_e32 v144, 0xbfb8aa3b, v132
	v_exp_f32_e32 v145, v145
	v_exp_f32_e32 v147, v146
	v_mul_f32_e32 v146, 0xbfb8aa3b, v137
	v_exp_f32_e32 v140, v140
	v_exp_f32_e32 v143, v143
	v_exp_f32_e32 v144, v144
	v_exp_f32_e32 v151, v146
	v_add_f32_e32 v145, 1.0, v145
	v_add_f32_e32 v140, 1.0, v140
	v_add_f32_e32 v143, 1.0, v143
	v_add_f32_e32 v144, 1.0, v144
	v_rcp_f32_e32 v146, v145
	v_add_f32_e32 v145, 1.0, v147
	v_add_f32_e32 v147, 1.0, v151
	v_rcp_f32_e32 v140, v140
	v_rcp_f32_e32 v141, v141
	v_rcp_f32_e32 v144, v144
	v_rcp_f32_e32 v145, v145
	v_rcp_f32_e32 v147, v147
	v_rcp_f32_e32 v143, v143
	v_pk_mul_f32 v[134:135], v[134:135], v[140:141]
	v_pk_mul_f32 v[132:133], v[132:133], v[144:145]
	v_pk_mul_f32 v[136:137], v[136:137], v[146:147]
	v_pk_mul_f32 v[138:139], v[138:139], v[142:143]

; __device__ __forceinline__ v4u pack8(const f32x4 a, const f32x4 b) { v4u w; w.x = pk2(a[0], a[1]); w.y = pk2(a[2], a[3]); w.z = pk2(b[0], b[1]); w.w = pk2(b[2], b[3]); return w; }
; __device__ __forceinline__ float silu_f(float x) { return x * __builtin_amdgcn_rcpf(1.0f + fast_exp(-x)); }
;     __device__ __forceinline__ void operator()(const f32x4 (&acc)[2][2][4][2], const pg8::Unit& u, int wr, int wc, int fr, int fq) const {
;     ...
;             for (int ai = 0; ai < 2; ++ai)
; #pragma unroll
;                 for (int m = 0; m < 4; ++m) {
;                     const int rowa = 256 * pm + 128 * ai + 64 * wr + 16 * m + tt.rr;
;                     const float rs = rs8[ai][m];
;                     v4u pk[2];
; #pragma unroll
;                     for (int bj = 0; bj < 2; ++bj) {
;                         f32x4 a = acc[ai][bj][m][0] * rs, b = acc[ai][bj][m][1] * rs;
;                         if (act) {
; #pragma unroll
;                             for (int j = 0; j < 4; ++j) { a[j] = silu_f(a[j]); b[j] = silu_f(b[j]); }
;                         }
;                         pk[bj] = pack8(a, b);
;                     }
;                     v4u a, b; tt.bf(pk[0], pk[1], a, b);
;                     bf16* d = dst + (size_t)rowa * 512 + cb; *(v4u*)d = a; *(v4u*)(d + 8 * 512) = b;
.LBB0_448:
	v_cvt_pk_bf16_f32 v154, v134, v135
	v_cvt_pk_bf16_f32 v155, v132, v133
	v_cvt_pk_bf16_f32 v156, v138, v139
	v_cvt_pk_bf16_f32 v157, v136, v137
	v_cvt_pk_bf16_f32 v132, v142, v143
	v_cvt_pk_bf16_f32 v133, v140, v141
	v_cvt_pk_bf16_f32 v134, v146, v147
	v_cvt_pk_bf16_f32 v135, v144, v145
	ds_write_b128 v148, v[154:157]
	ds_write_b128 v149, v[132:135]
	v_add_u32_e32 v140, 0xa0, v150
	ds_read_b128 v[132:135], v152
	ds_read_b128 v[136:139], v152 offset:1024
	v_ashrrev_i32_e32 v141, 31, v140
	v_lshlrev_b64 v[140:141], 10, v[140:141]
	v_lshl_add_u64 v[140:141], v[130:131], 0, v[140:141]
	s_waitcnt lgkmcnt(1)
	global_store_dwordx4 v[140:141], v[132:135], off sc1
	s_nop 1
	v_add_co_u32_e32 v132, vcc, s55, v140
	v_pk_mul_f32 v[134:135], v[14:15], v[196:197] op_sel_hi:[1,0]
	s_nop 0
	v_addc_co_u32_e32 v133, vcc, 0, v141, vcc
	s_waitcnt lgkmcnt(0)
	global_store_dwordx4 v[132:133], v[136:139], off sc1
	v_pk_mul_f32 v[132:133], v[16:17], v[196:197] op_sel_hi:[1,0]
	s_and_b64 vcc, exec, s[6:7]
	v_pk_mul_f32 v[136:137], v[12:13], v[196:197] op_sel_hi:[1,0]
	v_pk_mul_f32 v[138:139], v[10:11], v[196:197] op_sel_hi:[1,0]
	s_cbranch_vccnz .LBB0_450
	v_mul_f32_e32 v141, 0xbfb8aa3b, v138
	v_mul_f32_e32 v142, 0xbfb8aa3b, v135
	v_exp_f32_e32 v141, v141
	v_exp_f32_e32 v143, v142
	v_mul_f32_e32 v145, 0xbfb8aa3b, v136
	v_mul_f32_e32 v146, 0xbfb8aa3b, v133
	v_add_f32_e32 v141, 1.0, v141
	v_mul_f32_e32 v140, 0xbfb8aa3b, v134
	v_rcp_f32_e32 v142, v141
	v_add_f32_e32 v141, 1.0, v143
	v_mul_f32_e32 v143, 0xbfb8aa3b, v139
	v_mul_f32_e32 v144, 0xbfb8aa3b, v132
	v_exp_f32_e32 v145, v145
	v_exp_f32_e32 v147, v146
	v_mul_f32_e32 v146, 0xbfb8aa3b, v137
	v_exp_f32_e32 v140, v140
	v_exp_f32_e32 v143, v143
	v_exp_f32_e32 v144, v144
	v_exp_f32_e32 v151, v146
	v_add_f32_e32 v145, 1.0, v145
	v_add_f32_e32 v140, 1.0, v140
	v_add_f32_e32 v143, 1.0, v143
	v_add_f32_e32 v144, 1.0, v144
	v_rcp_f32_e32 v146, v145
	v_add_f32_e32 v145, 1.0, v147
	v_add_f32_e32 v147, 1.0, v151
	v_rcp_f32_e32 v140, v140
	v_rcp_f32_e32 v141, v141
	v_rcp_f32_e32 v144, v144
	v_rcp_f32_e32 v145, v145
	v_rcp_f32_e32 v147, v147
	v_rcp_f32_e32 v143, v143
	v_pk_mul_f32 v[134:135], v[134:135], v[140:141]
	v_pk_mul_f32 v[132:133], v[132:133], v[144:145]
	v_pk_mul_f32 v[136:137], v[136:137], v[146:147]
	v_pk_mul_f32 v[138:139], v[138:139], v[142:143]

; __device__ __forceinline__ v4u pack8(const f32x4 a, const f32x4 b) { v4u w; w.x = pk2(a[0], a[1]); w.y = pk2(a[2], a[3]); w.z = pk2(b[0], b[1]); w.w = pk2(b[2], b[3]); return w; }
; __device__ __forceinline__ float silu_f(float x) { return x * __builtin_amdgcn_rcpf(1.0f + fast_exp(-x)); }
;     __device__ __forceinline__ void operator()(const f32x4 (&acc)[2][2][4][2], const pg8::Unit& u, int wr, int wc, int fr, int fq) const {
;     ...
;             for (int ai = 0; ai < 2; ++ai)
; #pragma unroll
;                 for (int m = 0; m < 4; ++m) {
;                     const int rowa = 256 * pm + 128 * ai + 64 * wr + 16 * m + tt.rr;
;                     const float rs = rs8[ai][m];
;                     v4u pk[2];
; #pragma unroll
;                     for (int bj = 0; bj < 2; ++bj) {
;                         f32x4 a = acc[ai][bj][m][0] * rs, b = acc[ai][bj][m][1] * rs;
;                         if (act) {
; #pragma unroll
;                             for (int j = 0; j < 4; ++j) { a[j] = silu_f(a[j]); b[j] = silu_f(b[j]); }
;                         }
;                         pk[bj] = pack8(a, b);
;                     }
;                     v4u a, b; tt.bf(pk[0], pk[1], a, b);
;                     bf16* d = dst + (size_t)rowa * 512 + cb; *(v4u*)d = a; *(v4u*)(d + 8 * 512) = b;
.LBB0_452:
	v_cvt_pk_bf16_f32 v154, v134, v135
	v_cvt_pk_bf16_f32 v155, v132, v133
	v_cvt_pk_bf16_f32 v156, v138, v139
	v_cvt_pk_bf16_f32 v157, v136, v137
	v_cvt_pk_bf16_f32 v132, v142, v143
	v_cvt_pk_bf16_f32 v133, v140, v141
	v_cvt_pk_bf16_f32 v134, v146, v147
	v_cvt_pk_bf16_f32 v135, v144, v145
	ds_write_b128 v148, v[154:157]
	ds_write_b128 v149, v[132:135]
	v_add_u32_e32 v140, 0xb0, v150
	ds_read_b128 v[132:135], v152
	ds_read_b128 v[136:139], v152 offset:1024
	v_ashrrev_i32_e32 v141, 31, v140
	v_lshlrev_b64 v[140:141], 10, v[140:141]
	v_lshl_add_u64 v[130:131], v[130:131], 0, v[140:141]
	s_waitcnt lgkmcnt(1)
	global_store_dwordx4 v[130:131], v[132:135], off sc1
	v_add_co_u32_e32 v130, vcc, 0x2000, v130
	s_nop 1
	v_addc_co_u32_e32 v131, vcc, 0, v131, vcc
	s_waitcnt lgkmcnt(0)
	global_store_dwordx4 v[130:131], v[136:139], off sc1

; __device__ __forceinline__ v4u pack8(const f32x4 a, const f32x4 b) { v4u w; w.x = pk2(a[0], a[1]); w.y = pk2(a[2], a[3]); w.z = pk2(b[0], b[1]); w.w = pk2(b[2], b[3]); return w; }
;     __device__ __forceinline__ void operator()(const f32x4 (&acc)[2][2][4][2], const pg8::Unit& u, int wr, int wc, int fr, int fq) const {
;     ...
;         } else if (pn < 8) {
;             bf16* dst = (bf16*)(ws + (pn == 6 ? WS_QB : WS_KB)); const float sc = pn == 6 ? 0.125f : 1.0f;
; #pragma unroll
;             for (int ai = 0; ai < 2; ++ai)
; #pragma unroll
;                 for (int m = 0; m < 4; ++m) {
;                     const int rowa = 256 * pm + 128 * ai + 64 * wr + 16 * m + tt.rr;
;                     const float rs = rs8[ai][m] * sc;
;                     v4u a, b; tt.bf(pack8(acc[ai][0][m][0] * rs, acc[ai][0][m][1] * rs), pack8(acc[ai][1][m][0] * rs, acc[ai][1][m][1] * rs), a, b);
;                     bf16* d = dst + (size_t)rowa * 256 + wc * 64 + 8 * tt.p; *(v4u*)d = a; *(v4u*)(d + 8 * 256) = b;
.LBB0_454:
	s_andn2_b64 vcc, exec, s[6:7]
	s_cbranch_vccnz .LBB0_456
	s_cmp_eq_u32 s42, 6
	s_cselect_b64 vcc, -1, 0
	v_cndmask_b32_e32 v150, 1.0, v223, vcc
	s_waitcnt vmcnt(0)
	v_mul_f32_e32 v138, v150, v162
	s_and_b64 s[0:1], vcc, exec
	v_pk_mul_f32 v[136:137], v[128:129], v[138:139] op_sel_hi:[1,0]
	v_pk_mul_f32 v[134:135], v[126:127], v[138:139] op_sel_hi:[1,0]
	v_pk_mul_f32 v[140:141], v[124:125], v[138:139] op_sel_hi:[1,0]
	v_pk_mul_f32 v[142:143], v[122:123], v[138:139] op_sel_hi:[1,0]
	s_mov_b32 s0, 0x16c00000
	v_add_u32_e32 v151, s77, v229
	v_cvt_pk_bf16_f32 v134, v134, v135
	v_cvt_pk_bf16_f32 v135, v136, v137
	v_cvt_pk_bf16_f32 v136, v142, v143
	v_cvt_pk_bf16_f32 v137, v140, v141
	v_pk_mul_f32 v[140:141], v[120:121], v[138:139] op_sel_hi:[1,0]
	v_pk_mul_f32 v[142:143], v[118:119], v[138:139] op_sel_hi:[1,0]
	v_pk_mul_f32 v[144:145], v[116:117], v[138:139] op_sel_hi:[1,0]
	v_pk_mul_f32 v[146:147], v[114:115], v[138:139] op_sel_hi:[1,0]
	s_cselect_b32 s0, s0, 0x18e00000
	s_add_i32 s1, s9, s66
	v_add_u32_e32 v152, s77, v228
	v_add_u32_e32 v153, s77, v230
	v_cvt_pk_bf16_f32 v138, v142, v143
	v_cvt_pk_bf16_f32 v139, v140, v141
	v_cvt_pk_bf16_f32 v140, v146, v147
	v_cvt_pk_bf16_f32 v141, v144, v145
	ds_write_b128 v151, v[134:137]
	ds_write_b128 v152, v[138:141]
	v_add_u32_e32 v132, s1, v227
	s_add_u32 s0, s73, s0
	ds_read_b128 v[134:137], v153
	ds_read_b128 v[138:141], v153 offset:1024
	s_addc_u32 s1, s74, 0
	v_lshlrev_b32_e32 v184, 4, v213
	v_ashrrev_i32_e32 v133, 31, v132
	v_lshl_add_u64 v[130:131], s[0:1], 0, v[184:185]
	v_lshlrev_b64 v[142:143], 9, v[132:133]
	v_lshl_add_u64 v[142:143], v[130:131], 0, v[142:143]
	s_waitcnt lgkmcnt(1)
	global_store_dwordx4 v[142:143], v[134:137], off sc1
	s_nop 1
	v_add_co_u32_e32 v134, vcc, s92, v142
	v_add_u32_e32 v142, 16, v132
	s_nop 0
	v_addc_co_u32_e32 v135, vcc, 0, v143, vcc
	s_waitcnt lgkmcnt(0)
	global_store_dwordx4 v[134:135], v[138:141], off sc1
	v_ashrrev_i32_e32 v143, 31, v142
	v_lshlrev_b64 v[142:143], 9, v[142:143]
	v_mul_f32_e32 v138, v150, v210
	v_pk_mul_f32 v[136:137], v[112:113], v[138:139] op_sel_hi:[1,0]
	v_pk_mul_f32 v[134:135], v[110:111], v[138:139] op_sel_hi:[1,0]
	v_pk_mul_f32 v[140:141], v[108:109], v[138:139] op_sel_hi:[1,0]
	v_pk_mul_f32 v[144:145], v[106:107], v[138:139] op_sel_hi:[1,0]
	v_cvt_pk_bf16_f32 v134, v134, v135
	v_cvt_pk_bf16_f32 v135, v136, v137
	v_cvt_pk_bf16_f32 v136, v144, v145
	v_cvt_pk_bf16_f32 v137, v140, v141
	v_pk_mul_f32 v[140:141], v[104:105], v[138:139] op_sel_hi:[1,0]
	v_pk_mul_f32 v[144:145], v[102:103], v[138:139] op_sel_hi:[1,0]
	v_pk_mul_f32 v[146:147], v[100:101], v[138:139] op_sel_hi:[1,0]
	v_pk_mul_f32 v[148:149], v[98:99], v[138:139] op_sel_hi:[1,0]
	v_cvt_pk_bf16_f32 v138, v144, v145
	v_cvt_pk_bf16_f32 v139, v140, v141
	v_cvt_pk_bf16_f32 v140, v148, v149
	v_cvt_pk_bf16_f32 v141, v146, v147
	ds_write_b128 v151, v[134:137]
	ds_write_b128 v152, v[138:141]
	ds_read_b128 v[134:137], v153
	ds_read_b128 v[138:141], v153 offset:1024
	v_lshl_add_u64 v[142:143], v[130:131], 0, v[142:143]
	s_waitcnt lgkmcnt(1)
	global_store_dwordx4 v[142:143], v[134:137], off sc1
	s_nop 1
	v_add_co_u32_e32 v134, vcc, s92, v142
	v_add_u32_e32 v142, 32, v132
	s_nop 0
	v_addc_co_u32_e32 v135, vcc, 0, v143, vcc
	s_waitcnt lgkmcnt(0)
	global_store_dwordx4 v[134:135], v[138:141], off sc1
	v_ashrrev_i32_e32 v143, 31, v142
	v_lshlrev_b64 v[142:143], 9, v[142:143]
	v_mul_f32_e32 v138, v150, v208
	v_pk_mul_f32 v[136:137], v[96:97], v[138:139] op_sel_hi:[1,0]
	v_pk_mul_f32 v[134:135], v[94:95], v[138:139] op_sel_hi:[1,0]
	v_pk_mul_f32 v[140:141], v[92:93], v[138:139] op_sel_hi:[1,0]
	v_pk_mul_f32 v[144:145], v[90:91], v[138:139] op_sel_hi:[1,0]
	v_cvt_pk_bf16_f32 v134, v134, v135
	v_cvt_pk_bf16_f32 v135, v136, v137
	v_cvt_pk_bf16_f32 v136, v144, v145
	v_cvt_pk_bf16_f32 v137, v140, v141
	v_pk_mul_f32 v[140:141], v[88:89], v[138:139] op_sel_hi:[1,0]
	v_pk_mul_f32 v[144:145], v[86:87], v[138:139] op_sel_hi:[1,0]
	v_pk_mul_f32 v[146:147], v[84:85], v[138:139] op_sel_hi:[1,0]
	v_pk_mul_f32 v[148:149], v[82:83], v[138:139] op_sel_hi:[1,0]
	v_cvt_pk_bf16_f32 v138, v144, v145
	v_cvt_pk_bf16_f32 v139, v140, v141
	v_cvt_pk_bf16_f32 v140, v148, v149
	v_cvt_pk_bf16_f32 v141, v146, v147
	ds_write_b128 v151, v[134:137]
	ds_write_b128 v152, v[138:141]
	ds_read_b128 v[134:137], v153
	ds_read_b128 v[138:141], v153 offset:1024
	v_lshl_add_u64 v[142:143], v[130:131], 0, v[142:143]
	s_waitcnt lgkmcnt(1)
	global_store_dwordx4 v[142:143], v[134:137], off sc1
	s_nop 1
	v_add_co_u32_e32 v134, vcc, s92, v142
	v_add_u32_e32 v142, 48, v132
	s_nop 0
	v_addc_co_u32_e32 v135, vcc, 0, v143, vcc
	s_waitcnt lgkmcnt(0)
	global_store_dwordx4 v[134:135], v[138:141], off sc1
	v_ashrrev_i32_e32 v143, 31, v142
	v_lshlrev_b64 v[142:143], 9, v[142:143]
	v_mul_f32_e32 v138, v150, v206
	v_pk_mul_f32 v[136:137], v[80:81], v[138:139] op_sel_hi:[1,0]
	v_pk_mul_f32 v[134:135], v[78:79], v[138:139] op_sel_hi:[1,0]
	v_pk_mul_f32 v[140:141], v[76:77], v[138:139] op_sel_hi:[1,0]
	v_pk_mul_f32 v[144:145], v[74:75], v[138:139] op_sel_hi:[1,0]
	v_cvt_pk_bf16_f32 v134, v134, v135
	v_cvt_pk_bf16_f32 v135, v136, v137
	v_cvt_pk_bf16_f32 v136, v144, v145
	v_cvt_pk_bf16_f32 v137, v140, v141
	v_pk_mul_f32 v[140:141], v[72:73], v[138:139] op_sel_hi:[1,0]
	v_pk_mul_f32 v[144:145], v[70:71], v[138:139] op_sel_hi:[1,0]
	v_pk_mul_f32 v[146:147], v[68:69], v[138:139] op_sel_hi:[1,0]
	v_pk_mul_f32 v[148:149], v[66:67], v[138:139] op_sel_hi:[1,0]
	v_cvt_pk_bf16_f32 v138, v144, v145
	v_cvt_pk_bf16_f32 v139, v140, v141
	v_cvt_pk_bf16_f32 v140, v148, v149
	v_cvt_pk_bf16_f32 v141, v146, v147
	ds_write_b128 v151, v[134:137]
	ds_write_b128 v152, v[138:141]
	ds_read_b128 v[134:137], v153
	ds_read_b128 v[138:141], v153 offset:1024
	v_lshl_add_u64 v[142:143], v[130:131], 0, v[142:143]
	s_waitcnt lgkmcnt(1)
; __device__ __forceinline__ v4u pack8(const f32x4 a, const f32x4 b) { v4u w; w.x = pk2(a[0], a[1]); w.y = pk2(a[2], a[3]); w.z = pk2(b[0], b[1]); w.w = pk2(b[2], b[3]); return w; }
;     __device__ __forceinline__ void operator()(const f32x4 (&acc)[2][2][4][2], const pg8::Unit& u, int wr, int wc, int fr, int fq) const {
;     ...
; #pragma unroll
;             for (int ai = 0; ai < 2; ++ai)
; #pragma unroll
;                 for (int m = 0; m < 4; ++m) {
;                     const int rowa = 256 * pm + 128 * ai + 64 * wr + 16 * m + tt.rr;
;                     const float rs = rs8[ai][m] * sc;
;                     v4u a, b; tt.bf(pack8(acc[ai][0][m][0] * rs, acc[ai][0][m][1] * rs), pack8(acc[ai][1][m][0] * rs, acc[ai][1][m][1] * rs), a, b);
;                     bf16* d = dst + (size_t)rowa * 256 + wc * 64 + 8 * tt.p; *(v4u*)d = a; *(v4u*)(d + 8 * 256) = b;
	global_store_dwordx4 v[142:143], v[134:137], off sc1
	s_nop 1
	v_add_co_u32_e32 v134, vcc, s92, v142
	v_add_u32_e32 v142, 0x80, v132
	s_nop 0
	v_addc_co_u32_e32 v135, vcc, 0, v143, vcc
	s_waitcnt lgkmcnt(0)
	global_store_dwordx4 v[134:135], v[138:141], off sc1
	v_ashrrev_i32_e32 v143, 31, v142
	v_lshlrev_b64 v[142:143], 9, v[142:143]
	v_mul_f32_e32 v138, v150, v204
	v_pk_mul_f32 v[136:137], v[64:65], v[138:139] op_sel_hi:[1,0]
	v_pk_mul_f32 v[134:135], v[62:63], v[138:139] op_sel_hi:[1,0]
	v_pk_mul_f32 v[140:141], v[60:61], v[138:139] op_sel_hi:[1,0]
	v_pk_mul_f32 v[144:145], v[58:59], v[138:139] op_sel_hi:[1,0]
	v_cvt_pk_bf16_f32 v134, v134, v135
	v_cvt_pk_bf16_f32 v135, v136, v137
	v_cvt_pk_bf16_f32 v136, v144, v145
	v_cvt_pk_bf16_f32 v137, v140, v141
	v_pk_mul_f32 v[140:141], v[56:57], v[138:139] op_sel_hi:[1,0]
	v_pk_mul_f32 v[144:145], v[54:55], v[138:139] op_sel_hi:[1,0]
	v_pk_mul_f32 v[146:147], v[52:53], v[138:139] op_sel_hi:[1,0]
	v_pk_mul_f32 v[148:149], v[50:51], v[138:139] op_sel_hi:[1,0]
	v_cvt_pk_bf16_f32 v138, v144, v145
	v_cvt_pk_bf16_f32 v139, v140, v141
	v_cvt_pk_bf16_f32 v140, v148, v149
	v_cvt_pk_bf16_f32 v141, v146, v147
	ds_write_b128 v151, v[134:137]
	ds_write_b128 v152, v[138:141]
	ds_read_b128 v[134:137], v153
	ds_read_b128 v[138:141], v153 offset:1024
	v_lshl_add_u64 v[142:143], v[130:131], 0, v[142:143]
	s_waitcnt lgkmcnt(1)
	global_store_dwordx4 v[142:143], v[134:137], off sc1
	s_nop 1
	v_add_co_u32_e32 v134, vcc, s92, v142
	v_add_u32_e32 v142, 0x90, v132
	s_nop 0
	v_addc_co_u32_e32 v135, vcc, 0, v143, vcc
	s_waitcnt lgkmcnt(0)
	global_store_dwordx4 v[134:135], v[138:141], off sc1
	v_ashrrev_i32_e32 v143, 31, v142
	v_lshlrev_b64 v[142:143], 9, v[142:143]
	v_mul_f32_e32 v138, v150, v202
	v_pk_mul_f32 v[136:137], v[48:49], v[138:139] op_sel_hi:[1,0]
	v_pk_mul_f32 v[134:135], v[46:47], v[138:139] op_sel_hi:[1,0]
	v_pk_mul_f32 v[140:141], v[44:45], v[138:139] op_sel_hi:[1,0]
	v_pk_mul_f32 v[144:145], v[42:43], v[138:139] op_sel_hi:[1,0]
	v_cvt_pk_bf16_f32 v134, v134, v135
	v_cvt_pk_bf16_f32 v135, v136, v137
	v_cvt_pk_bf16_f32 v136, v144, v145
	v_cvt_pk_bf16_f32 v137, v140, v141
	v_pk_mul_f32 v[140:141], v[40:41], v[138:139] op_sel_hi:[1,0]
	v_pk_mul_f32 v[144:145], v[38:39], v[138:139] op_sel_hi:[1,0]
	v_pk_mul_f32 v[146:147], v[36:37], v[138:139] op_sel_hi:[1,0]
	v_pk_mul_f32 v[148:149], v[34:35], v[138:139] op_sel_hi:[1,0]
	v_cvt_pk_bf16_f32 v138, v144, v145
	v_cvt_pk_bf16_f32 v139, v140, v141
	v_cvt_pk_bf16_f32 v140, v148, v149
	v_cvt_pk_bf16_f32 v141, v146, v147
	ds_write_b128 v151, v[134:137]
	ds_write_b128 v152, v[138:141]
	ds_read_b128 v[134:137], v153
	ds_read_b128 v[138:141], v153 offset:1024
	v_lshl_add_u64 v[142:143], v[130:131], 0, v[142:143]
	s_waitcnt lgkmcnt(1)
	global_store_dwordx4 v[142:143], v[134:137], off sc1
	s_nop 1
	v_add_co_u32_e32 v134, vcc, s92, v142
	v_add_u32_e32 v142, 0xa0, v132
	s_nop 0
	v_addc_co_u32_e32 v135, vcc, 0, v143, vcc
	s_waitcnt lgkmcnt(0)
	global_store_dwordx4 v[134:135], v[138:141], off sc1
	v_ashrrev_i32_e32 v143, 31, v142
	v_lshlrev_b64 v[142:143], 9, v[142:143]
	v_mul_f32_e32 v138, v150, v198
	v_pk_mul_f32 v[136:137], v[32:33], v[138:139] op_sel_hi:[1,0]
	v_pk_mul_f32 v[134:135], v[30:31], v[138:139] op_sel_hi:[1,0]
	v_pk_mul_f32 v[140:141], v[28:29], v[138:139] op_sel_hi:[1,0]
	v_pk_mul_f32 v[144:145], v[26:27], v[138:139] op_sel_hi:[1,0]
	v_cvt_pk_bf16_f32 v134, v134, v135
	v_cvt_pk_bf16_f32 v135, v136, v137
	v_cvt_pk_bf16_f32 v136, v144, v145
	v_cvt_pk_bf16_f32 v137, v140, v141
	v_pk_mul_f32 v[140:141], v[24:25], v[138:139] op_sel_hi:[1,0]
	v_pk_mul_f32 v[144:145], v[22:23], v[138:139] op_sel_hi:[1,0]
	v_pk_mul_f32 v[146:147], v[20:21], v[138:139] op_sel_hi:[1,0]
	v_pk_mul_f32 v[148:149], v[18:19], v[138:139] op_sel_hi:[1,0]
	v_cvt_pk_bf16_f32 v138, v144, v145
	v_cvt_pk_bf16_f32 v139, v140, v141
	v_cvt_pk_bf16_f32 v140, v148, v149
	v_cvt_pk_bf16_f32 v141, v146, v147
	ds_write_b128 v151, v[134:137]
	ds_write_b128 v152, v[138:141]
	ds_read_b128 v[134:137], v153
	ds_read_b128 v[138:141], v153 offset:1024
	v_lshl_add_u64 v[142:143], v[130:131], 0, v[142:143]
	s_waitcnt lgkmcnt(1)
	global_store_dwordx4 v[142:143], v[134:137], off sc1
	s_nop 1
	v_add_co_u32_e32 v134, vcc, s92, v142
	v_mul_f32_e32 v136, v150, v196
	s_nop 0
	v_addc_co_u32_e32 v135, vcc, 0, v143, vcc
	s_waitcnt lgkmcnt(0)
	global_store_dwordx4 v[134:135], v[138:141], off sc1
	v_pk_mul_f32 v[134:135], v[16:17], v[136:137] op_sel_hi:[1,0]
	v_pk_mul_f32 v[142:143], v[10:11], v[136:137] op_sel_hi:[1,0]
	v_add_u32_e32 v140, 0xb0, v132
	v_pk_mul_f32 v[132:133], v[14:15], v[136:137] op_sel_hi:[1,0]
	v_pk_mul_f32 v[138:139], v[12:13], v[136:137] op_sel_hi:[1,0]
	v_cvt_pk_bf16_f32 v132, v132, v133
	v_cvt_pk_bf16_f32 v133, v134, v135
	v_cvt_pk_bf16_f32 v134, v142, v143
	v_cvt_pk_bf16_f32 v135, v138, v139
	v_pk_mul_f32 v[138:139], v[8:9], v[136:137] op_sel_hi:[1,0]
	v_pk_mul_f32 v[142:143], v[6:7], v[136:137] op_sel_hi:[1,0]
	v_pk_mul_f32 v[144:145], v[4:5], v[136:137] op_sel_hi:[1,0]
	v_pk_mul_f32 v[146:147], v[2:3], v[136:137] op_sel_hi:[1,0]
	v_cvt_pk_bf16_f32 v136, v142, v143
	v_cvt_pk_bf16_f32 v137, v138, v139
	v_cvt_pk_bf16_f32 v138, v146, v147
	v_cvt_pk_bf16_f32 v139, v144, v145
	ds_write_b128 v151, v[132:135]
	ds_write_b128 v152, v[136:139]
	ds_read_b128 v[132:135], v153
	ds_read_b128 v[136:139], v153 offset:1024
	v_ashrrev_i32_e32 v141, 31, v140
	v_lshlrev_b64 v[140:141], 9, v[140:141]
	v_lshl_add_u64 v[130:131], v[130:131], 0, v[140:141]
	s_waitcnt lgkmcnt(1)
	global_store_dwordx4 v[130:131], v[132:135], off sc1
	v_add_co_u32_e32 v130, vcc, 0x1000, v130
	s_nop 1
	v_addc_co_u32_e32 v131, vcc, 0, v131, vcc
	s_waitcnt lgkmcnt(0)
	global_store_dwordx4 v[130:131], v[136:139], off sc1

; __device__ __forceinline__ v4u pack8(const f32x4 a, const f32x4 b) { v4u w; w.x = pk2(a[0], a[1]); w.y = pk2(a[2], a[3]); w.z = pk2(b[0], b[1]); w.w = pk2(b[2], b[3]); return w; }
;     __device__ __forceinline__ void operator()(const f32x4 (&acc)[2][2][4][2], const pg8::Unit& u, int wr, int wc, int fr, int fq) const {
;     ...
;         } else if (pn < 6) {
;             const int head = 4 * (pn & 1) + wc;
;             const bool wout = sample || (pm & 15) >= 8;
; #pragma unroll
;             for (int ai = 0; ai < 2; ++ai)
; #pragma unroll
;                 for (int m = 0; m < 4; ++m) {
;                     const int rl = 128 * ai + 64 * wr + 16 * m + tt.rr, rowa = 256 * pm + rl;
;                     const float rs = rs8[ai][m];
;                     const f32x4 a0 = acc[ai][0][m][0] * rs, a1 = acc[ai][0][m][1] * rs, b0 = acc[ai][1][m][0] * rs, b1 = acc[ai][1][m][1] * rs;
;                     { v4u a, b; tt.bf(pack8(a0, a1), pack8(b0, b1), a, b);
;                       bf16* d = (bf16*)(ws + WS_V) + (size_t)rowa * DA + head * 64 + 8 * tt.p; *(v4u*)d = a; *(v4u*)(d + 8 * DA) = b; }
;                     if (wout) {
;                         float* op = sample ? out + OUT_VNEW + (size_t)(rowa - MP) * DA : out + OUT_VWIN + ((size_t)(pm >> 4) * WIN + (256 * (pm & 15) + rl - (SEQ - WIN))) * DA;
;                         op += head * 64 + 4 * tt.p;
;                         f32x4 a, b; tt.f4(a0, a1, a, b); *(f32x4*)op = a; *(f32x4*)(op + 8 * DA) = b;
;                         tt.f4(b0, b1, a, b); *(f32x4*)(op + 32) = a; *(f32x4*)(op + 32 + 8 * DA) = b;
;                     }
;                 }
.LBB0_457:
	s_andn2_b64 vcc, exec, s[6:7]
	s_cbranch_vccnz .LBB0_474
	s_lshl_b32 s0, s42, 2
	v_add_u32_e32 v153, s66, v227
	s_waitcnt vmcnt(0)
	v_pk_mul_f32 v[140:141], v[128:129], v[162:163] op_sel_hi:[1,0]
	v_pk_mul_f32 v[138:139], v[126:127], v[162:163] op_sel_hi:[1,0]
	v_pk_mul_f32 v[144:145], v[124:125], v[162:163] op_sel_hi:[1,0]
	v_pk_mul_f32 v[142:143], v[122:123], v[162:163] op_sel_hi:[1,0]
	s_and_b32 s0, s0, 4
	v_add_u32_e32 v151, s77, v229
	v_add_u32_e32 v148, s9, v153
	v_pk_mul_f32 v[132:133], v[120:121], v[162:163] op_sel_hi:[1,0]
	v_pk_mul_f32 v[130:131], v[118:119], v[162:163] op_sel_hi:[1,0]
	v_pk_mul_f32 v[136:137], v[116:117], v[162:163] op_sel_hi:[1,0]
	v_pk_mul_f32 v[134:135], v[114:115], v[162:163] op_sel_hi:[1,0]
	v_cvt_pk_bf16_f32 v154, v138, v139
	v_cvt_pk_bf16_f32 v155, v140, v141
	v_cvt_pk_bf16_f32 v156, v142, v143
	v_cvt_pk_bf16_f32 v157, v144, v145
	s_or_b32 s12, s0, s65
	s_and_b32 s0, s8, 15
	v_add_u32_e32 v152, s77, v228
	v_add_u32_e32 v150, s77, v230
	v_cvt_pk_bf16_f32 v164, v130, v131
	v_cvt_pk_bf16_f32 v165, v132, v133
	v_cvt_pk_bf16_f32 v166, v134, v135
	v_cvt_pk_bf16_f32 v167, v136, v137
	ds_write_b128 v151, v[154:157]
	ds_write_b128 v152, v[164:167]
	v_ashrrev_i32_e32 v149, 31, v148
	s_cmp_gt_u32 s0, 7
	ds_read_b128 v[154:157], v150
	ds_read_b128 v[164:167], v150 offset:1024
	v_lshlrev_b64 v[146:147], 10, v[148:149]
	s_cselect_b64 s[6:7], -1, 0
	s_lshl_b32 s1, s12, 6
	v_lshl_add_u64 v[146:147], s[26:27], 0, v[146:147]
	s_lshl_b32 s12, s12, 7
	v_lshl_add_u64 v[146:147], v[146:147], 0, s[12:13]
	v_lshlrev_b32_e32 v184, 4, v213
	v_lshl_add_u64 v[146:147], v[146:147], 0, v[184:185]
	s_waitcnt lgkmcnt(1)
	global_store_dwordx4 v[146:147], v[154:157], off sc1
	v_add_co_u32_e32 v146, vcc, 0x2000, v146
	s_ashr_i32 s44, s8, 4
	s_nop 0
	v_addc_co_u32_e32 v147, vcc, 0, v147, vcc
	s_or_b64 s[46:47], s[4:5], s[6:7]
	s_ashr_i32 s45, s44, 31
	s_lshl_b32 s0, s0, 8
	v_lshl_or_b32 v160, v213, 2, s1
	s_waitcnt lgkmcnt(0)
	global_store_dwordx4 v[146:147], v[164:167], off sc1
	v_cndmask_b32_e64 v146, 0, 1, s[46:47]
	s_addk_i32 s0, 0xf800
	s_lshl_b64 s[44:45], s[44:45], 22
	v_cmp_ne_u32_e64 s[6:7], 1, v146
	s_andn2_b64 vcc, exec, s[46:47]
	v_lshlrev_b32_e32 v146, 2, v160
	s_cbranch_vccnz .LBB0_460
	v_add_u32_e32 v154, s77, v226
	v_add_u32_e32 v155, s77, v225
	v_add_u32_e32 v147, s0, v153
	s_add_u32 s12, s78, s44
	v_add_u32_e32 v148, 0xffff0000, v148
	ds_write_b128 v154, v[138:141]
	ds_write_b128 v155, v[142:145]
	s_addc_u32 s33, s79, s45
	v_cndmask_b32_e64 v148, v147, v148, s[4:5]
	ds_read_b128 v[138:141], v150
	s_and_b64 s[46:47], s[4:5], exec
	v_ashrrev_i32_e32 v149, 31, v148
	s_cselect_b32 s47, s81, s33
	s_cselect_b32 s46, s80, s12
	v_lshlrev_b64 v[148:149], 11, v[148:149]
	v_lshl_add_u64 v[142:143], s[46:47], 0, v[148:149]
	v_mov_b32_e32 v147, v185
	v_lshl_add_u64 v[148:149], v[142:143], 0, v[146:147]
	ds_read_b128 v[142:145], v150 offset:1024
	s_waitcnt lgkmcnt(1)
	global_store_dwordx4 v[148:149], v[138:141], off nt
	ds_write_b128 v154, v[130:133]
	ds_write_b128 v155, v[134:137]
	ds_read_b128 v[130:133], v150
	ds_read_b128 v[134:137], v150 offset:1024
	v_add_co_u32_e32 v138, vcc, 0x4000, v148
	s_nop 1
	v_addc_co_u32_e32 v139, vcc, 0, v149, vcc
	s_waitcnt lgkmcnt(4)
	global_store_dwordx4 v[138:139], v[142:145], off nt
	s_waitcnt lgkmcnt(1)
	global_store_dwordx4 v[148:149], v[130:133], off offset:128 nt
	s_waitcnt lgkmcnt(0)
	global_store_dwordx4 v[138:139], v[134:137], off offset:128 nt
.LBB0_460:
	v_add_u32_e32 v147, 16, v153
	v_pk_mul_f32 v[140:141], v[112:113], v[210:211] op_sel_hi:[1,0]
	v_pk_mul_f32 v[138:139], v[110:111], v[210:211] op_sel_hi:[1,0]
	v_pk_mul_f32 v[144:145], v[108:109], v[210:211] op_sel_hi:[1,0]
	v_pk_mul_f32 v[142:143], v[106:107], v[210:211] op_sel_hi:[1,0]
	v_add_u32_e32 v148, s9, v147
	v_pk_mul_f32 v[132:133], v[104:105], v[210:211] op_sel_hi:[1,0]
	v_pk_mul_f32 v[130:131], v[102:103], v[210:211] op_sel_hi:[1,0]
	v_pk_mul_f32 v[136:137], v[100:101], v[210:211] op_sel_hi:[1,0]
	v_pk_mul_f32 v[134:135], v[98:99], v[210:211] op_sel_hi:[1,0]
	v_cvt_pk_bf16_f32 v154, v138, v139
	v_cvt_pk_bf16_f32 v155, v140, v141
	v_cvt_pk_bf16_f32 v156, v142, v143
	v_cvt_pk_bf16_f32 v157, v144, v145
	v_cvt_pk_bf16_f32 v164, v130, v131
	v_cvt_pk_bf16_f32 v165, v132, v133
	v_cvt_pk_bf16_f32 v166, v134, v135
	v_cvt_pk_bf16_f32 v167, v136, v137
	ds_write_b128 v151, v[154:157]
	ds_write_b128 v152, v[164:167]
	v_ashrrev_i32_e32 v149, 31, v148
	ds_read_b128 v[154:157], v150
	ds_read_b128 v[164:167], v150 offset:1024
	v_lshlrev_b64 v[160:161], 10, v[148:149]
	v_lshlrev_b32_e32 v163, 3, v213
	v_lshl_add_u64 v[160:161], s[26:27], 0, v[160:161]
	s_lshl_b32 s12, s1, 1
	v_lshl_add_u64 v[160:161], v[160:161], 0, s[12:13]
	v_lshlrev_b32_e32 v184, 1, v163
	v_lshl_add_u64 v[160:161], v[160:161], 0, v[184:185]
	s_waitcnt lgkmcnt(1)
	global_store_dwordx4 v[160:161], v[154:157], off sc1
	s_nop 1
	v_add_co_u32_e32 v154, vcc, 0x2000, v160
	s_nop 1
	v_addc_co_u32_e32 v155, vcc, 0, v161, vcc
	s_and_b64 vcc, exec, s[6:7]
	s_waitcnt lgkmcnt(0)
	global_store_dwordx4 v[154:155], v[164:167], off sc1
	s_cbranch_vccnz .LBB0_462
	v_add_u32_e32 v154, s77, v226
	v_add_u32_e32 v155, s77, v225
	v_add_u32_e32 v148, 0xffff0000, v148
	v_add_u32_e32 v147, s0, v147
	s_add_u32 s1, s78, s44
	ds_write_b128 v154, v[138:141]
	ds_write_b128 v155, v[142:145]
	s_addc_u32 s33, s79, s45
	v_cndmask_b32_e64 v148, v147, v148, s[4:5]
	ds_read_b128 v[138:141], v150
	s_and_b64 s[46:47], s[4:5], exec
	v_ashrrev_i32_e32 v149, 31, v148
	s_cselect_b32 s47, s81, s33
	s_cselect_b32 s46, s80, s1
	v_lshlrev_b64 v[148:149], 11, v[148:149]
	v_lshl_add_u64 v[142:143], s[46:47], 0, v[148:149]
	v_mov_b32_e32 v147, v185
	v_lshl_add_u64 v[148:149], v[142:143], 0, v[146:147]
	ds_read_b128 v[142:145], v150 offset:1024
	s_waitcnt lgkmcnt(1)
	global_store_dwordx4 v[148:149], v[138:141], off nt
	ds_write_b128 v154, v[130:133]
	ds_write_b128 v155, v[134:137]
	ds_read_b128 v[130:133], v150
	ds_read_b128 v[134:137], v150 offset:1024
	v_add_co_u32_e32 v138, vcc, 0x4000, v148
	s_nop 1
	v_addc_co_u32_e32 v139, vcc, 0, v149, vcc
	s_waitcnt lgkmcnt(4)
	global_store_dwordx4 v[138:139], v[142:145], off nt
	s_waitcnt lgkmcnt(1)
	global_store_dwordx4 v[148:149], v[130:133], off offset:128 nt
	s_waitcnt lgkmcnt(0)
	global_store_dwordx4 v[138:139], v[134:137], off offset:128 nt
; __device__ __forceinline__ v4u pack8(const f32x4 a, const f32x4 b) { v4u w; w.x = pk2(a[0], a[1]); w.y = pk2(a[2], a[3]); w.z = pk2(b[0], b[1]); w.w = pk2(b[2], b[3]); return w; }
;     __device__ __forceinline__ void operator()(const f32x4 (&acc)[2][2][4][2], const pg8::Unit& u, int wr, int wc, int fr, int fq) const {
;     ...
;         } else if (pn < 6) {
;             const int head = 4 * (pn & 1) + wc;
;             const bool wout = sample || (pm & 15) >= 8;
; #pragma unroll
;             for (int ai = 0; ai < 2; ++ai)
; #pragma unroll
;                 for (int m = 0; m < 4; ++m) {
;                     const int rl = 128 * ai + 64 * wr + 16 * m + tt.rr, rowa = 256 * pm + rl;
;                     const float rs = rs8[ai][m];
;                     const f32x4 a0 = acc[ai][0][m][0] * rs, a1 = acc[ai][0][m][1] * rs, b0 = acc[ai][1][m][0] * rs, b1 = acc[ai][1][m][1] * rs;
;                     { v4u a, b; tt.bf(pack8(a0, a1), pack8(b0, b1), a, b);
;                       bf16* d = (bf16*)(ws + WS_V) + (size_t)rowa * DA + head * 64 + 8 * tt.p; *(v4u*)d = a; *(v4u*)(d + 8 * DA) = b; }
;                     if (wout) {
;                         float* op = sample ? out + OUT_VNEW + (size_t)(rowa - MP) * DA : out + OUT_VWIN + ((size_t)(pm >> 4) * WIN + (256 * (pm & 15) + rl - (SEQ - WIN))) * DA;
;                         op += head * 64 + 4 * tt.p;
;                         f32x4 a, b; tt.f4(a0, a1, a, b); *(f32x4*)op = a; *(f32x4*)(op + 8 * DA) = b;
;                         tt.f4(b0, b1, a, b); *(f32x4*)(op + 32) = a; *(f32x4*)(op + 32 + 8 * DA) = b;
;                     }
;                 }
.LBB0_462:
	v_add_u32_e32 v147, 32, v153
	v_pk_mul_f32 v[140:141], v[96:97], v[208:209] op_sel_hi:[1,0]
	v_pk_mul_f32 v[138:139], v[94:95], v[208:209] op_sel_hi:[1,0]
	v_pk_mul_f32 v[144:145], v[92:93], v[208:209] op_sel_hi:[1,0]
	v_pk_mul_f32 v[142:143], v[90:91], v[208:209] op_sel_hi:[1,0]
	v_add_u32_e32 v148, s9, v147
	v_pk_mul_f32 v[132:133], v[88:89], v[208:209] op_sel_hi:[1,0]
	v_pk_mul_f32 v[130:131], v[86:87], v[208:209] op_sel_hi:[1,0]
	v_pk_mul_f32 v[136:137], v[84:85], v[208:209] op_sel_hi:[1,0]
	v_pk_mul_f32 v[134:135], v[82:83], v[208:209] op_sel_hi:[1,0]
	v_cvt_pk_bf16_f32 v154, v138, v139
	v_cvt_pk_bf16_f32 v155, v140, v141
	v_cvt_pk_bf16_f32 v156, v142, v143
	v_cvt_pk_bf16_f32 v157, v144, v145
	v_cvt_pk_bf16_f32 v164, v130, v131
	v_cvt_pk_bf16_f32 v165, v132, v133
	v_cvt_pk_bf16_f32 v166, v134, v135
	v_cvt_pk_bf16_f32 v167, v136, v137
	ds_write_b128 v151, v[154:157]
	ds_write_b128 v152, v[164:167]
	v_ashrrev_i32_e32 v149, 31, v148
	ds_read_b128 v[154:157], v150
	ds_read_b128 v[164:167], v150 offset:1024
	v_lshlrev_b64 v[160:161], 10, v[148:149]
	v_lshl_add_u64 v[160:161], s[26:27], 0, v[160:161]
	v_lshl_add_u64 v[160:161], v[160:161], 0, s[12:13]
	v_lshl_add_u64 v[160:161], v[160:161], 0, v[184:185]
	s_waitcnt lgkmcnt(1)
	global_store_dwordx4 v[160:161], v[154:157], off sc1
	s_nop 1
	v_add_co_u32_e32 v154, vcc, 0x2000, v160
	s_nop 1
	v_addc_co_u32_e32 v155, vcc, 0, v161, vcc
	s_and_b64 vcc, exec, s[6:7]
	s_waitcnt lgkmcnt(0)
	global_store_dwordx4 v[154:155], v[164:167], off sc1
	s_cbranch_vccnz .LBB0_464
	v_add_u32_e32 v154, s77, v226
	v_add_u32_e32 v155, s77, v225
	v_add_u32_e32 v148, 0xffff0000, v148
	v_add_u32_e32 v147, s0, v147
	s_add_u32 s1, s78, s44
	ds_write_b128 v154, v[138:141]
	ds_write_b128 v155, v[142:145]
	s_addc_u32 s33, s79, s45
	v_cndmask_b32_e64 v148, v147, v148, s[4:5]
	ds_read_b128 v[138:141], v150
	s_and_b64 s[46:47], s[4:5], exec
	v_ashrrev_i32_e32 v149, 31, v148
	s_cselect_b32 s47, s81, s33
	s_cselect_b32 s46, s80, s1
	v_lshlrev_b64 v[148:149], 11, v[148:149]
	v_lshl_add_u64 v[142:143], s[46:47], 0, v[148:149]
	v_mov_b32_e32 v147, v185
	v_lshl_add_u64 v[148:149], v[142:143], 0, v[146:147]
	ds_read_b128 v[142:145], v150 offset:1024
	s_waitcnt lgkmcnt(1)
	global_store_dwordx4 v[148:149], v[138:141], off nt
	ds_write_b128 v154, v[130:133]
	ds_write_b128 v155, v[134:137]
	ds_read_b128 v[130:133], v150
	ds_read_b128 v[134:137], v150 offset:1024
	v_add_co_u32_e32 v138, vcc, 0x4000, v148
	s_nop 1
	v_addc_co_u32_e32 v139, vcc, 0, v149, vcc
	s_waitcnt lgkmcnt(4)
	global_store_dwordx4 v[138:139], v[142:145], off nt
	s_waitcnt lgkmcnt(1)
	global_store_dwordx4 v[148:149], v[130:133], off offset:128 nt
	s_waitcnt lgkmcnt(0)
	global_store_dwordx4 v[138:139], v[134:137], off offset:128 nt
.LBB0_464:
	v_add_u32_e32 v147, 48, v153
	v_pk_mul_f32 v[140:141], v[80:81], v[206:207] op_sel_hi:[1,0]
	v_pk_mul_f32 v[138:139], v[78:79], v[206:207] op_sel_hi:[1,0]
	v_pk_mul_f32 v[144:145], v[76:77], v[206:207] op_sel_hi:[1,0]
	v_pk_mul_f32 v[142:143], v[74:75], v[206:207] op_sel_hi:[1,0]
	v_add_u32_e32 v148, s9, v147
	v_pk_mul_f32 v[132:133], v[72:73], v[206:207] op_sel_hi:[1,0]
	v_pk_mul_f32 v[130:131], v[70:71], v[206:207] op_sel_hi:[1,0]
	v_pk_mul_f32 v[136:137], v[68:69], v[206:207] op_sel_hi:[1,0]
	v_pk_mul_f32 v[134:135], v[66:67], v[206:207] op_sel_hi:[1,0]
	v_cvt_pk_bf16_f32 v154, v138, v139
	v_cvt_pk_bf16_f32 v155, v140, v141
	v_cvt_pk_bf16_f32 v156, v142, v143
	v_cvt_pk_bf16_f32 v157, v144, v145
	v_cvt_pk_bf16_f32 v164, v130, v131
	v_cvt_pk_bf16_f32 v165, v132, v133
	v_cvt_pk_bf16_f32 v166, v134, v135
	v_cvt_pk_bf16_f32 v167, v136, v137
	ds_write_b128 v151, v[154:157]
	ds_write_b128 v152, v[164:167]
	v_ashrrev_i32_e32 v149, 31, v148
	ds_read_b128 v[154:157], v150
	ds_read_b128 v[164:167], v150 offset:1024
	v_lshlrev_b64 v[160:161], 10, v[148:149]
	v_lshl_add_u64 v[160:161], s[26:27], 0, v[160:161]
	v_lshl_add_u64 v[160:161], v[160:161], 0, s[12:13]
	v_lshl_add_u64 v[160:161], v[160:161], 0, v[184:185]
	s_waitcnt lgkmcnt(1)
	global_store_dwordx4 v[160:161], v[154:157], off sc1
	s_nop 1
	v_add_co_u32_e32 v154, vcc, 0x2000, v160
	s_nop 1
	v_addc_co_u32_e32 v155, vcc, 0, v161, vcc
	s_and_b64 vcc, exec, s[6:7]
	s_waitcnt lgkmcnt(0)
	global_store_dwordx4 v[154:155], v[164:167], off sc1
	s_cbranch_vccnz .LBB0_466
	v_add_u32_e32 v154, s77, v226
	v_add_u32_e32 v155, s77, v225
	v_add_u32_e32 v148, 0xffff0000, v148
	v_add_u32_e32 v147, s0, v147
	s_add_u32 s1, s78, s44
	ds_write_b128 v154, v[138:141]
	ds_write_b128 v155, v[142:145]
	s_addc_u32 s33, s79, s45
	v_cndmask_b32_e64 v148, v147, v148, s[4:5]
	ds_read_b128 v[138:141], v150
	s_and_b64 s[46:47], s[4:5], exec
	v_ashrrev_i32_e32 v149, 31, v148
	s_cselect_b32 s47, s81, s33
	s_cselect_b32 s46, s80, s1
	v_lshlrev_b64 v[148:149], 11, v[148:149]
	v_lshl_add_u64 v[142:143], s[46:47], 0, v[148:149]
	v_mov_b32_e32 v147, v185
	v_lshl_add_u64 v[148:149], v[142:143], 0, v[146:147]
	ds_read_b128 v[142:145], v150 offset:1024
	s_waitcnt lgkmcnt(1)
	global_store_dwordx4 v[148:149], v[138:141], off nt
	ds_write_b128 v154, v[130:133]
	ds_write_b128 v155, v[134:137]
	ds_read_b128 v[130:133], v150
	ds_read_b128 v[134:137], v150 offset:1024
	v_add_co_u32_e32 v138, vcc, 0x4000, v148
	s_nop 1
	v_addc_co_u32_e32 v139, vcc, 0, v149, vcc
	s_waitcnt lgkmcnt(4)
	global_store_dwordx4 v[138:139], v[142:145], off nt
	s_waitcnt lgkmcnt(1)
	global_store_dwordx4 v[148:149], v[130:133], off offset:128 nt
	s_waitcnt lgkmcnt(0)
	global_store_dwordx4 v[138:139], v[134:137], off offset:128 nt
; __device__ __forceinline__ v4u pack8(const f32x4 a, const f32x4 b) { v4u w; w.x = pk2(a[0], a[1]); w.y = pk2(a[2], a[3]); w.z = pk2(b[0], b[1]); w.w = pk2(b[2], b[3]); return w; }
;     __device__ __forceinline__ void operator()(const f32x4 (&acc)[2][2][4][2], const pg8::Unit& u, int wr, int wc, int fr, int fq) const {
;     ...
;         } else if (pn < 6) {
;             const int head = 4 * (pn & 1) + wc;
;             const bool wout = sample || (pm & 15) >= 8;
; #pragma unroll
;             for (int ai = 0; ai < 2; ++ai)
; #pragma unroll
;                 for (int m = 0; m < 4; ++m) {
;                     const int rl = 128 * ai + 64 * wr + 16 * m + tt.rr, rowa = 256 * pm + rl;
;                     const float rs = rs8[ai][m];
;                     const f32x4 a0 = acc[ai][0][m][0] * rs, a1 = acc[ai][0][m][1] * rs, b0 = acc[ai][1][m][0] * rs, b1 = acc[ai][1][m][1] * rs;
;                     { v4u a, b; tt.bf(pack8(a0, a1), pack8(b0, b1), a, b);
;                       bf16* d = (bf16*)(ws + WS_V) + (size_t)rowa * DA + head * 64 + 8 * tt.p; *(v4u*)d = a; *(v4u*)(d + 8 * DA) = b; }
;                     if (wout) {
;                         float* op = sample ? out + OUT_VNEW + (size_t)(rowa - MP) * DA : out + OUT_VWIN + ((size_t)(pm >> 4) * WIN + (256 * (pm & 15) + rl - (SEQ - WIN))) * DA;
;                         op += head * 64 + 4 * tt.p;
;                         f32x4 a, b; tt.f4(a0, a1, a, b); *(f32x4*)op = a; *(f32x4*)(op + 8 * DA) = b;
;                         tt.f4(b0, b1, a, b); *(f32x4*)(op + 32) = a; *(f32x4*)(op + 32 + 8 * DA) = b;
;                     }
;                 }
.LBB0_466:
	v_add_u32_e32 v147, 0x80, v153
	v_pk_mul_f32 v[140:141], v[64:65], v[204:205] op_sel_hi:[1,0]
	v_pk_mul_f32 v[138:139], v[62:63], v[204:205] op_sel_hi:[1,0]
	v_pk_mul_f32 v[144:145], v[60:61], v[204:205] op_sel_hi:[1,0]
	v_pk_mul_f32 v[142:143], v[58:59], v[204:205] op_sel_hi:[1,0]
	v_add_u32_e32 v148, s9, v147
	v_pk_mul_f32 v[132:133], v[56:57], v[204:205] op_sel_hi:[1,0]
	v_pk_mul_f32 v[130:131], v[54:55], v[204:205] op_sel_hi:[1,0]
	v_pk_mul_f32 v[136:137], v[52:53], v[204:205] op_sel_hi:[1,0]
	v_pk_mul_f32 v[134:135], v[50:51], v[204:205] op_sel_hi:[1,0]
	v_cvt_pk_bf16_f32 v154, v138, v139
	v_cvt_pk_bf16_f32 v155, v140, v141
	v_cvt_pk_bf16_f32 v156, v142, v143
	v_cvt_pk_bf16_f32 v157, v144, v145
	v_cvt_pk_bf16_f32 v164, v130, v131
	v_cvt_pk_bf16_f32 v165, v132, v133
	v_cvt_pk_bf16_f32 v166, v134, v135
	v_cvt_pk_bf16_f32 v167, v136, v137
	ds_write_b128 v151, v[154:157]
	ds_write_b128 v152, v[164:167]
	v_ashrrev_i32_e32 v149, 31, v148
	ds_read_b128 v[154:157], v150
	ds_read_b128 v[164:167], v150 offset:1024
	v_lshlrev_b64 v[160:161], 10, v[148:149]
	v_lshl_add_u64 v[160:161], s[26:27], 0, v[160:161]
	v_lshl_add_u64 v[160:161], v[160:161], 0, s[12:13]
	v_lshl_add_u64 v[160:161], v[160:161], 0, v[184:185]
	s_waitcnt lgkmcnt(1)
	global_store_dwordx4 v[160:161], v[154:157], off sc1
	s_nop 1
	v_add_co_u32_e32 v154, vcc, 0x2000, v160
	s_nop 1
	v_addc_co_u32_e32 v155, vcc, 0, v161, vcc
	s_and_b64 vcc, exec, s[6:7]
	s_waitcnt lgkmcnt(0)
	global_store_dwordx4 v[154:155], v[164:167], off sc1
	s_cbranch_vccnz .LBB0_468
	v_add_u32_e32 v154, s77, v226
	v_add_u32_e32 v155, s77, v225
	v_add_u32_e32 v148, 0xffff0000, v148
	v_add_u32_e32 v147, s0, v147
	s_add_u32 s1, s78, s44
	ds_write_b128 v154, v[138:141]
	ds_write_b128 v155, v[142:145]
	s_addc_u32 s33, s79, s45
	v_cndmask_b32_e64 v148, v147, v148, s[4:5]
	ds_read_b128 v[138:141], v150
	s_and_b64 s[46:47], s[4:5], exec
	v_ashrrev_i32_e32 v149, 31, v148
	s_cselect_b32 s47, s81, s33
	s_cselect_b32 s46, s80, s1
	v_lshlrev_b64 v[148:149], 11, v[148:149]
	v_lshl_add_u64 v[142:143], s[46:47], 0, v[148:149]
	v_mov_b32_e32 v147, v185
	v_lshl_add_u64 v[148:149], v[142:143], 0, v[146:147]
	ds_read_b128 v[142:145], v150 offset:1024
	s_waitcnt lgkmcnt(1)
	global_store_dwordx4 v[148:149], v[138:141], off nt
	ds_write_b128 v154, v[130:133]
	ds_write_b128 v155, v[134:137]
	ds_read_b128 v[130:133], v150
	ds_read_b128 v[134:137], v150 offset:1024
	v_add_co_u32_e32 v138, vcc, 0x4000, v148
	s_nop 1
	v_addc_co_u32_e32 v139, vcc, 0, v149, vcc
	s_waitcnt lgkmcnt(4)
	global_store_dwordx4 v[138:139], v[142:145], off nt
	s_waitcnt lgkmcnt(1)
	global_store_dwordx4 v[148:149], v[130:133], off offset:128 nt
	s_waitcnt lgkmcnt(0)
	global_store_dwordx4 v[138:139], v[134:137], off offset:128 nt
.LBB0_468:
	v_add_u32_e32 v147, 0x90, v153
	v_pk_mul_f32 v[140:141], v[48:49], v[202:203] op_sel_hi:[1,0]
	v_pk_mul_f32 v[138:139], v[46:47], v[202:203] op_sel_hi:[1,0]
	v_pk_mul_f32 v[144:145], v[44:45], v[202:203] op_sel_hi:[1,0]
	v_pk_mul_f32 v[142:143], v[42:43], v[202:203] op_sel_hi:[1,0]
	v_add_u32_e32 v148, s9, v147
	v_pk_mul_f32 v[132:133], v[40:41], v[202:203] op_sel_hi:[1,0]
	v_pk_mul_f32 v[130:131], v[38:39], v[202:203] op_sel_hi:[1,0]
	v_pk_mul_f32 v[136:137], v[36:37], v[202:203] op_sel_hi:[1,0]
	v_pk_mul_f32 v[134:135], v[34:35], v[202:203] op_sel_hi:[1,0]
	v_cvt_pk_bf16_f32 v154, v138, v139
	v_cvt_pk_bf16_f32 v155, v140, v141
	v_cvt_pk_bf16_f32 v156, v142, v143
	v_cvt_pk_bf16_f32 v157, v144, v145
	v_cvt_pk_bf16_f32 v164, v130, v131
	v_cvt_pk_bf16_f32 v165, v132, v133
	v_cvt_pk_bf16_f32 v166, v134, v135
	v_cvt_pk_bf16_f32 v167, v136, v137
	ds_write_b128 v151, v[154:157]
	ds_write_b128 v152, v[164:167]
	v_ashrrev_i32_e32 v149, 31, v148
	ds_read_b128 v[154:157], v150
	ds_read_b128 v[164:167], v150 offset:1024
	v_lshlrev_b64 v[160:161], 10, v[148:149]
	v_lshl_add_u64 v[160:161], s[26:27], 0, v[160:161]
	v_lshl_add_u64 v[160:161], v[160:161], 0, s[12:13]
	v_lshl_add_u64 v[160:161], v[160:161], 0, v[184:185]
	s_waitcnt lgkmcnt(1)
	global_store_dwordx4 v[160:161], v[154:157], off sc1
	s_nop 1
	v_add_co_u32_e32 v154, vcc, 0x2000, v160
	s_nop 1
	v_addc_co_u32_e32 v155, vcc, 0, v161, vcc
	s_and_b64 vcc, exec, s[6:7]
	s_waitcnt lgkmcnt(0)
	global_store_dwordx4 v[154:155], v[164:167], off sc1
	s_cbranch_vccnz .LBB0_470
	v_add_u32_e32 v154, s77, v226
	v_add_u32_e32 v155, s77, v225
	v_add_u32_e32 v148, 0xffff0000, v148
	v_add_u32_e32 v147, s0, v147
	s_add_u32 s1, s78, s44
	ds_write_b128 v154, v[138:141]
	ds_write_b128 v155, v[142:145]
	s_addc_u32 s33, s79, s45
	v_cndmask_b32_e64 v148, v147, v148, s[4:5]
	ds_read_b128 v[138:141], v150
	s_and_b64 s[46:47], s[4:5], exec
	v_ashrrev_i32_e32 v149, 31, v148
	s_cselect_b32 s47, s81, s33
	s_cselect_b32 s46, s80, s1
	v_lshlrev_b64 v[148:149], 11, v[148:149]
	v_lshl_add_u64 v[142:143], s[46:47], 0, v[148:149]
	v_mov_b32_e32 v147, v185
	v_lshl_add_u64 v[148:149], v[142:143], 0, v[146:147]
	ds_read_b128 v[142:145], v150 offset:1024
	s_waitcnt lgkmcnt(1)
	global_store_dwordx4 v[148:149], v[138:141], off nt
	ds_write_b128 v154, v[130:133]
	ds_write_b128 v155, v[134:137]
	ds_read_b128 v[130:133], v150
	ds_read_b128 v[134:137], v150 offset:1024
	v_add_co_u32_e32 v138, vcc, 0x4000, v148
	s_nop 1
	v_addc_co_u32_e32 v139, vcc, 0, v149, vcc
	s_waitcnt lgkmcnt(4)
	global_store_dwordx4 v[138:139], v[142:145], off nt
	s_waitcnt lgkmcnt(1)
	global_store_dwordx4 v[148:149], v[130:133], off offset:128 nt
	s_waitcnt lgkmcnt(0)
	global_store_dwordx4 v[138:139], v[134:137], off offset:128 nt
; __device__ __forceinline__ v4u pack8(const f32x4 a, const f32x4 b) { v4u w; w.x = pk2(a[0], a[1]); w.y = pk2(a[2], a[3]); w.z = pk2(b[0], b[1]); w.w = pk2(b[2], b[3]); return w; }
;     __device__ __forceinline__ void operator()(const f32x4 (&acc)[2][2][4][2], const pg8::Unit& u, int wr, int wc, int fr, int fq) const {
;     ...
;         } else if (pn < 6) {
;             const int head = 4 * (pn & 1) + wc;
;             const bool wout = sample || (pm & 15) >= 8;
; #pragma unroll
;             for (int ai = 0; ai < 2; ++ai)
; #pragma unroll
;                 for (int m = 0; m < 4; ++m) {
;                     const int rl = 128 * ai + 64 * wr + 16 * m + tt.rr, rowa = 256 * pm + rl;
;                     const float rs = rs8[ai][m];
;                     const f32x4 a0 = acc[ai][0][m][0] * rs, a1 = acc[ai][0][m][1] * rs, b0 = acc[ai][1][m][0] * rs, b1 = acc[ai][1][m][1] * rs;
;                     { v4u a, b; tt.bf(pack8(a0, a1), pack8(b0, b1), a, b);
;                       bf16* d = (bf16*)(ws + WS_V) + (size_t)rowa * DA + head * 64 + 8 * tt.p; *(v4u*)d = a; *(v4u*)(d + 8 * DA) = b; }
;                     if (wout) {
;                         float* op = sample ? out + OUT_VNEW + (size_t)(rowa - MP) * DA : out + OUT_VWIN + ((size_t)(pm >> 4) * WIN + (256 * (pm & 15) + rl - (SEQ - WIN))) * DA;
;                         op += head * 64 + 4 * tt.p;
;                         f32x4 a, b; tt.f4(a0, a1, a, b); *(f32x4*)op = a; *(f32x4*)(op + 8 * DA) = b;
;                         tt.f4(b0, b1, a, b); *(f32x4*)(op + 32) = a; *(f32x4*)(op + 32 + 8 * DA) = b;
;                     }
;                 }
.LBB0_470:
	v_add_u32_e32 v147, 0xa0, v153
	v_pk_mul_f32 v[140:141], v[32:33], v[198:199] op_sel_hi:[1,0]
	v_pk_mul_f32 v[138:139], v[30:31], v[198:199] op_sel_hi:[1,0]
	v_pk_mul_f32 v[144:145], v[28:29], v[198:199] op_sel_hi:[1,0]
	v_pk_mul_f32 v[142:143], v[26:27], v[198:199] op_sel_hi:[1,0]
	v_add_u32_e32 v148, s9, v147
	v_pk_mul_f32 v[132:133], v[24:25], v[198:199] op_sel_hi:[1,0]
	v_pk_mul_f32 v[130:131], v[22:23], v[198:199] op_sel_hi:[1,0]
	v_pk_mul_f32 v[136:137], v[20:21], v[198:199] op_sel_hi:[1,0]
	v_pk_mul_f32 v[134:135], v[18:19], v[198:199] op_sel_hi:[1,0]
	v_cvt_pk_bf16_f32 v154, v138, v139
	v_cvt_pk_bf16_f32 v155, v140, v141
	v_cvt_pk_bf16_f32 v156, v142, v143
	v_cvt_pk_bf16_f32 v157, v144, v145
	v_cvt_pk_bf16_f32 v164, v130, v131
	v_cvt_pk_bf16_f32 v165, v132, v133
	v_cvt_pk_bf16_f32 v166, v134, v135
	v_cvt_pk_bf16_f32 v167, v136, v137
	ds_write_b128 v151, v[154:157]
	ds_write_b128 v152, v[164:167]
	v_ashrrev_i32_e32 v149, 31, v148
	ds_read_b128 v[154:157], v150
	ds_read_b128 v[164:167], v150 offset:1024
	v_lshlrev_b64 v[160:161], 10, v[148:149]
	v_lshl_add_u64 v[160:161], s[26:27], 0, v[160:161]
	v_lshl_add_u64 v[160:161], v[160:161], 0, s[12:13]
	v_lshl_add_u64 v[160:161], v[160:161], 0, v[184:185]
	s_waitcnt lgkmcnt(1)
	global_store_dwordx4 v[160:161], v[154:157], off sc1
	s_nop 1
	v_add_co_u32_e32 v154, vcc, 0x2000, v160
	s_nop 1
	v_addc_co_u32_e32 v155, vcc, 0, v161, vcc
	s_and_b64 vcc, exec, s[6:7]
	s_waitcnt lgkmcnt(0)
	global_store_dwordx4 v[154:155], v[164:167], off sc1
	s_cbranch_vccnz .LBB0_472
	v_add_u32_e32 v154, s77, v226
	v_add_u32_e32 v155, s77, v225
	v_add_u32_e32 v148, 0xffff0000, v148
	v_add_u32_e32 v147, s0, v147
	s_add_u32 s1, s78, s44
	ds_write_b128 v154, v[138:141]
	ds_write_b128 v155, v[142:145]
	s_addc_u32 s33, s79, s45
	v_cndmask_b32_e64 v148, v147, v148, s[4:5]
	ds_read_b128 v[138:141], v150
	s_and_b64 s[46:47], s[4:5], exec
	v_ashrrev_i32_e32 v149, 31, v148
	s_cselect_b32 s47, s81, s33
	s_cselect_b32 s46, s80, s1
	v_lshlrev_b64 v[148:149], 11, v[148:149]
	v_lshl_add_u64 v[142:143], s[46:47], 0, v[148:149]
	v_mov_b32_e32 v147, v185
	v_lshl_add_u64 v[148:149], v[142:143], 0, v[146:147]
	ds_read_b128 v[142:145], v150 offset:1024
	s_waitcnt lgkmcnt(1)
	global_store_dwordx4 v[148:149], v[138:141], off nt
	ds_write_b128 v154, v[130:133]
	ds_write_b128 v155, v[134:137]
	ds_read_b128 v[130:133], v150
	ds_read_b128 v[134:137], v150 offset:1024
	v_add_co_u32_e32 v138, vcc, 0x4000, v148
	s_nop 1
	v_addc_co_u32_e32 v139, vcc, 0, v149, vcc
	s_waitcnt lgkmcnt(4)
	global_store_dwordx4 v[138:139], v[142:145], off nt
	s_waitcnt lgkmcnt(1)
	global_store_dwordx4 v[148:149], v[130:133], off offset:128 nt
	s_waitcnt lgkmcnt(0)
	global_store_dwordx4 v[138:139], v[134:137], off offset:128 nt
.LBB0_472:
	v_add_u32_e32 v147, 0xb0, v153
	v_pk_mul_f32 v[140:141], v[16:17], v[196:197] op_sel_hi:[1,0]
	v_pk_mul_f32 v[138:139], v[14:15], v[196:197] op_sel_hi:[1,0]
	v_pk_mul_f32 v[144:145], v[12:13], v[196:197] op_sel_hi:[1,0]
	v_pk_mul_f32 v[142:143], v[10:11], v[196:197] op_sel_hi:[1,0]
	v_add_u32_e32 v148, s9, v147
	v_pk_mul_f32 v[132:133], v[8:9], v[196:197] op_sel_hi:[1,0]
	v_pk_mul_f32 v[130:131], v[6:7], v[196:197] op_sel_hi:[1,0]
	v_pk_mul_f32 v[136:137], v[4:5], v[196:197] op_sel_hi:[1,0]
	v_pk_mul_f32 v[134:135], v[2:3], v[196:197] op_sel_hi:[1,0]
	v_cvt_pk_bf16_f32 v154, v138, v139
	v_cvt_pk_bf16_f32 v155, v140, v141
	v_cvt_pk_bf16_f32 v156, v142, v143
	v_cvt_pk_bf16_f32 v157, v144, v145
	v_cvt_pk_bf16_f32 v164, v130, v131
	v_cvt_pk_bf16_f32 v165, v132, v133
	v_cvt_pk_bf16_f32 v166, v134, v135
	v_cvt_pk_bf16_f32 v167, v136, v137
	ds_write_b128 v151, v[154:157]
	ds_write_b128 v152, v[164:167]
	v_ashrrev_i32_e32 v149, 31, v148
	ds_read_b128 v[152:155], v150
	ds_read_b128 v[164:167], v150 offset:1024
	v_lshlrev_b64 v[156:157], 10, v[148:149]
	v_lshl_add_u64 v[156:157], s[26:27], 0, v[156:157]
	v_lshl_add_u64 v[156:157], v[156:157], 0, s[12:13]
	v_lshl_add_u64 v[156:157], v[156:157], 0, v[184:185]
	s_waitcnt lgkmcnt(1)
	global_store_dwordx4 v[156:157], v[152:155], off sc1
	s_nop 1
	v_add_co_u32_e32 v152, vcc, 0x2000, v156
	s_nop 1
	v_addc_co_u32_e32 v153, vcc, 0, v157, vcc
	s_and_b64 vcc, exec, s[6:7]
	s_waitcnt lgkmcnt(0)
	global_store_dwordx4 v[152:153], v[164:167], off sc1
	s_cbranch_vccnz .LBB0_474
	v_add_u32_e32 v151, s77, v226
	v_add_u32_e32 v152, s77, v225
	v_add_u32_e32 v148, 0xffff0000, v148
	v_add_u32_e32 v147, s0, v147
	s_add_u32 s6, s78, s44
	ds_write_b128 v151, v[138:141]
	ds_write_b128 v152, v[142:145]
	s_addc_u32 s7, s79, s45
	v_cndmask_b32_e64 v148, v147, v148, s[4:5]
	ds_read_b128 v[138:141], v150
	s_and_b64 s[0:1], s[4:5], exec
	v_ashrrev_i32_e32 v149, 31, v148
	s_cselect_b32 s1, s81, s7
	s_cselect_b32 s0, s80, s6
	v_lshlrev_b64 v[148:149], 11, v[148:149]
	v_lshl_add_u64 v[142:143], s[0:1], 0, v[148:149]
	v_mov_b32_e32 v147, v185
	v_lshl_add_u64 v[146:147], v[142:143], 0, v[146:147]
	ds_read_b128 v[142:145], v150 offset:1024
	s_waitcnt lgkmcnt(1)
	global_store_dwordx4 v[146:147], v[138:141], off nt
	ds_write_b128 v151, v[130:133]
	ds_write_b128 v152, v[134:137]
	ds_read_b128 v[130:133], v150
	ds_read_b128 v[134:137], v150 offset:1024
	v_add_co_u32_e32 v138, vcc, 0x4000, v146
	s_nop 1
	v_addc_co_u32_e32 v139, vcc, 0, v147, vcc
	s_waitcnt lgkmcnt(4)
	global_store_dwordx4 v[138:139], v[142:145], off nt
	s_waitcnt lgkmcnt(1)
	global_store_dwordx4 v[146:147], v[130:133], off offset:128 nt
	s_waitcnt lgkmcnt(0)
	global_store_dwordx4 v[138:139], v[134:137], off offset:128 nt

; __device__ __forceinline__ v4u pack8(const f32x4 a, const f32x4 b) { v4u w; w.x = pk2(a[0], a[1]); w.y = pk2(a[2], a[3]); w.z = pk2(b[0], b[1]); w.w = pk2(b[2], b[3]); return w; }
;     __device__ __forceinline__ void operator()(const f32x4 (&acc)[2][2][4][2], const pg8::Unit& u, int wr, int wc, int fr, int fq) const {
;     ...
;             bf16* dst = (bf16*)(ws + (isq ? WS_Q : WS_K));
;             const bool wout = !isq && (sample || (pm & 15) >= 8);
;     ...
;                     const int rowa = 256 * pm + 128 * ai + 64 * wr + 16 * m + tt.rr;
;                     { v4u a, b; if (isq) tt.bf(pack8(o1[0] * QSCALE, o1[1] * QSCALE), pack8(o2[0] * QSCALE, o2[1] * QSCALE), a, b); else tt.bf(pack8(o1[0], o1[1]), pack8(o2[0], o2[1]), a, b);
;                       bf16* d = dst + (size_t)rowa * DA + head * 64 + 8 * tt.p; *(v4u*)d = a; *(v4u*)(d + 8 * DA) = b; }
;                     if (wout) {
;                         const int rl = 128 * ai + 64 * wr + 16 * m + tt.rr;
;                         float* op = sample ? out + OUT_KNEW + (size_t)(rowa - MP) * DA : out + OUT_KWIN + ((size_t)(pm >> 4) * WIN + (256 * (pm & 15) + rl - (SEQ - WIN))) * DA;
;                         op += head * 64 + 4 * tt.p;
;                         f32x4 a, b; tt.f4(o1[0], o1[1], a, b); *(f32x4*)op = a; *(f32x4*)(op + 8 * DA) = b;
;                         tt.f4(o2[0], o2[1], a, b); *(f32x4*)(op + 32) = a; *(f32x4*)(op + 32 + 8 * DA) = b;
;                     }
.LBB0_480:
	s_lshl_b32 s1, s42, 2
	s_and_b32 s1, s1, 4
	s_and_b64 s[6:7], s[46:47], exec
	s_cselect_b32 s12, s93, 0xa000000
	s_bitcmp1_b32 s8, 3
	s_cselect_b64 s[6:7], -1, 0
	s_or_b64 s[6:7], s[4:5], s[6:7]
	s_or_b32 s1, s1, s65
	s_add_u32 s12, s58, s12
	s_addc_u32 s33, s59, 0
	s_add_i32 s9, s9, s66
	v_cvt_pk_bf16_f32 v232, v166, v167
	v_add_u32_e32 v166, s77, v229
	s_and_b64 s[46:47], s[46:47], s[6:7]
	v_add_u32_e32 v212, s9, v227
	s_lshl_b32 s9, s1, 6
	s_lshl_b32 s1, s1, 7
	v_cvt_pk_bf16_f32 v233, v168, v169
	v_cvt_pk_bf16_f32 v234, v170, v171
	v_cvt_pk_bf16_f32 v235, v172, v173
	ds_write_b128 v166, v[162:165]
	v_add_u32_e32 v165, s77, v228
	s_add_u32 s6, s12, s1
	ds_write_b128 v165, v[232:235]
	v_add_u32_e32 v162, s77, v230
	s_addc_u32 s7, s33, 0
	v_lshlrev_b32_e32 v184, 4, v213
	ds_read_b128 v[168:171], v162
	ds_read_b128 v[228:231], v162 offset:1024
	v_lshl_add_u64 v[214:215], s[6:7], 0, v[184:185]
	v_lshl_or_b32 v184, v213, 2, s9
	v_ashrrev_i32_e32 v213, 31, v212
	v_lshlrev_b64 v[172:173], 10, v[212:213]
	v_lshl_add_u64 v[172:173], v[214:215], 0, v[172:173]
	s_ashr_i32 s6, s8, 4
	s_waitcnt lgkmcnt(1)
	global_store_dwordx4 v[172:173], v[168:171], off sc1
	s_ashr_i32 s7, s6, 31
	s_add_i32 s0, s70, s0
	v_add_co_u32_e32 v168, vcc, 0x2000, v172
	v_cndmask_b32_e64 v163, 0, 1, s[46:47]
	s_nop 0
	v_addc_co_u32_e32 v169, vcc, 0, v173, vcc
	v_add_u32_e32 v199, s0, v227
	s_lshl_b64 s[42:43], s[6:7], 22
	v_cmp_ne_u32_e64 s[6:7], 1, v163
	s_andn2_b64 vcc, exec, s[46:47]
	v_add_u32_e32 v163, s77, v226
	v_add_u32_e32 v164, s77, v225
	v_lshlrev_b32_e32 v184, 2, v184
	s_waitcnt lgkmcnt(0)
	global_store_dwordx4 v[168:169], v[228:231], off sc1
	s_cbranch_vccnz .LBB0_482
	s_add_u32 s8, s82, s42
	v_add_u32_e32 v167, 0xffff0000, v212
	ds_write_b128 v163, v[118:121]
	ds_write_b128 v164, v[126:129]
	s_addc_u32 s9, s83, s43
	v_cndmask_b32_e64 v168, v199, v167, s[4:5]
	ds_read_b128 v[118:121], v162
	s_and_b64 s[0:1], s[4:5], exec
	v_ashrrev_i32_e32 v169, 31, v168
	s_cselect_b32 s1, s85, s9
	s_cselect_b32 s0, s84, s8
	v_lshlrev_b64 v[126:127], 11, v[168:169]
	v_lshl_add_u64 v[126:127], s[0:1], 0, v[126:127]
	v_lshl_add_u64 v[168:169], v[126:127], 0, v[184:185]
	ds_read_b128 v[126:129], v162 offset:1024
	s_waitcnt lgkmcnt(1)
	global_store_dwordx4 v[168:169], v[118:121], off nt
	ds_write_b128 v163, v[114:117]
	ds_write_b128 v164, v[122:125]
	ds_read_b128 v[114:117], v162
	ds_read_b128 v[118:121], v162 offset:1024
	v_add_co_u32_e32 v170, vcc, 0x4000, v168
	s_nop 1
	v_addc_co_u32_e32 v171, vcc, 0, v169, vcc
	s_waitcnt lgkmcnt(4)
	global_store_dwordx4 v[170:171], v[126:129], off nt
	s_waitcnt lgkmcnt(1)
	global_store_dwordx4 v[168:169], v[114:117], off offset:128 nt
	s_waitcnt lgkmcnt(0)
	global_store_dwordx4 v[170:171], v[118:121], off offset:128 nt

; __device__ __forceinline__ v4u pack8(const f32x4 a, const f32x4 b) { v4u w; w.x = pk2(a[0], a[1]); w.y = pk2(a[2], a[3]); w.z = pk2(b[0], b[1]); w.w = pk2(b[2], b[3]); return w; }
;     __device__ __forceinline__ void operator()(const f32x4 (&acc)[2][2][4][2], const pg8::Unit& u, int wr, int wc, int fr, int fq) const {
;     ...
;                     const int rowa = 256 * pm + 128 * ai + 64 * wr + 16 * m + tt.rr;
;                     { v4u a, b; if (isq) tt.bf(pack8(o1[0] * QSCALE, o1[1] * QSCALE), pack8(o2[0] * QSCALE, o2[1] * QSCALE), a, b); else tt.bf(pack8(o1[0], o1[1]), pack8(o2[0], o2[1]), a, b);
;                       bf16* d = dst + (size_t)rowa * DA + head * 64 + 8 * tt.p; *(v4u*)d = a; *(v4u*)(d + 8 * DA) = b; }
;                     if (wout) {
;                         const int rl = 128 * ai + 64 * wr + 16 * m + tt.rr;
;                         float* op = sample ? out + OUT_KNEW + (size_t)(rowa - MP) * DA : out + OUT_KWIN + ((size_t)(pm >> 4) * WIN + (256 * (pm & 15) + rl - (SEQ - WIN))) * DA;
;                         op += head * 64 + 4 * tt.p;
;                         f32x4 a, b; tt.f4(o1[0], o1[1], a, b); *(f32x4*)op = a; *(f32x4*)(op + 8 * DA) = b;
;                         tt.f4(o2[0], o2[1], a, b); *(f32x4*)(op + 32) = a; *(f32x4*)(op + 32 + 8 * DA) = b;
;                     }
.LBB0_486:
	v_cvt_pk_bf16_f32 v150, v150, v151
	v_cvt_pk_bf16_f32 v151, v152, v153
	v_cvt_pk_bf16_f32 v152, v154, v155
	v_cvt_pk_bf16_f32 v153, v156, v157
	ds_write_b128 v166, v[146:149]
	ds_write_b128 v165, v[150:153]
	v_add_u32_e32 v158, 16, v212
	ds_read_b128 v[146:149], v162
	ds_read_b128 v[150:153], v162 offset:1024
	v_ashrrev_i32_e32 v159, 31, v158
	v_lshlrev_b64 v[154:155], 10, v[158:159]
	v_lshl_add_u64 v[154:155], v[214:215], 0, v[154:155]
	s_waitcnt lgkmcnt(1)
	global_store_dwordx4 v[154:155], v[146:149], off sc1
	s_nop 1
	v_add_co_u32_e32 v146, vcc, 0x2000, v154
	s_nop 1
	v_addc_co_u32_e32 v147, vcc, 0, v155, vcc
	s_and_b64 vcc, exec, s[6:7]
	s_waitcnt lgkmcnt(0)
	global_store_dwordx4 v[146:147], v[150:153], off sc1
	s_cbranch_vccnz .LBB0_488
	v_add_u32_e32 v146, 0xffff0010, v212
	v_add_u32_e32 v147, 16, v199
	s_add_u32 s12, s82, s42
	ds_write_b128 v163, v[102:105]
	ds_write_b128 v164, v[110:113]
	s_addc_u32 s33, s83, s43
	v_cndmask_b32_e64 v146, v147, v146, s[4:5]
	ds_read_b128 v[102:105], v162
	s_and_b64 s[0:1], s[4:5], exec
	v_ashrrev_i32_e32 v147, 31, v146
	s_cselect_b32 s1, s85, s33
	s_cselect_b32 s0, s84, s12
	v_lshlrev_b64 v[110:111], 11, v[146:147]
	v_lshl_add_u64 v[110:111], s[0:1], 0, v[110:111]
	v_lshl_add_u64 v[146:147], v[110:111], 0, v[184:185]
	ds_read_b128 v[110:113], v162 offset:1024
	s_waitcnt lgkmcnt(1)
	global_store_dwordx4 v[146:147], v[102:105], off nt
	ds_write_b128 v163, v[98:101]
	ds_write_b128 v164, v[106:109]
	ds_read_b128 v[98:101], v162
	ds_read_b128 v[102:105], v162 offset:1024
	v_add_co_u32_e32 v148, vcc, 0x4000, v146
	s_nop 1
	v_addc_co_u32_e32 v149, vcc, 0, v147, vcc
	s_waitcnt lgkmcnt(4)
	global_store_dwordx4 v[148:149], v[110:113], off nt
	s_waitcnt lgkmcnt(1)
	global_store_dwordx4 v[146:147], v[98:101], off offset:128 nt
	s_waitcnt lgkmcnt(0)
	global_store_dwordx4 v[148:149], v[102:105], off offset:128 nt

; __device__ __forceinline__ v4u pack8(const f32x4 a, const f32x4 b) { v4u w; w.x = pk2(a[0], a[1]); w.y = pk2(a[2], a[3]); w.z = pk2(b[0], b[1]); w.w = pk2(b[2], b[3]); return w; }
;     __device__ __forceinline__ void operator()(const f32x4 (&acc)[2][2][4][2], const pg8::Unit& u, int wr, int wc, int fr, int fq) const {
;     ...
;                     const int rowa = 256 * pm + 128 * ai + 64 * wr + 16 * m + tt.rr;
;                     { v4u a, b; if (isq) tt.bf(pack8(o1[0] * QSCALE, o1[1] * QSCALE), pack8(o2[0] * QSCALE, o2[1] * QSCALE), a, b); else tt.bf(pack8(o1[0], o1[1]), pack8(o2[0], o2[1]), a, b);
;                       bf16* d = dst + (size_t)rowa * DA + head * 64 + 8 * tt.p; *(v4u*)d = a; *(v4u*)(d + 8 * DA) = b; }
;                     if (wout) {
;                         const int rl = 128 * ai + 64 * wr + 16 * m + tt.rr;
;                         float* op = sample ? out + OUT_KNEW + (size_t)(rowa - MP) * DA : out + OUT_KWIN + ((size_t)(pm >> 4) * WIN + (256 * (pm & 15) + rl - (SEQ - WIN))) * DA;
;                         op += head * 64 + 4 * tt.p;
;                         f32x4 a, b; tt.f4(o1[0], o1[1], a, b); *(f32x4*)op = a; *(f32x4*)(op + 8 * DA) = b;
;                         tt.f4(o2[0], o2[1], a, b); *(f32x4*)(op + 32) = a; *(f32x4*)(op + 32 + 8 * DA) = b;
;                     }
.LBB0_492:
	v_cvt_pk_bf16_f32 v118, v118, v119
	v_cvt_pk_bf16_f32 v119, v120, v121
	v_cvt_pk_bf16_f32 v120, v122, v123
	v_cvt_pk_bf16_f32 v121, v124, v125
	ds_write_b128 v166, v[114:117]
	ds_write_b128 v165, v[118:121]
	v_add_u32_e32 v126, 32, v212
	ds_read_b128 v[114:117], v162
	ds_read_b128 v[118:121], v162 offset:1024
	v_ashrrev_i32_e32 v127, 31, v126
	v_lshlrev_b64 v[122:123], 10, v[126:127]
	v_lshl_add_u64 v[122:123], v[214:215], 0, v[122:123]
	s_waitcnt lgkmcnt(1)
	global_store_dwordx4 v[122:123], v[114:117], off sc1
	s_nop 1
	v_add_co_u32_e32 v114, vcc, 0x2000, v122
	s_nop 1
	v_addc_co_u32_e32 v115, vcc, 0, v123, vcc
	s_and_b64 vcc, exec, s[6:7]
	s_waitcnt lgkmcnt(0)
	global_store_dwordx4 v[114:115], v[118:121], off sc1
	s_cbranch_vccnz .LBB0_494
	v_add_u32_e32 v114, 0xffff0020, v212
	v_add_u32_e32 v115, 32, v199
	s_add_u32 s12, s82, s42
	ds_write_b128 v163, v[86:89]
	ds_write_b128 v164, v[94:97]
	s_addc_u32 s33, s83, s43
	v_cndmask_b32_e64 v114, v115, v114, s[4:5]
	ds_read_b128 v[86:89], v162
	s_and_b64 s[0:1], s[4:5], exec
	v_ashrrev_i32_e32 v115, 31, v114
	s_cselect_b32 s1, s85, s33
	s_cselect_b32 s0, s84, s12
	v_lshlrev_b64 v[94:95], 11, v[114:115]
	v_lshl_add_u64 v[94:95], s[0:1], 0, v[94:95]
	v_lshl_add_u64 v[114:115], v[94:95], 0, v[184:185]
	ds_read_b128 v[94:97], v162 offset:1024
	s_waitcnt lgkmcnt(1)
	global_store_dwordx4 v[114:115], v[86:89], off nt
	ds_write_b128 v163, v[82:85]
	ds_write_b128 v164, v[90:93]
	ds_read_b128 v[82:85], v162
	ds_read_b128 v[86:89], v162 offset:1024
	v_add_co_u32_e32 v116, vcc, 0x4000, v114
	s_nop 1
	v_addc_co_u32_e32 v117, vcc, 0, v115, vcc
	s_waitcnt lgkmcnt(4)
	global_store_dwordx4 v[116:117], v[94:97], off nt
	s_waitcnt lgkmcnt(1)
	global_store_dwordx4 v[114:115], v[82:85], off offset:128 nt
	s_waitcnt lgkmcnt(0)
	global_store_dwordx4 v[116:117], v[86:89], off offset:128 nt

; __device__ __forceinline__ v4u pack8(const f32x4 a, const f32x4 b) { v4u w; w.x = pk2(a[0], a[1]); w.y = pk2(a[2], a[3]); w.z = pk2(b[0], b[1]); w.w = pk2(b[2], b[3]); return w; }
;     __device__ __forceinline__ void operator()(const f32x4 (&acc)[2][2][4][2], const pg8::Unit& u, int wr, int wc, int fr, int fq) const {
;     ...
;                     const int rowa = 256 * pm + 128 * ai + 64 * wr + 16 * m + tt.rr;
;                     { v4u a, b; if (isq) tt.bf(pack8(o1[0] * QSCALE, o1[1] * QSCALE), pack8(o2[0] * QSCALE, o2[1] * QSCALE), a, b); else tt.bf(pack8(o1[0], o1[1]), pack8(o2[0], o2[1]), a, b);
;                       bf16* d = dst + (size_t)rowa * DA + head * 64 + 8 * tt.p; *(v4u*)d = a; *(v4u*)(d + 8 * DA) = b; }
;                     if (wout) {
;                         const int rl = 128 * ai + 64 * wr + 16 * m + tt.rr;
;                         float* op = sample ? out + OUT_KNEW + (size_t)(rowa - MP) * DA : out + OUT_KWIN + ((size_t)(pm >> 4) * WIN + (256 * (pm & 15) + rl - (SEQ - WIN))) * DA;
;                         op += head * 64 + 4 * tt.p;
;                         f32x4 a, b; tt.f4(o1[0], o1[1], a, b); *(f32x4*)op = a; *(f32x4*)(op + 8 * DA) = b;
;                         tt.f4(o2[0], o2[1], a, b); *(f32x4*)(op + 32) = a; *(f32x4*)(op + 32 + 8 * DA) = b;
;                     }
.LBB0_498:
	v_cvt_pk_bf16_f32 v102, v102, v103
	v_cvt_pk_bf16_f32 v103, v104, v105
	v_cvt_pk_bf16_f32 v104, v106, v107
	v_cvt_pk_bf16_f32 v105, v108, v109
	ds_write_b128 v166, v[98:101]
	ds_write_b128 v165, v[102:105]
	v_add_u32_e32 v110, 48, v212
	ds_read_b128 v[98:101], v162
	ds_read_b128 v[102:105], v162 offset:1024
	v_ashrrev_i32_e32 v111, 31, v110
	v_lshlrev_b64 v[106:107], 10, v[110:111]
	v_lshl_add_u64 v[106:107], v[214:215], 0, v[106:107]
	s_waitcnt lgkmcnt(1)
	global_store_dwordx4 v[106:107], v[98:101], off sc1
	s_nop 1
	v_add_co_u32_e32 v98, vcc, 0x2000, v106
	s_nop 1
	v_addc_co_u32_e32 v99, vcc, 0, v107, vcc
	s_and_b64 vcc, exec, s[6:7]
	s_waitcnt lgkmcnt(0)
	global_store_dwordx4 v[98:99], v[102:105], off sc1
	s_cbranch_vccnz .LBB0_500
	v_add_u32_e32 v98, 0xffff0030, v212
	v_add_u32_e32 v99, 48, v199
	s_add_u32 s12, s82, s42
	ds_write_b128 v163, v[70:73]
	ds_write_b128 v164, v[78:81]
	s_addc_u32 s33, s83, s43
	v_cndmask_b32_e64 v98, v99, v98, s[4:5]
	ds_read_b128 v[70:73], v162
	s_and_b64 s[0:1], s[4:5], exec
	v_ashrrev_i32_e32 v99, 31, v98
	s_cselect_b32 s1, s85, s33
	s_cselect_b32 s0, s84, s12
	v_lshlrev_b64 v[78:79], 11, v[98:99]
	v_lshl_add_u64 v[78:79], s[0:1], 0, v[78:79]
	v_lshl_add_u64 v[98:99], v[78:79], 0, v[184:185]
	ds_read_b128 v[78:81], v162 offset:1024
	s_waitcnt lgkmcnt(1)
	global_store_dwordx4 v[98:99], v[70:73], off nt
	ds_write_b128 v163, v[66:69]
	ds_write_b128 v164, v[74:77]
	ds_read_b128 v[66:69], v162
	ds_read_b128 v[70:73], v162 offset:1024
	v_add_co_u32_e32 v100, vcc, 0x4000, v98
	s_nop 1
	v_addc_co_u32_e32 v101, vcc, 0, v99, vcc
	s_waitcnt lgkmcnt(4)
	global_store_dwordx4 v[100:101], v[78:81], off nt
	s_waitcnt lgkmcnt(1)
	global_store_dwordx4 v[98:99], v[66:69], off offset:128 nt
	s_waitcnt lgkmcnt(0)
	global_store_dwordx4 v[100:101], v[70:73], off offset:128 nt

; __device__ __forceinline__ v4u pack8(const f32x4 a, const f32x4 b) { v4u w; w.x = pk2(a[0], a[1]); w.y = pk2(a[2], a[3]); w.z = pk2(b[0], b[1]); w.w = pk2(b[2], b[3]); return w; }
;     __device__ __forceinline__ void operator()(const f32x4 (&acc)[2][2][4][2], const pg8::Unit& u, int wr, int wc, int fr, int fq) const {
;     ...
;                     const int rowa = 256 * pm + 128 * ai + 64 * wr + 16 * m + tt.rr;
;                     { v4u a, b; if (isq) tt.bf(pack8(o1[0] * QSCALE, o1[1] * QSCALE), pack8(o2[0] * QSCALE, o2[1] * QSCALE), a, b); else tt.bf(pack8(o1[0], o1[1]), pack8(o2[0], o2[1]), a, b);
;                       bf16* d = dst + (size_t)rowa * DA + head * 64 + 8 * tt.p; *(v4u*)d = a; *(v4u*)(d + 8 * DA) = b; }
;                     if (wout) {
;                         const int rl = 128 * ai + 64 * wr + 16 * m + tt.rr;
;                         float* op = sample ? out + OUT_KNEW + (size_t)(rowa - MP) * DA : out + OUT_KWIN + ((size_t)(pm >> 4) * WIN + (256 * (pm & 15) + rl - (SEQ - WIN))) * DA;
;                         op += head * 64 + 4 * tt.p;
;                         f32x4 a, b; tt.f4(o1[0], o1[1], a, b); *(f32x4*)op = a; *(f32x4*)(op + 8 * DA) = b;
;                         tt.f4(o2[0], o2[1], a, b); *(f32x4*)(op + 32) = a; *(f32x4*)(op + 32 + 8 * DA) = b;
;                     }
.LBB0_504:
	v_cvt_pk_bf16_f32 v86, v86, v87
	v_cvt_pk_bf16_f32 v87, v88, v89
	v_cvt_pk_bf16_f32 v88, v90, v91
	v_cvt_pk_bf16_f32 v89, v92, v93
	ds_write_b128 v166, v[82:85]
	ds_write_b128 v165, v[86:89]
	v_add_u32_e32 v94, 0x80, v212
	ds_read_b128 v[82:85], v162
	ds_read_b128 v[86:89], v162 offset:1024
	v_ashrrev_i32_e32 v95, 31, v94
	v_lshlrev_b64 v[90:91], 10, v[94:95]
	v_lshl_add_u64 v[90:91], v[214:215], 0, v[90:91]
	s_waitcnt lgkmcnt(1)
	global_store_dwordx4 v[90:91], v[82:85], off sc1
	s_nop 1
	v_add_co_u32_e32 v82, vcc, 0x2000, v90
	s_nop 1
	v_addc_co_u32_e32 v83, vcc, 0, v91, vcc
	s_and_b64 vcc, exec, s[6:7]
	s_waitcnt lgkmcnt(0)
	global_store_dwordx4 v[82:83], v[86:89], off sc1
	s_cbranch_vccnz .LBB0_506
	v_add_u32_e32 v82, 0x80, v199
	v_add_u32_e32 v83, 0xffff0080, v212
	s_add_u32 s12, s82, s42
	ds_write_b128 v163, v[54:57]
	ds_write_b128 v164, v[62:65]
	s_addc_u32 s33, s83, s43
	v_cndmask_b32_e64 v82, v82, v83, s[4:5]
	ds_read_b128 v[54:57], v162
	s_and_b64 s[0:1], s[4:5], exec
	v_ashrrev_i32_e32 v83, 31, v82
	s_cselect_b32 s1, s85, s33
	s_cselect_b32 s0, s84, s12
	v_lshlrev_b64 v[62:63], 11, v[82:83]
	v_lshl_add_u64 v[62:63], s[0:1], 0, v[62:63]
	v_lshl_add_u64 v[82:83], v[62:63], 0, v[184:185]
	ds_read_b128 v[62:65], v162 offset:1024
	s_waitcnt lgkmcnt(1)
	global_store_dwordx4 v[82:83], v[54:57], off nt
	ds_write_b128 v163, v[50:53]
	ds_write_b128 v164, v[58:61]
	ds_read_b128 v[50:53], v162
	ds_read_b128 v[54:57], v162 offset:1024
	v_add_co_u32_e32 v84, vcc, 0x4000, v82
	s_nop 1
	v_addc_co_u32_e32 v85, vcc, 0, v83, vcc
	s_waitcnt lgkmcnt(4)
	global_store_dwordx4 v[84:85], v[62:65], off nt
	s_waitcnt lgkmcnt(1)
	global_store_dwordx4 v[82:83], v[50:53], off offset:128 nt
	s_waitcnt lgkmcnt(0)
	global_store_dwordx4 v[84:85], v[54:57], off offset:128 nt

; __device__ __forceinline__ v4u pack8(const f32x4 a, const f32x4 b) { v4u w; w.x = pk2(a[0], a[1]); w.y = pk2(a[2], a[3]); w.z = pk2(b[0], b[1]); w.w = pk2(b[2], b[3]); return w; }
;     __device__ __forceinline__ void operator()(const f32x4 (&acc)[2][2][4][2], const pg8::Unit& u, int wr, int wc, int fr, int fq) const {
;     ...
;                     const int rowa = 256 * pm + 128 * ai + 64 * wr + 16 * m + tt.rr;
;                     { v4u a, b; if (isq) tt.bf(pack8(o1[0] * QSCALE, o1[1] * QSCALE), pack8(o2[0] * QSCALE, o2[1] * QSCALE), a, b); else tt.bf(pack8(o1[0], o1[1]), pack8(o2[0], o2[1]), a, b);
;                       bf16* d = dst + (size_t)rowa * DA + head * 64 + 8 * tt.p; *(v4u*)d = a; *(v4u*)(d + 8 * DA) = b; }
;                     if (wout) {
;                         const int rl = 128 * ai + 64 * wr + 16 * m + tt.rr;
;                         float* op = sample ? out + OUT_KNEW + (size_t)(rowa - MP) * DA : out + OUT_KWIN + ((size_t)(pm >> 4) * WIN + (256 * (pm & 15) + rl - (SEQ - WIN))) * DA;
;                         op += head * 64 + 4 * tt.p;
;                         f32x4 a, b; tt.f4(o1[0], o1[1], a, b); *(f32x4*)op = a; *(f32x4*)(op + 8 * DA) = b;
;                         tt.f4(o2[0], o2[1], a, b); *(f32x4*)(op + 32) = a; *(f32x4*)(op + 32 + 8 * DA) = b;
;                     }
.LBB0_510:
	v_cvt_pk_bf16_f32 v70, v70, v71
	v_cvt_pk_bf16_f32 v71, v72, v73
	v_cvt_pk_bf16_f32 v72, v74, v75
	v_cvt_pk_bf16_f32 v73, v76, v77
	ds_write_b128 v166, v[66:69]
	ds_write_b128 v165, v[70:73]
	v_add_u32_e32 v78, 0x90, v212
	ds_read_b128 v[66:69], v162
	ds_read_b128 v[70:73], v162 offset:1024
	v_ashrrev_i32_e32 v79, 31, v78
	v_lshlrev_b64 v[74:75], 10, v[78:79]
	v_lshl_add_u64 v[74:75], v[214:215], 0, v[74:75]
	s_waitcnt lgkmcnt(1)
	global_store_dwordx4 v[74:75], v[66:69], off sc1
	s_nop 1
	v_add_co_u32_e32 v66, vcc, 0x2000, v74
	s_nop 1
	v_addc_co_u32_e32 v67, vcc, 0, v75, vcc
	s_and_b64 vcc, exec, s[6:7]
	s_waitcnt lgkmcnt(0)
	global_store_dwordx4 v[66:67], v[70:73], off sc1
	s_cbranch_vccnz .LBB0_512
	v_add_u32_e32 v66, 0xffff0090, v212
	v_add_u32_e32 v67, 0x90, v199
	s_add_u32 s12, s82, s42
	ds_write_b128 v163, v[38:41]
	ds_write_b128 v164, v[46:49]
	s_addc_u32 s33, s83, s43
	v_cndmask_b32_e64 v66, v67, v66, s[4:5]
	ds_read_b128 v[38:41], v162
	s_and_b64 s[0:1], s[4:5], exec
	v_ashrrev_i32_e32 v67, 31, v66
	s_cselect_b32 s1, s85, s33
	s_cselect_b32 s0, s84, s12
	v_lshlrev_b64 v[46:47], 11, v[66:67]
	v_lshl_add_u64 v[46:47], s[0:1], 0, v[46:47]
	v_lshl_add_u64 v[66:67], v[46:47], 0, v[184:185]
	ds_read_b128 v[46:49], v162 offset:1024
	s_waitcnt lgkmcnt(1)
	global_store_dwordx4 v[66:67], v[38:41], off nt
	ds_write_b128 v163, v[34:37]
	ds_write_b128 v164, v[42:45]
	ds_read_b128 v[34:37], v162
	ds_read_b128 v[38:41], v162 offset:1024
	v_add_co_u32_e32 v68, vcc, 0x4000, v66
	s_nop 1
	v_addc_co_u32_e32 v69, vcc, 0, v67, vcc
	s_waitcnt lgkmcnt(4)
	global_store_dwordx4 v[68:69], v[46:49], off nt
	s_waitcnt lgkmcnt(1)
	global_store_dwordx4 v[66:67], v[34:37], off offset:128 nt
	s_waitcnt lgkmcnt(0)
	global_store_dwordx4 v[68:69], v[38:41], off offset:128 nt

; __device__ __forceinline__ v4u pack8(const f32x4 a, const f32x4 b) { v4u w; w.x = pk2(a[0], a[1]); w.y = pk2(a[2], a[3]); w.z = pk2(b[0], b[1]); w.w = pk2(b[2], b[3]); return w; }
;     __device__ __forceinline__ void operator()(const f32x4 (&acc)[2][2][4][2], const pg8::Unit& u, int wr, int wc, int fr, int fq) const {
;     ...
;                     const int rowa = 256 * pm + 128 * ai + 64 * wr + 16 * m + tt.rr;
;                     { v4u a, b; if (isq) tt.bf(pack8(o1[0] * QSCALE, o1[1] * QSCALE), pack8(o2[0] * QSCALE, o2[1] * QSCALE), a, b); else tt.bf(pack8(o1[0], o1[1]), pack8(o2[0], o2[1]), a, b);
;                       bf16* d = dst + (size_t)rowa * DA + head * 64 + 8 * tt.p; *(v4u*)d = a; *(v4u*)(d + 8 * DA) = b; }
;                     if (wout) {
;                         const int rl = 128 * ai + 64 * wr + 16 * m + tt.rr;
;                         float* op = sample ? out + OUT_KNEW + (size_t)(rowa - MP) * DA : out + OUT_KWIN + ((size_t)(pm >> 4) * WIN + (256 * (pm & 15) + rl - (SEQ - WIN))) * DA;
;                         op += head * 64 + 4 * tt.p;
;                         f32x4 a, b; tt.f4(o1[0], o1[1], a, b); *(f32x4*)op = a; *(f32x4*)(op + 8 * DA) = b;
;                         tt.f4(o2[0], o2[1], a, b); *(f32x4*)(op + 32) = a; *(f32x4*)(op + 32 + 8 * DA) = b;
;                     }
.LBB0_516:
	v_cvt_pk_bf16_f32 v54, v54, v55
	v_cvt_pk_bf16_f32 v55, v56, v57
	v_cvt_pk_bf16_f32 v56, v58, v59
	v_cvt_pk_bf16_f32 v57, v60, v61
	ds_write_b128 v166, v[50:53]
	ds_write_b128 v165, v[54:57]
	v_add_u32_e32 v62, 0xa0, v212
	ds_read_b128 v[50:53], v162
	ds_read_b128 v[54:57], v162 offset:1024
	v_ashrrev_i32_e32 v63, 31, v62
	v_lshlrev_b64 v[58:59], 10, v[62:63]
	v_lshl_add_u64 v[58:59], v[214:215], 0, v[58:59]
	s_waitcnt lgkmcnt(1)
	global_store_dwordx4 v[58:59], v[50:53], off sc1
	s_nop 1
	v_add_co_u32_e32 v50, vcc, 0x2000, v58
	s_nop 1
	v_addc_co_u32_e32 v51, vcc, 0, v59, vcc
	s_and_b64 vcc, exec, s[6:7]
	s_waitcnt lgkmcnt(0)
	global_store_dwordx4 v[50:51], v[54:57], off sc1
	s_cbranch_vccnz .LBB0_518
	v_add_u32_e32 v50, 0xffff00a0, v212
	v_add_u32_e32 v51, 0xa0, v199
	s_add_u32 s12, s82, s42
	ds_write_b128 v163, v[22:25]
	ds_write_b128 v164, v[30:33]
	s_addc_u32 s33, s83, s43
	v_cndmask_b32_e64 v50, v51, v50, s[4:5]
	ds_read_b128 v[22:25], v162
	s_and_b64 s[0:1], s[4:5], exec
	v_ashrrev_i32_e32 v51, 31, v50
	s_cselect_b32 s1, s85, s33
	s_cselect_b32 s0, s84, s12
	v_lshlrev_b64 v[30:31], 11, v[50:51]
	v_lshl_add_u64 v[30:31], s[0:1], 0, v[30:31]
	v_lshl_add_u64 v[50:51], v[30:31], 0, v[184:185]
	ds_read_b128 v[30:33], v162 offset:1024
	s_waitcnt lgkmcnt(1)
	global_store_dwordx4 v[50:51], v[22:25], off nt
	ds_write_b128 v163, v[18:21]
	ds_write_b128 v164, v[26:29]
	ds_read_b128 v[18:21], v162
	ds_read_b128 v[22:25], v162 offset:1024
	v_add_co_u32_e32 v52, vcc, 0x4000, v50
	s_nop 1
	v_addc_co_u32_e32 v53, vcc, 0, v51, vcc
	s_waitcnt lgkmcnt(4)
	global_store_dwordx4 v[52:53], v[30:33], off nt
	s_waitcnt lgkmcnt(1)
	global_store_dwordx4 v[50:51], v[18:21], off offset:128 nt
	s_waitcnt lgkmcnt(0)
	global_store_dwordx4 v[52:53], v[22:25], off offset:128 nt

; __device__ __forceinline__ v4u pack8(const f32x4 a, const f32x4 b) { v4u w; w.x = pk2(a[0], a[1]); w.y = pk2(a[2], a[3]); w.z = pk2(b[0], b[1]); w.w = pk2(b[2], b[3]); return w; }
;     __device__ __forceinline__ void operator()(const f32x4 (&acc)[2][2][4][2], const pg8::Unit& u, int wr, int wc, int fr, int fq) const {
;     ...
;                     const int rowa = 256 * pm + 128 * ai + 64 * wr + 16 * m + tt.rr;
;                     { v4u a, b; if (isq) tt.bf(pack8(o1[0] * QSCALE, o1[1] * QSCALE), pack8(o2[0] * QSCALE, o2[1] * QSCALE), a, b); else tt.bf(pack8(o1[0], o1[1]), pack8(o2[0], o2[1]), a, b);
;                       bf16* d = dst + (size_t)rowa * DA + head * 64 + 8 * tt.p; *(v4u*)d = a; *(v4u*)(d + 8 * DA) = b; }
;                     if (wout) {
;                         const int rl = 128 * ai + 64 * wr + 16 * m + tt.rr;
;                         float* op = sample ? out + OUT_KNEW + (size_t)(rowa - MP) * DA : out + OUT_KWIN + ((size_t)(pm >> 4) * WIN + (256 * (pm & 15) + rl - (SEQ - WIN))) * DA;
;                         op += head * 64 + 4 * tt.p;
;                         f32x4 a, b; tt.f4(o1[0], o1[1], a, b); *(f32x4*)op = a; *(f32x4*)(op + 8 * DA) = b;
;                         tt.f4(o2[0], o2[1], a, b); *(f32x4*)(op + 32) = a; *(f32x4*)(op + 32 + 8 * DA) = b;
;                     }
.LBB0_522:
	v_cvt_pk_bf16_f32 v22, v22, v23
	v_cvt_pk_bf16_f32 v23, v24, v25
	v_cvt_pk_bf16_f32 v24, v26, v27
	v_cvt_pk_bf16_f32 v25, v28, v29
	ds_write_b128 v166, v[18:21]
	ds_write_b128 v165, v[22:25]
	v_add_u32_e32 v30, 0xb0, v212
	ds_read_b128 v[18:21], v162
	ds_read_b128 v[22:25], v162 offset:1024
	v_ashrrev_i32_e32 v31, 31, v30
	v_lshlrev_b64 v[26:27], 10, v[30:31]
	v_lshl_add_u64 v[26:27], v[214:215], 0, v[26:27]
	s_waitcnt lgkmcnt(1)
	global_store_dwordx4 v[26:27], v[18:21], off sc1
	s_nop 1
	v_add_co_u32_e32 v18, vcc, 0x2000, v26
	s_nop 1
	v_addc_co_u32_e32 v19, vcc, 0, v27, vcc
	s_and_b64 vcc, exec, s[6:7]
	s_waitcnt lgkmcnt(0)
	global_store_dwordx4 v[18:19], v[22:25], off sc1
	s_cbranch_vccnz .LBB0_524
	v_add_u32_e32 v18, 0xffff00b0, v212
	v_add_u32_e32 v19, 0xb0, v199
	s_add_u32 s6, s82, s42
	ds_write_b128 v163, v[6:9]
	ds_write_b128 v164, v[14:17]
	s_addc_u32 s7, s83, s43
	v_cndmask_b32_e64 v18, v19, v18, s[4:5]
	ds_read_b128 v[6:9], v162
	s_and_b64 s[0:1], s[4:5], exec
	v_ashrrev_i32_e32 v19, 31, v18
	s_cselect_b32 s1, s85, s7
	s_cselect_b32 s0, s84, s6
	v_lshlrev_b64 v[14:15], 11, v[18:19]
	v_lshl_add_u64 v[14:15], s[0:1], 0, v[14:15]
	v_lshl_add_u64 v[18:19], v[14:15], 0, v[184:185]
	ds_read_b128 v[14:17], v162 offset:1024
	s_waitcnt lgkmcnt(1)
	global_store_dwordx4 v[18:19], v[6:9], off nt
	ds_write_b128 v163, v[2:5]
	ds_write_b128 v164, v[10:13]
	ds_read_b128 v[2:5], v162
	ds_read_b128 v[6:9], v162 offset:1024
	v_add_co_u32_e32 v20, vcc, 0x4000, v18
	s_nop 1
	v_addc_co_u32_e32 v21, vcc, 0, v19, vcc
	s_waitcnt lgkmcnt(4)
	global_store_dwordx4 v[20:21], v[14:17], off nt
	s_waitcnt lgkmcnt(1)
	global_store_dwordx4 v[18:19], v[2:5], off offset:128 nt
	s_waitcnt lgkmcnt(0)
	global_store_dwordx4 v[20:21], v[6:9], off offset:128 nt
